# nt cache policy on the read-once gate loads (global_load_ushort) of all attention epilogues
# speedup vs baseline: 1.0080x; 1.0069x over previous
; #define SBAR() __builtin_amdgcn_sched_barrier(0)
; __device__ __forceinline__ int crow(int r, int hi) { return (r & 3) + 8 * (r >> 2) + 4 * hi; }
; template <int MODE, bool FAST>
; __device__ __forceinline__ int attn_item(const AttnP& a, int b, int h, int blk, char* lds) {
;     ...
;     const float lam = MODE == 0 ? a.lam[0] : 0.f;
;     if (hi == 0) { wsf[r32] = 1.f / l_reg[0]; if (MODE == 0) wsf[32 + r32] = lam / l_reg[NMAP - 1]; }
;     asm volatile("s_waitcnt lgkmcnt(0)" ::: "memory");
;     const size_t obase = ((size_t)b * SEQ + qtok) * DM + (MODE == 0 ? 0 : 1024) + h * 128 + r32;
;     float sg[4];
; #pragma unroll
;     for (int d = 0; d < 4; ++d) sg[d] = MODE == 0 ? a.subln_g[d * 32 + r32] * 0.8f : 1.f;
;     bf16_t gq[16][4];
; #pragma unroll
;     for (int r = 0; r < 16; ++r)
; #pragma unroll
;         for (int d = 0; d < 4; ++d) gq[r][d] = a.G[obase + (size_t)crow(r, hi) * DM + d * 32];
;     asm volatile("s_waitcnt vmcnt(0)" ::: "memory"); SBAR();
.LBB0_162:
	s_or_b64 exec, exec, s[4:5]
	s_ashr_i32 s27, s26, 31
	s_lshl_b64 s[4:5], s[28:29], 11
	s_lshl_b32 s2, s2, 7
	s_lshl_b64 s[26:27], s[26:27], 24
	v_readlane_b32 s64, v254, 0
	s_add_u32 s4, s4, s26
	s_waitcnt lgkmcnt(0)
	v_lshlrev_b32_e32 v128, 2, v205
	v_readlane_b32 s74, v254, 10
	v_readlane_b32 s75, v254, 11
	s_addc_u32 s5, s5, s27
	s_or_b32 s2, s4, s2
	s_nop 2
	global_load_dword v181, v128, s[74:75]
	global_load_dword v184, v128, s[74:75] offset:128
	global_load_dword v185, v128, s[74:75] offset:256
	global_load_dword v186, v128, s[74:75] offset:384
	v_or_b32_e32 v128, s2, v205
	v_mov_b32_e32 v129, s5
	v_lshlrev_b64 v[128:129], 1, v[128:129]
	v_lshl_add_u64 v[132:133], s[12:13], 0, v[128:129]
	v_lshlrev_b32_e32 v192, 14, v204
	v_lshl_add_u64 v[132:133], v[132:133], 0, v[192:193]
	v_add_co_u32_e32 v134, vcc, s0, v132
	v_readlane_b32 s65, v254, 1
	s_nop 0
	v_addc_co_u32_e32 v135, vcc, 0, v133, vcc
	v_add_co_u32_e32 v136, vcc, s34, v132
	v_readlane_b32 s66, v254, 2
	s_nop 0
	v_addc_co_u32_e32 v137, vcc, 0, v133, vcc
	v_add_co_u32_e32 v138, vcc, s48, v132
	v_readlane_b32 s67, v254, 3
	s_nop 0
	v_addc_co_u32_e32 v139, vcc, 0, v133, vcc
	global_load_ushort v194, v[132:133], off nt
	global_load_ushort v195, v[132:133], off offset:64 nt
	global_load_ushort v196, v[132:133], off offset:128 nt
	global_load_ushort v197, v[132:133], off offset:192 nt
	global_load_ushort v198, v[134:135], off offset:64 nt
	global_load_ushort v199, v[134:135], off offset:128 nt
	global_load_ushort v205, v[134:135], off offset:192 nt
	global_load_ushort v206, v[138:139], off nt
	v_add_co_u32_e32 v134, vcc, s1, v132
	v_readlane_b32 s68, v254, 4
	s_nop 0
	v_addc_co_u32_e32 v135, vcc, 0, v133, vcc
	v_add_co_u32_e32 v140, vcc, s49, v132
	v_readlane_b32 s69, v254, 5
	s_nop 0
	v_addc_co_u32_e32 v141, vcc, 0, v133, vcc
	v_add_co_u32_e32 v142, vcc, s33, v132
	v_readlane_b32 s70, v254, 6
	s_nop 0
	v_addc_co_u32_e32 v143, vcc, 0, v133, vcc
	v_add_co_u32_e32 v144, vcc, s50, v132
	v_readlane_b32 s71, v254, 7
	s_nop 0
	v_addc_co_u32_e32 v145, vcc, 0, v133, vcc
	global_load_ushort v207, v[136:137], off offset:128 nt
	global_load_ushort v208, v[136:137], off offset:192 nt
	global_load_ushort v209, v[140:141], off offset:-4096 nt
	global_load_ushort v180, v[140:141], off nt
	global_load_ushort v179, v[140:141], off offset:64 nt
	global_load_ushort v178, v[140:141], off offset:128 nt
	global_load_ushort v177, v[140:141], off offset:192 nt
	global_load_ushort v174, v[144:145], off offset:-4096 nt
	global_load_ushort v210, v[138:139], off offset:64 nt
	global_load_ushort v211, v[138:139], off offset:128 nt
	global_load_ushort v212, v[138:139], off offset:192 nt
	global_load_ushort v213, v[134:135], off offset:64 nt
	global_load_ushort v214, v[134:135], off offset:128 nt
	global_load_ushort v215, v[134:135], off offset:192 nt
	global_load_ushort v175, v[142:143], off offset:64 nt
	global_load_ushort v173, v[142:143], off offset:128 nt
	v_add_co_u32_e32 v134, vcc, s47, v132
	v_readlane_b32 s72, v254, 8
	s_nop 0
	v_addc_co_u32_e32 v135, vcc, 0, v133, vcc
	v_add_co_u32_e32 v138, vcc, s51, v132
	v_readlane_b32 s73, v254, 9
	s_nop 0
	v_addc_co_u32_e32 v139, vcc, 0, v133, vcc
	v_add_co_u32_e32 v140, vcc, s52, v132
	global_load_ushort v172, v[144:145], off nt
	global_load_ushort v171, v[144:145], off offset:64 nt
	global_load_ushort v170, v[144:145], off offset:128 nt
	global_load_ushort v169, v[144:145], off offset:192 nt
	global_load_ushort v165, v[138:139], off offset:-4096 nt
	global_load_ushort v163, v[138:139], off nt
	global_load_ushort v162, v[138:139], off offset:64 nt
	global_load_ushort v161, v[138:139], off offset:128 nt
	v_addc_co_u32_e32 v141, vcc, 0, v133, vcc
	v_add_co_u32_e32 v144, vcc, s53, v132
	v_readlane_b32 s76, v254, 12
	s_nop 0
	v_addc_co_u32_e32 v145, vcc, 0, v133, vcc
	v_add_co_u32_e32 v146, vcc, s54, v132
	v_readlane_b32 s77, v254, 13
	s_nop 0
	v_addc_co_u32_e32 v147, vcc, 0, v133, vcc
	v_add_co_u32_e32 v182, vcc, s55, v132
	v_readlane_b32 s78, v254, 14
	s_nop 0
	v_addc_co_u32_e32 v183, vcc, 0, v133, vcc
	global_load_ushort v176, v[142:143], off offset:192 nt
	global_load_ushort v168, v[134:135], off offset:64 nt
	global_load_ushort v167, v[134:135], off offset:128 nt
	global_load_ushort v166, v[134:135], off offset:192 nt
	global_load_ushort v159, v[140:141], off offset:64 nt
	global_load_ushort v158, v[140:141], off offset:128 nt
	global_load_ushort v157, v[140:141], off offset:192 nt
	global_load_ushort v149, v[146:147], off offset:64 nt
	global_load_ushort v164, v[138:139], off offset:192 nt
	global_load_ushort v160, v[144:145], off offset:-4096 nt
	global_load_ushort v156, v[144:145], off nt
	global_load_ushort v155, v[144:145], off offset:64 nt
	global_load_ushort v154, v[144:145], off offset:128 nt
	global_load_ushort v153, v[144:145], off offset:192 nt
	global_load_ushort v150, v[182:183], off offset:-4096 nt
	s_nop 0
	global_load_ushort v145, v[182:183], off nt
	v_add_co_u32_e32 v134, vcc, s56, v132
	v_readlane_b32 s79, v254, 15
	s_nop 0
	v_addc_co_u32_e32 v135, vcc, 0, v133, vcc
	v_add_co_u32_e32 v138, vcc, s57, v132
	s_nop 1
	v_addc_co_u32_e32 v139, vcc, 0, v133, vcc
	global_load_ushort v216, v[136:137], off offset:-4096 nt
	global_load_ushort v217, v[136:137], off nt
	global_load_ushort v218, v[136:137], off offset:64 nt
	global_load_ushort v152, v[146:147], off offset:128 nt
	global_load_ushort v151, v[146:147], off offset:192 nt
	global_load_ushort v142, v[134:135], off offset:64 nt
	global_load_ushort v141, v[134:135], off offset:128 nt
	global_load_ushort v140, v[134:135], off offset:192 nt
	global_load_ushort v148, v[182:183], off offset:64 nt
	s_nop 0
	global_load_ushort v147, v[182:183], off offset:128 nt
	global_load_ushort v146, v[182:183], off offset:192 nt
	global_load_ushort v143, v[138:139], off offset:-4096 nt
	global_load_ushort v134, v[138:139], off nt
	global_load_ushort v133, v[138:139], off offset:64 nt
	global_load_ushort v132, v[138:139], off offset:128 nt
	global_load_ushort v131, v[138:139], off offset:192 nt
	s_waitcnt vmcnt(0)
; __device__ __forceinline__ unsigned cvtpk(float lo, float hi) { unsigned r; asm volatile("v_cvt_pk_bf16_f32 %0, %1, %2" : "=v"(r) : "v"(lo), "v"(hi)); return r; }
; __device__ __forceinline__ float bf2f(bf16_t v) { return __uint_as_float((unsigned)v << 16); }
; __device__ __forceinline__ int crow(int r, int hi) { return (r & 3) + 8 * (r >> 2) + 4 * hi; }
; template <int MODE, bool FAST>
; __device__ __forceinline__ int attn_item(const AttnP& a, int b, int h, int blk, char* lds) {
;     ...
;     for (int r = 0; r < 16; ++r) {
;         const int cr = crow(r, hi);
;         const float ra = wsf[cr];
;         float v[4];
;         if (MODE == 0) {
;             const float rb = wsf[32 + cr];
;             float ss = 0.f;
; #pragma unroll
;             for (int d = 0; d < 4; ++d) { v[d] = o[0][d][r] * ra - o[NMAP - 1][d][r] * rb; ss += v[d] * v[d]; }
;             ss += __shfl_xor(ss, 1); ss += __shfl_xor(ss, 2); ss += __shfl_xor(ss, 4); ss += __shfl_xor(ss, 8); ss += __shfl_xor(ss, 16);
;             const float rstd = rsqrtf(ss * (1.f / 128.f) + 1e-5f);
; #pragma unroll
;             for (int d = 0; d < 4; ++d) v[d] *= rstd * sg[d];
;         } else {
; #pragma unroll
;             for (int d = 0; d < 4; ++d) v[d] = o[0][d][r] * ra;
;         }
;         const size_t ro = obase + (size_t)cr * DM;
; #pragma unroll
;         for (int d = 0; d < 4; ++d) { const float gg = bf2f(gq[r][d]); a.MIX[ro + d * 32] = (bf16_t)(cvtpk(v[d] * gg, 0.f) & 0xffffu); }
;     }
	s_waitcnt vmcnt(62)
	v_mul_f32_e32 v138, 0x3f4ccccd, v181
	v_mul_f32_e32 v137, 0x3f4ccccd, v184
	v_mul_f32_e32 v136, 0x3f4ccccd, v185
	v_mul_f32_e32 v135, 0x3f4ccccd, v186
	v_and_b32_e32 v144, 64, v203
	v_add_u32_e32 v181, 64, v144
	v_lshl_add_u32 v144, v204, 4, s6
	ds_read2_b32 v[182:183], v144 offset1:32
	v_mov_b32_e32 v184, v0
	v_mov_b32_e32 v186, v64
	v_mov_b32_e32 v187, v80
	v_mov_b32_e32 v185, v16
	s_waitcnt lgkmcnt(0)
	v_mov_b32_e32 v0, v183
	v_pk_mul_f32 v[186:187], v[186:187], v[0:1] op_sel_hi:[1,0]
	v_mov_b32_e32 v190, v112
	v_mov_b32_e32 v191, v96
	v_pk_fma_f32 v[184:185], v[184:185], v[182:183], v[186:187] op_sel_hi:[1,0,1] neg_lo:[0,0,1] neg_hi:[0,0,1]
	v_mov_b32_e32 v188, v48
	v_mov_b32_e32 v189, v32
	v_pk_mul_f32 v[190:191], v[190:191], v[0:1] op_sel_hi:[1,0]
	v_xor_b32_e32 v139, 1, v203
	v_pk_mul_f32 v[186:187], v[184:185], v[184:185]
	v_pk_fma_f32 v[182:183], v[188:189], v[182:183], v[190:191] op_sel_hi:[1,0,1] neg_lo:[0,0,1] neg_hi:[0,0,1]
	v_cmp_lt_i32_e32 vcc, v139, v181
	v_pk_mul_f32 v[188:189], v[182:183], v[182:183]
	v_add_f32_e32 v0, v186, v187
	v_cndmask_b32_e32 v139, v203, v139, vcc
	v_add_f32_e32 v0, v189, v0
	v_lshlrev_b32_e32 v139, 2, v139
	v_add_f32_e32 v16, v188, v0
	ds_bpermute_b32 v32, v139, v16
	v_xor_b32_e32 v0, 2, v203
	v_cmp_lt_i32_e32 vcc, v0, v181
	v_xor_b32_e32 v48, 4, v203
	v_xor_b32_e32 v64, 8, v203
	v_cndmask_b32_e32 v0, v203, v0, vcc
	v_lshlrev_b32_e32 v0, 2, v0
	s_waitcnt lgkmcnt(0)
	v_add_f32_e32 v16, v16, v32
	ds_bpermute_b32 v32, v0, v16
	v_cmp_lt_i32_e32 vcc, v48, v181
	v_xor_b32_e32 v80, 16, v203
	v_lshl_add_u64 v[128:129], s[14:15], 0, v[128:129]
	v_cndmask_b32_e32 v48, v203, v48, vcc
	v_lshlrev_b32_e32 v48, 2, v48
	s_waitcnt lgkmcnt(0)
	v_add_f32_e32 v16, v16, v32
	ds_bpermute_b32 v32, v48, v16
	v_cmp_lt_i32_e32 vcc, v64, v181
	s_waitcnt lgkmcnt(0)
	v_add_f32_e32 v16, v16, v32
	v_cndmask_b32_e32 v64, v203, v64, vcc
	v_lshlrev_b32_e32 v64, 2, v64
	ds_bpermute_b32 v32, v64, v16
	v_cmp_lt_i32_e32 vcc, v80, v181
	v_lshlrev_b32_e32 v181, 16, v194
	s_waitcnt lgkmcnt(0)
	v_add_f32_e32 v16, v16, v32
	v_cndmask_b32_e32 v80, v203, v80, vcc
	v_lshlrev_b32_e32 v112, 2, v80
	ds_bpermute_b32 v32, v112, v16
	s_waitcnt lgkmcnt(0)
	v_add_f32_e32 v16, v16, v32
	v_fmamk_f32 v16, v16, 0x3c000000, v202
	v_mul_f32_e32 v32, 0x4b800000, v16
	v_cmp_gt_f32_e32 vcc, s58, v16
	s_nop 1
	v_cndmask_b32_e32 v16, v16, v32, vcc
	v_rsq_f32_e32 v16, v16
	s_nop 0
	v_mul_f32_e32 v32, 0x45800000, v16
	v_cndmask_b32_e32 v16, v16, v32, vcc
	v_mul_f32_e32 v32, v138, v16
	v_mul_f32_e32 v32, v184, v32
	v_mul_f32_e32 v80, v137, v16
	v_mul_f32_e32 v96, v136, v16
	v_mul_f32_e32 v16, v135, v16
	v_mul_f32_e32 v32, v32, v181
	v_mul_f32_e32 v96, v183, v96
	v_mul_f32_e32 v16, v182, v16
	v_cvt_pk_bf16_f32 v32, v32, v193
	v_lshl_add_u64 v[182:183], v[128:129], 0, v[192:193]
	v_mul_f32_e32 v80, v185, v80
	global_store_short v[182:183], v32, off
	v_lshlrev_b32_e32 v32, 16, v195
	v_mul_f32_e32 v32, v80, v32
	v_cvt_pk_bf16_f32 v32, v32, v193
	global_store_short v[182:183], v32, off offset:64
	s_waitcnt vmcnt(62)
	v_lshlrev_b32_e32 v32, 16, v196
	v_mul_f32_e32 v32, v96, v32
	v_cvt_pk_bf16_f32 v32, v32, v193
	global_store_short v[182:183], v32, off offset:128
	v_lshlrev_b32_e32 v32, 16, v197
	v_mul_f32_e32 v16, v16, v32
	v_cvt_pk_bf16_f32 v181, v16, v193
	ds_read2_b32 v[184:185], v144 offset0:1 offset1:33
	v_mov_b32_e32 v80, v65
	v_mov_b32_e32 v16, v1
	v_mov_b32_e32 v96, v113
	v_mov_b32_e32 v32, v49
	s_waitcnt lgkmcnt(0)
	v_mov_b32_e32 v186, v185
	v_pk_mul_f32 v[80:81], v[80:81], v[186:187] op_sel_hi:[1,0]
	v_pk_mul_f32 v[96:97], v[96:97], v[186:187] op_sel_hi:[1,0]
	v_pk_fma_f32 v[16:17], v[16:17], v[184:185], v[80:81] op_sel_hi:[1,0,1] neg_lo:[0,0,1] neg_hi:[0,0,1]
	v_pk_fma_f32 v[32:33], v[32:33], v[184:185], v[96:97] op_sel_hi:[1,0,1] neg_lo:[0,0,1] neg_hi:[0,0,1]
	v_pk_mul_f32 v[80:81], v[16:17], v[16:17]
	v_pk_mul_f32 v[96:97], v[32:33], v[32:33]
	v_add_f32_e32 v1, v80, v81
	v_add_f32_e32 v1, v97, v1
	v_add_f32_e32 v1, v96, v1
	ds_bpermute_b32 v49, v139, v1
	global_store_short v[182:183], v181, off offset:192
	v_mov_b32_e32 v80, v2
	v_mov_b32_e32 v96, v66
	v_mov_b32_e32 v97, v82
	s_waitcnt lgkmcnt(0)
	v_add_f32_e32 v1, v1, v49
	ds_bpermute_b32 v49, v0, v1
	v_mov_b32_e32 v81, v18
	v_mov_b32_e32 v184, v114
	v_mov_b32_e32 v185, v98
	v_mov_b32_e32 v182, v50
	s_waitcnt lgkmcnt(0)
	v_add_f32_e32 v1, v1, v49
	ds_bpermute_b32 v49, v48, v1
	v_mov_b32_e32 v183, v34
	v_mov_b32_e32 v82, v67
	v_mov_b32_e32 v98, v115
	v_mov_b32_e32 v34, v51
	s_waitcnt lgkmcnt(0)
	v_add_f32_e32 v1, v1, v49
	ds_bpermute_b32 v49, v64, v1
	v_mov_b32_e32 v50, v116
	v_mov_b32_e32 v51, v100
	v_mov_b32_e32 v100, v117
	s_waitcnt lgkmcnt(0)
	v_add_f32_e32 v1, v1, v49
	ds_bpermute_b32 v49, v112, v1
	s_waitcnt lgkmcnt(0)
	v_add_f32_e32 v1, v1, v49
	v_fmamk_f32 v1, v1, 0x3c000000, v202
	v_mul_f32_e32 v49, 0x4b800000, v1
	v_cmp_gt_f32_e32 vcc, s58, v1
	s_nop 1
	v_cndmask_b32_e32 v1, v1, v49, vcc
	v_rsq_f32_e32 v1, v1
	s_nop 0
	v_mul_f32_e32 v49, 0x45800000, v1
	v_cndmask_b32_e32 v1, v1, v49, vcc
	v_mul_f32_e32 v49, v138, v1
	v_mul_f32_e32 v49, v16, v49
	v_mul_f32_e32 v16, v137, v1
	v_mul_f32_e32 v65, v17, v16
	v_mul_f32_e32 v16, v136, v1
	v_mul_f32_e32 v1, v135, v1
	v_mul_f32_e32 v1, v32, v1
	s_waitcnt vmcnt(19)
; __device__ __forceinline__ unsigned cvtpk(float lo, float hi) { unsigned r; asm volatile("v_cvt_pk_bf16_f32 %0, %1, %2" : "=v"(r) : "v"(lo), "v"(hi)); return r; }
; __device__ __forceinline__ float bf2f(bf16_t v) { return __uint_as_float((unsigned)v << 16); }
; __device__ __forceinline__ int crow(int r, int hi) { return (r & 3) + 8 * (r >> 2) + 4 * hi; }
; template <int MODE, bool FAST>
; __device__ __forceinline__ int attn_item(const AttnP& a, int b, int h, int blk, char* lds) {
;     ...
;     for (int r = 0; r < 16; ++r) {
;         const int cr = crow(r, hi);
;         const float ra = wsf[cr];
;         float v[4];
;         if (MODE == 0) {
;             const float rb = wsf[32 + cr];
;             float ss = 0.f;
; #pragma unroll
;             for (int d = 0; d < 4; ++d) { v[d] = o[0][d][r] * ra - o[NMAP - 1][d][r] * rb; ss += v[d] * v[d]; }
;             ss += __shfl_xor(ss, 1); ss += __shfl_xor(ss, 2); ss += __shfl_xor(ss, 4); ss += __shfl_xor(ss, 8); ss += __shfl_xor(ss, 16);
;             const float rstd = rsqrtf(ss * (1.f / 128.f) + 1e-5f);
; #pragma unroll
;             for (int d = 0; d < 4; ++d) v[d] *= rstd * sg[d];
;         } else {
; #pragma unroll
;             for (int d = 0; d < 4; ++d) v[d] = o[0][d][r] * ra;
;         }
;         const size_t ro = obase + (size_t)cr * DM;
; #pragma unroll
;         for (int d = 0; d < 4; ++d) { const float gg = bf2f(gq[r][d]); a.MIX[ro + d * 32] = (bf16_t)(cvtpk(v[d] * gg, 0.f) & 0xffffu); }
;     }
	v_lshlrev_b32_e32 v32, 16, v216
	v_mul_f32_e32 v33, v33, v16
	v_or_b32_e32 v16, 0x1000, v192
	v_mov_b32_e32 v17, v193
	v_mul_f32_e32 v32, v49, v32
	v_cvt_pk_bf16_f32 v32, v32, v193
	v_lshl_add_u64 v[16:17], v[128:129], 0, v[16:17]
	global_store_short v[16:17], v32, off
	v_lshlrev_b32_e32 v32, 16, v198
	v_mul_f32_e32 v32, v65, v32
	v_cvt_pk_bf16_f32 v32, v32, v193
	global_store_short v[16:17], v32, off offset:64
	v_lshlrev_b32_e32 v32, 16, v199
	v_mul_f32_e32 v32, v33, v32
	v_cvt_pk_bf16_f32 v32, v32, v193
	global_store_short v[16:17], v32, off offset:128
	v_lshlrev_b32_e32 v32, 16, v205
	v_mul_f32_e32 v1, v1, v32
	v_cvt_pk_bf16_f32 v1, v1, v193
	ds_read2_b32 v[32:33], v144 offset0:2 offset1:34
	global_store_short v[16:17], v1, off offset:192
	v_mov_b32_e32 v17, v193
	s_waitcnt lgkmcnt(0)
	v_mov_b32_e32 v2, v33
	v_pk_mul_f32 v[96:97], v[96:97], v[2:3] op_sel_hi:[1,0]
	v_pk_mul_f32 v[184:185], v[184:185], v[2:3] op_sel_hi:[1,0]
	v_pk_fma_f32 v[80:81], v[80:81], v[32:33], v[96:97] op_sel_hi:[1,0,1] neg_lo:[0,0,1] neg_hi:[0,0,1]
	v_pk_fma_f32 v[32:33], v[182:183], v[32:33], v[184:185] op_sel_hi:[1,0,1] neg_lo:[0,0,1] neg_hi:[0,0,1]
	v_pk_mul_f32 v[96:97], v[80:81], v[80:81]
	v_pk_mul_f32 v[182:183], v[32:33], v[32:33]
	v_add_f32_e32 v2, v96, v97
	v_add_f32_e32 v2, v183, v2
	v_add_f32_e32 v2, v182, v2
	ds_bpermute_b32 v18, v139, v2
	s_waitcnt lgkmcnt(0)
	v_add_f32_e32 v2, v2, v18
	ds_bpermute_b32 v18, v0, v2
	s_waitcnt lgkmcnt(0)
	v_add_f32_e32 v2, v2, v18
	ds_bpermute_b32 v18, v48, v2
	s_waitcnt lgkmcnt(0)
	v_add_f32_e32 v2, v2, v18
	ds_bpermute_b32 v18, v64, v2
	s_waitcnt lgkmcnt(0)
	v_add_f32_e32 v2, v2, v18
	ds_bpermute_b32 v18, v112, v2
	s_waitcnt lgkmcnt(0)
	v_add_f32_e32 v2, v2, v18
	v_fmamk_f32 v2, v2, 0x3c000000, v202
	v_mul_f32_e32 v18, 0x4b800000, v2
	v_cmp_gt_f32_e32 vcc, s58, v2
	s_nop 1
	v_cndmask_b32_e32 v2, v2, v18, vcc
	v_rsq_f32_e32 v2, v2
	s_nop 0
	v_mul_f32_e32 v1, 0x45800000, v2
	v_cndmask_b32_e32 v1, v2, v1, vcc
	v_mul_f32_e32 v16, v137, v1
	v_mul_f32_e32 v2, v138, v1
	v_mul_f32_e32 v18, v81, v16
	v_mul_f32_e32 v16, v136, v1
	v_mul_f32_e32 v1, v135, v1
	v_mul_f32_e32 v2, v80, v2
	v_mul_f32_e32 v1, v32, v1
	s_waitcnt vmcnt(22)
	v_lshlrev_b32_e32 v32, 16, v217
	v_mul_f32_e32 v33, v33, v16
	v_or_b32_e32 v16, 0x2000, v192
	v_mul_f32_e32 v2, v2, v32
	v_cvt_pk_bf16_f32 v2, v2, v193
	v_lshl_add_u64 v[16:17], v[128:129], 0, v[16:17]
	global_store_short v[16:17], v2, off
	s_waitcnt vmcnt(22)
	v_lshlrev_b32_e32 v2, 16, v218
	v_mul_f32_e32 v2, v18, v2
	v_cvt_pk_bf16_f32 v2, v2, v193
	global_store_short v[16:17], v2, off offset:64
	v_lshlrev_b32_e32 v2, 16, v207
	v_mul_f32_e32 v2, v33, v2
	v_cvt_pk_bf16_f32 v2, v2, v193
	global_store_short v[16:17], v2, off offset:128
	v_lshlrev_b32_e32 v2, 16, v208
	v_mul_f32_e32 v1, v1, v2
	v_cvt_pk_bf16_f32 v1, v1, v193
	ds_read2_b32 v[32:33], v144 offset0:3 offset1:35
	v_mov_b32_e32 v18, v3
	global_store_short v[16:17], v1, off offset:192
	s_waitcnt lgkmcnt(0)
	v_mov_b32_e32 v2, v33
	v_pk_mul_f32 v[66:67], v[82:83], v[2:3] op_sel_hi:[1,0]
	v_pk_mul_f32 v[2:3], v[98:99], v[2:3] op_sel_hi:[1,0]
	v_pk_fma_f32 v[18:19], v[18:19], v[32:33], v[66:67] op_sel_hi:[1,0,1] neg_lo:[0,0,1] neg_hi:[0,0,1]
	v_pk_fma_f32 v[2:3], v[34:35], v[32:33], v[2:3] op_sel_hi:[1,0,1] neg_lo:[0,0,1] neg_hi:[0,0,1]
	v_pk_mul_f32 v[66:67], v[18:19], v[18:19]
	v_pk_mul_f32 v[32:33], v[2:3], v[2:3]
	v_add_f32_e32 v34, v66, v67
	v_add_f32_e32 v33, v33, v34
	v_add_f32_e32 v32, v32, v33
	ds_bpermute_b32 v33, v139, v32
	v_mov_b32_e32 v34, v52
	v_mov_b32_e32 v35, v36
	v_mov_b32_e32 v36, v53
	s_waitcnt lgkmcnt(0)
	v_add_f32_e32 v32, v32, v33
	ds_bpermute_b32 v33, v0, v32
	s_waitcnt lgkmcnt(0)
	v_add_f32_e32 v32, v32, v33
	ds_bpermute_b32 v33, v48, v32
	s_waitcnt lgkmcnt(0)
	v_add_f32_e32 v32, v32, v33
	ds_bpermute_b32 v33, v64, v32
	s_waitcnt lgkmcnt(0)
	v_add_f32_e32 v32, v32, v33
	ds_bpermute_b32 v33, v112, v32
	s_waitcnt lgkmcnt(0)
	v_add_f32_e32 v32, v32, v33
	v_fmamk_f32 v32, v32, 0x3c000000, v202
	v_mul_f32_e32 v33, 0x4b800000, v32
	v_cmp_gt_f32_e32 vcc, s58, v32
	s_nop 1
	v_cndmask_b32_e32 v32, v32, v33, vcc
	v_rsq_f32_e32 v32, v32
	v_mov_b32_e32 v33, v84
	v_mov_b32_e32 v84, v69
	v_mul_f32_e32 v1, 0x45800000, v32
	v_cndmask_b32_e32 v1, v32, v1, vcc
	v_mul_f32_e32 v16, v138, v1
	v_mul_f32_e32 v17, v137, v1
	v_mul_f32_e32 v16, v18, v16
	v_mul_f32_e32 v17, v19, v17
	v_mul_f32_e32 v18, v136, v1
	v_mul_f32_e32 v1, v135, v1
	v_lshlrev_b32_e32 v19, 16, v206
	v_mul_f32_e32 v18, v3, v18
	v_mul_f32_e32 v1, v2, v1
	v_or_b32_e32 v2, 0x3000, v192
	v_mov_b32_e32 v3, v193
	v_mul_f32_e32 v16, v16, v19
	v_cvt_pk_bf16_f32 v16, v16, v193
	v_lshl_add_u64 v[2:3], v[128:129], 0, v[2:3]
	global_store_short v[2:3], v16, off
	v_lshlrev_b32_e32 v16, 16, v210
	v_mul_f32_e32 v16, v17, v16
	v_cvt_pk_bf16_f32 v16, v16, v193
	global_store_short v[2:3], v16, off offset:64
	v_lshlrev_b32_e32 v16, 16, v211
	v_mul_f32_e32 v16, v18, v16
	v_cvt_pk_bf16_f32 v16, v16, v193
	global_store_short v[2:3], v16, off offset:128
	v_lshlrev_b32_e32 v16, 16, v212
	v_mul_f32_e32 v1, v1, v16
	v_cvt_pk_bf16_f32 v1, v1, v193
	ds_read2_b32 v[16:17], v144 offset0:8 offset1:40
	v_mov_b32_e32 v18, v4
	v_mov_b32_e32 v32, v68
	v_mov_b32_e32 v19, v20
	global_store_short v[2:3], v1, off offset:192
	s_waitcnt lgkmcnt(0)
	v_mov_b32_e32 v4, v17
	v_pk_mul_f32 v[32:33], v[32:33], v[4:5] op_sel_hi:[1,0]
	v_pk_mul_f32 v[50:51], v[50:51], v[4:5] op_sel_hi:[1,0]
	v_pk_fma_f32 v[18:19], v[18:19], v[16:17], v[32:33] op_sel_hi:[1,0,1] neg_lo:[0,0,1] neg_hi:[0,0,1]
	v_pk_fma_f32 v[16:17], v[34:35], v[16:17], v[50:51] op_sel_hi:[1,0,1] neg_lo:[0,0,1] neg_hi:[0,0,1]
	v_pk_mul_f32 v[32:33], v[18:19], v[18:19]
	v_pk_mul_f32 v[34:35], v[16:17], v[16:17]
	v_add_f32_e32 v4, v32, v33
	v_add_f32_e32 v4, v35, v4
	v_add_f32_e32 v4, v34, v4
	ds_bpermute_b32 v20, v139, v4
	v_mov_b32_e32 v3, v193
	v_mov_b32_e32 v32, v118
	v_mov_b32_e32 v33, v102
	v_mov_b32_e32 v102, v119
	s_waitcnt lgkmcnt(0)
; __device__ __forceinline__ unsigned cvtpk(float lo, float hi) { unsigned r; asm volatile("v_cvt_pk_bf16_f32 %0, %1, %2" : "=v"(r) : "v"(lo), "v"(hi)); return r; }
; __device__ __forceinline__ float bf2f(bf16_t v) { return __uint_as_float((unsigned)v << 16); }
; __device__ __forceinline__ int crow(int r, int hi) { return (r & 3) + 8 * (r >> 2) + 4 * hi; }
; template <int MODE, bool FAST>
; __device__ __forceinline__ int attn_item(const AttnP& a, int b, int h, int blk, char* lds) {
;     ...
;     for (int r = 0; r < 16; ++r) {
;         const int cr = crow(r, hi);
;         const float ra = wsf[cr];
;         float v[4];
;         if (MODE == 0) {
;             const float rb = wsf[32 + cr];
;             float ss = 0.f;
; #pragma unroll
;             for (int d = 0; d < 4; ++d) { v[d] = o[0][d][r] * ra - o[NMAP - 1][d][r] * rb; ss += v[d] * v[d]; }
;             ss += __shfl_xor(ss, 1); ss += __shfl_xor(ss, 2); ss += __shfl_xor(ss, 4); ss += __shfl_xor(ss, 8); ss += __shfl_xor(ss, 16);
;             const float rstd = rsqrtf(ss * (1.f / 128.f) + 1e-5f);
; #pragma unroll
;             for (int d = 0; d < 4; ++d) v[d] *= rstd * sg[d];
;         } else {
; #pragma unroll
;             for (int d = 0; d < 4; ++d) v[d] = o[0][d][r] * ra;
;         }
;         const size_t ro = obase + (size_t)cr * DM;
; #pragma unroll
;         for (int d = 0; d < 4; ++d) { const float gg = bf2f(gq[r][d]); a.MIX[ro + d * 32] = (bf16_t)(cvtpk(v[d] * gg, 0.f) & 0xffffu); }
;     }
	v_add_f32_e32 v4, v4, v20
	ds_bpermute_b32 v20, v0, v4
	s_waitcnt lgkmcnt(0)
	v_add_f32_e32 v4, v4, v20
	ds_bpermute_b32 v20, v48, v4
	s_waitcnt lgkmcnt(0)
	v_add_f32_e32 v4, v4, v20
	ds_bpermute_b32 v20, v64, v4
	s_waitcnt lgkmcnt(0)
	v_add_f32_e32 v4, v4, v20
	ds_bpermute_b32 v20, v112, v4
	s_waitcnt lgkmcnt(0)
	v_add_f32_e32 v4, v4, v20
	v_fmamk_f32 v4, v4, 0x3c000000, v202
	v_mul_f32_e32 v20, 0x4b800000, v4
	v_cmp_gt_f32_e32 vcc, s58, v4
	s_nop 1
	v_cndmask_b32_e32 v4, v4, v20, vcc
	v_rsq_f32_e32 v4, v4
	v_mov_b32_e32 v20, v5
	v_mul_f32_e32 v1, 0x45800000, v4
	v_cndmask_b32_e32 v1, v4, v1, vcc
	v_mul_f32_e32 v2, v138, v1
	v_mul_f32_e32 v4, v18, v2
	v_mul_f32_e32 v2, v137, v1
	v_mul_f32_e32 v18, v19, v2
	v_mul_f32_e32 v2, v136, v1
	v_mul_f32_e32 v1, v135, v1
	v_mul_f32_e32 v1, v16, v1
	v_lshlrev_b32_e32 v16, 16, v209
	v_mul_f32_e32 v17, v17, v2
	v_or_b32_e32 v2, 0x8000, v192
	v_mul_f32_e32 v4, v4, v16
	v_cvt_pk_bf16_f32 v4, v4, v193
	v_lshl_add_u64 v[2:3], v[128:129], 0, v[2:3]
	global_store_short v[2:3], v4, off
	v_lshlrev_b32_e32 v4, 16, v213
	v_mul_f32_e32 v4, v18, v4
	v_cvt_pk_bf16_f32 v4, v4, v193
	global_store_short v[2:3], v4, off offset:64
	v_lshlrev_b32_e32 v4, 16, v214
	v_mul_f32_e32 v4, v17, v4
	v_cvt_pk_bf16_f32 v4, v4, v193
	global_store_short v[2:3], v4, off offset:128
	v_lshlrev_b32_e32 v4, 16, v215
	v_mul_f32_e32 v1, v1, v4
	v_cvt_pk_bf16_f32 v1, v1, v193
	ds_read2_b32 v[16:17], v144 offset0:9 offset1:41
	global_store_short v[2:3], v1, off offset:192
	v_mov_b32_e32 v3, v193
	s_waitcnt lgkmcnt(0)
	v_mov_b32_e32 v4, v17
	v_pk_mul_f32 v[18:19], v[84:85], v[4:5] op_sel_hi:[1,0]
	v_pk_mul_f32 v[4:5], v[100:101], v[4:5] op_sel_hi:[1,0]
	v_pk_fma_f32 v[18:19], v[20:21], v[16:17], v[18:19] op_sel_hi:[1,0,1] neg_lo:[0,0,1] neg_hi:[0,0,1]
	v_pk_fma_f32 v[4:5], v[36:37], v[16:17], v[4:5] op_sel_hi:[1,0,1] neg_lo:[0,0,1] neg_hi:[0,0,1]
	v_pk_mul_f32 v[20:21], v[18:19], v[18:19]
	v_pk_mul_f32 v[16:17], v[4:5], v[4:5]
	v_add_f32_e32 v20, v20, v21
	v_add_f32_e32 v17, v17, v20
	v_add_f32_e32 v16, v16, v17
	ds_bpermute_b32 v17, v139, v16
	v_mov_b32_e32 v20, v54
	v_mov_b32_e32 v21, v38
	v_mov_b32_e32 v38, v55
	s_waitcnt lgkmcnt(0)
	v_add_f32_e32 v16, v16, v17
	ds_bpermute_b32 v17, v0, v16
	s_waitcnt lgkmcnt(0)
	v_add_f32_e32 v16, v16, v17
	ds_bpermute_b32 v17, v48, v16
	s_waitcnt lgkmcnt(0)
	v_add_f32_e32 v16, v16, v17
	ds_bpermute_b32 v17, v64, v16
	s_waitcnt lgkmcnt(0)
	v_add_f32_e32 v16, v16, v17
	ds_bpermute_b32 v17, v112, v16
	s_waitcnt lgkmcnt(0)
	v_add_f32_e32 v16, v16, v17
	v_fmamk_f32 v16, v16, 0x3c000000, v202
	v_mul_f32_e32 v17, 0x4b800000, v16
	v_cmp_gt_f32_e32 vcc, s58, v16
	s_nop 1
	v_cndmask_b32_e32 v16, v16, v17, vcc
	v_rsq_f32_e32 v16, v16
	s_nop 0
	v_mul_f32_e32 v1, 0x45800000, v16
	v_cndmask_b32_e32 v1, v16, v1, vcc
	v_mul_f32_e32 v2, v138, v1
	v_mul_f32_e32 v16, v18, v2
	v_mul_f32_e32 v2, v137, v1
	v_mul_f32_e32 v17, v19, v2
	v_mul_f32_e32 v2, v136, v1
	v_mul_f32_e32 v1, v135, v1
	v_mul_f32_e32 v1, v4, v1
	v_lshlrev_b32_e32 v4, 16, v180
	v_mul_f32_e32 v5, v5, v2
	v_or_b32_e32 v2, 0x9000, v192
	v_mul_f32_e32 v4, v16, v4
	v_cvt_pk_bf16_f32 v4, v4, v193
	v_lshl_add_u64 v[2:3], v[128:129], 0, v[2:3]
	global_store_short v[2:3], v4, off
	v_lshlrev_b32_e32 v4, 16, v179
	v_mul_f32_e32 v4, v17, v4
	v_cvt_pk_bf16_f32 v4, v4, v193
	global_store_short v[2:3], v4, off offset:64
	v_lshlrev_b32_e32 v4, 16, v178
	v_mul_f32_e32 v4, v5, v4
	v_cvt_pk_bf16_f32 v4, v4, v193
	global_store_short v[2:3], v4, off offset:128
	v_lshlrev_b32_e32 v4, 16, v177
	v_mul_f32_e32 v1, v1, v4
	v_cvt_pk_bf16_f32 v1, v1, v193
	ds_read2_b32 v[4:5], v144 offset0:10 offset1:42
	v_mov_b32_e32 v16, v6
	v_mov_b32_e32 v18, v70
	v_mov_b32_e32 v19, v86
	v_mov_b32_e32 v17, v22
	s_waitcnt lgkmcnt(0)
	v_mov_b32_e32 v6, v5
	v_pk_mul_f32 v[18:19], v[18:19], v[6:7] op_sel_hi:[1,0]
	v_pk_mul_f32 v[32:33], v[32:33], v[6:7] op_sel_hi:[1,0]
	v_pk_fma_f32 v[16:17], v[16:17], v[4:5], v[18:19] op_sel_hi:[1,0,1] neg_lo:[0,0,1] neg_hi:[0,0,1]
	v_pk_fma_f32 v[4:5], v[20:21], v[4:5], v[32:33] op_sel_hi:[1,0,1] neg_lo:[0,0,1] neg_hi:[0,0,1]
	v_pk_mul_f32 v[18:19], v[16:17], v[16:17]
	v_pk_mul_f32 v[20:21], v[4:5], v[4:5]
	v_add_f32_e32 v6, v18, v19
	v_add_f32_e32 v6, v21, v6
	v_add_f32_e32 v6, v20, v6
	ds_bpermute_b32 v18, v139, v6
	global_store_short v[2:3], v1, off offset:192
	v_mov_b32_e32 v3, v193
	v_mov_b32_e32 v86, v71
	v_mov_b32_e32 v22, v7
	s_waitcnt lgkmcnt(0)
	v_add_f32_e32 v6, v6, v18
	ds_bpermute_b32 v18, v0, v6
	v_mov_b32_e32 v20, v120
	v_mov_b32_e32 v21, v104
	v_mov_b32_e32 v104, v121
	s_waitcnt lgkmcnt(0)
	v_add_f32_e32 v6, v6, v18
	ds_bpermute_b32 v18, v48, v6
	s_waitcnt lgkmcnt(0)
	v_add_f32_e32 v6, v6, v18
	ds_bpermute_b32 v18, v64, v6
	s_waitcnt lgkmcnt(0)
	v_add_f32_e32 v6, v6, v18
	ds_bpermute_b32 v18, v112, v6
	s_waitcnt lgkmcnt(0)
	v_add_f32_e32 v6, v6, v18
	v_fmamk_f32 v6, v6, 0x3c000000, v202
	v_mul_f32_e32 v18, 0x4b800000, v6
	v_cmp_gt_f32_e32 vcc, s58, v6
	s_nop 1
	v_cndmask_b32_e32 v6, v6, v18, vcc
	v_rsq_f32_e32 v6, v6
	s_nop 0
	v_mul_f32_e32 v1, 0x45800000, v6
	v_cndmask_b32_e32 v1, v6, v1, vcc
	v_mul_f32_e32 v2, v138, v1
	v_mul_f32_e32 v6, v16, v2
	v_mul_f32_e32 v2, v137, v1
	v_mul_f32_e32 v16, v17, v2
	v_mul_f32_e32 v2, v136, v1
	v_mul_f32_e32 v1, v135, v1
	v_mul_f32_e32 v1, v4, v1
	v_lshlrev_b32_e32 v4, 16, v174
	v_mul_f32_e32 v5, v5, v2
	v_or_b32_e32 v2, 0xa000, v192
	v_mul_f32_e32 v4, v6, v4
	v_cvt_pk_bf16_f32 v4, v4, v193
	v_lshl_add_u64 v[2:3], v[128:129], 0, v[2:3]
	global_store_short v[2:3], v4, off
	v_lshlrev_b32_e32 v4, 16, v175
	v_mul_f32_e32 v4, v16, v4
	v_cvt_pk_bf16_f32 v4, v4, v193
	global_store_short v[2:3], v4, off offset:64
	v_lshlrev_b32_e32 v4, 16, v173
	v_mul_f32_e32 v4, v5, v4
	v_cvt_pk_bf16_f32 v4, v4, v193
	global_store_short v[2:3], v4, off offset:128
	v_lshlrev_b32_e32 v4, 16, v176
	v_mul_f32_e32 v1, v1, v4
	v_cvt_pk_bf16_f32 v1, v1, v193
	ds_read2_b32 v[4:5], v144 offset0:11 offset1:43
	global_store_short v[2:3], v1, off offset:192
	v_mov_b32_e32 v3, v193
	s_waitcnt lgkmcnt(0)
; __device__ __forceinline__ unsigned cvtpk(float lo, float hi) { unsigned r; asm volatile("v_cvt_pk_bf16_f32 %0, %1, %2" : "=v"(r) : "v"(lo), "v"(hi)); return r; }
; __device__ __forceinline__ float bf2f(bf16_t v) { return __uint_as_float((unsigned)v << 16); }
; __device__ __forceinline__ int crow(int r, int hi) { return (r & 3) + 8 * (r >> 2) + 4 * hi; }
; template <int MODE, bool FAST>
; __device__ __forceinline__ int attn_item(const AttnP& a, int b, int h, int blk, char* lds) {
;     ...
;     for (int r = 0; r < 16; ++r) {
;         const int cr = crow(r, hi);
;         const float ra = wsf[cr];
;         float v[4];
;         if (MODE == 0) {
;             const float rb = wsf[32 + cr];
;             float ss = 0.f;
; #pragma unroll
;             for (int d = 0; d < 4; ++d) { v[d] = o[0][d][r] * ra - o[NMAP - 1][d][r] * rb; ss += v[d] * v[d]; }
;             ss += __shfl_xor(ss, 1); ss += __shfl_xor(ss, 2); ss += __shfl_xor(ss, 4); ss += __shfl_xor(ss, 8); ss += __shfl_xor(ss, 16);
;             const float rstd = rsqrtf(ss * (1.f / 128.f) + 1e-5f);
; #pragma unroll
;             for (int d = 0; d < 4; ++d) v[d] *= rstd * sg[d];
;         } else {
; #pragma unroll
;             for (int d = 0; d < 4; ++d) v[d] = o[0][d][r] * ra;
;         }
;         const size_t ro = obase + (size_t)cr * DM;
; #pragma unroll
;         for (int d = 0; d < 4; ++d) { const float gg = bf2f(gq[r][d]); a.MIX[ro + d * 32] = (bf16_t)(cvtpk(v[d] * gg, 0.f) & 0xffffu); }
;     }
	v_mov_b32_e32 v6, v5
	v_pk_mul_f32 v[16:17], v[86:87], v[6:7] op_sel_hi:[1,0]
	v_pk_mul_f32 v[6:7], v[102:103], v[6:7] op_sel_hi:[1,0]
	v_pk_fma_f32 v[16:17], v[22:23], v[4:5], v[16:17] op_sel_hi:[1,0,1] neg_lo:[0,0,1] neg_hi:[0,0,1]
	v_pk_fma_f32 v[4:5], v[38:39], v[4:5], v[6:7] op_sel_hi:[1,0,1] neg_lo:[0,0,1] neg_hi:[0,0,1]
	v_pk_mul_f32 v[18:19], v[16:17], v[16:17]
	v_pk_mul_f32 v[6:7], v[4:5], v[4:5]
	v_add_f32_e32 v18, v18, v19
	v_add_f32_e32 v7, v7, v18
	v_add_f32_e32 v6, v6, v7
	ds_bpermute_b32 v7, v139, v6
	v_mov_b32_e32 v18, v56
	v_mov_b32_e32 v19, v40
	v_mov_b32_e32 v40, v57
	s_waitcnt lgkmcnt(0)
	v_add_f32_e32 v6, v6, v7
	ds_bpermute_b32 v7, v0, v6
	s_waitcnt lgkmcnt(0)
	v_add_f32_e32 v6, v6, v7
	ds_bpermute_b32 v7, v48, v6
	s_waitcnt lgkmcnt(0)
	v_add_f32_e32 v6, v6, v7
	ds_bpermute_b32 v7, v64, v6
	s_waitcnt lgkmcnt(0)
	v_add_f32_e32 v6, v6, v7
	ds_bpermute_b32 v7, v112, v6
	s_waitcnt lgkmcnt(0)
	v_add_f32_e32 v6, v6, v7
	v_fmamk_f32 v6, v6, 0x3c000000, v202
	v_mul_f32_e32 v7, 0x4b800000, v6
	v_cmp_gt_f32_e32 vcc, s58, v6
	s_nop 1
	v_cndmask_b32_e32 v6, v6, v7, vcc
	v_rsq_f32_e32 v6, v6
	s_nop 0
	v_mul_f32_e32 v1, 0x45800000, v6
	v_cndmask_b32_e32 v1, v6, v1, vcc
	v_mul_f32_e32 v2, v138, v1
	v_mul_f32_e32 v6, v16, v2
	v_mul_f32_e32 v2, v137, v1
	v_mul_f32_e32 v7, v17, v2
	v_mul_f32_e32 v2, v136, v1
	v_mul_f32_e32 v1, v135, v1
	v_mul_f32_e32 v1, v4, v1
	v_lshlrev_b32_e32 v4, 16, v172
	v_mul_f32_e32 v5, v5, v2
	v_or_b32_e32 v2, 0xb000, v192
	v_mul_f32_e32 v4, v6, v4
	v_cvt_pk_bf16_f32 v4, v4, v193
	v_lshl_add_u64 v[2:3], v[128:129], 0, v[2:3]
	global_store_short v[2:3], v4, off
	v_lshlrev_b32_e32 v4, 16, v171
	v_mul_f32_e32 v4, v7, v4
	v_cvt_pk_bf16_f32 v4, v4, v193
	global_store_short v[2:3], v4, off offset:64
	v_lshlrev_b32_e32 v4, 16, v170
	v_mul_f32_e32 v4, v5, v4
	v_cvt_pk_bf16_f32 v4, v4, v193
	global_store_short v[2:3], v4, off offset:128
	v_lshlrev_b32_e32 v4, 16, v169
	v_mul_f32_e32 v1, v1, v4
	v_cvt_pk_bf16_f32 v1, v1, v193
	ds_read2_b32 v[4:5], v144 offset0:16 offset1:48
	v_mov_b32_e32 v6, v8
	v_mov_b32_e32 v16, v72
	v_mov_b32_e32 v17, v88
	v_mov_b32_e32 v7, v24
	s_waitcnt lgkmcnt(0)
	v_mov_b32_e32 v8, v5
	v_pk_mul_f32 v[16:17], v[16:17], v[8:9] op_sel_hi:[1,0]
	v_pk_mul_f32 v[20:21], v[20:21], v[8:9] op_sel_hi:[1,0]
	v_pk_fma_f32 v[6:7], v[6:7], v[4:5], v[16:17] op_sel_hi:[1,0,1] neg_lo:[0,0,1] neg_hi:[0,0,1]
	v_pk_fma_f32 v[4:5], v[18:19], v[4:5], v[20:21] op_sel_hi:[1,0,1] neg_lo:[0,0,1] neg_hi:[0,0,1]
	v_pk_mul_f32 v[16:17], v[6:7], v[6:7]
	v_pk_mul_f32 v[18:19], v[4:5], v[4:5]
	v_add_f32_e32 v8, v16, v17
	v_add_f32_e32 v8, v19, v8
	v_add_f32_e32 v8, v18, v8
	ds_bpermute_b32 v16, v139, v8
	global_store_short v[2:3], v1, off offset:192
	v_mov_b32_e32 v3, v193
	v_mov_b32_e32 v88, v73
	v_mov_b32_e32 v24, v9
	s_waitcnt lgkmcnt(0)
	v_add_f32_e32 v8, v8, v16
	ds_bpermute_b32 v16, v0, v8
	v_mov_b32_e32 v18, v122
	v_mov_b32_e32 v19, v106
	v_mov_b32_e32 v106, v123
	s_waitcnt lgkmcnt(0)
	v_add_f32_e32 v8, v8, v16
	ds_bpermute_b32 v16, v48, v8
	s_waitcnt lgkmcnt(0)
	v_add_f32_e32 v8, v8, v16
	ds_bpermute_b32 v16, v64, v8
	s_waitcnt lgkmcnt(0)
	v_add_f32_e32 v8, v8, v16
	ds_bpermute_b32 v16, v112, v8
	s_waitcnt lgkmcnt(0)
	v_add_f32_e32 v8, v8, v16
	v_fmamk_f32 v8, v8, 0x3c000000, v202
	v_mul_f32_e32 v16, 0x4b800000, v8
	v_cmp_gt_f32_e32 vcc, s58, v8
	s_nop 1
	v_cndmask_b32_e32 v8, v8, v16, vcc
	v_rsq_f32_e32 v8, v8
	s_nop 0
	v_mul_f32_e32 v1, 0x45800000, v8
	v_cndmask_b32_e32 v1, v8, v1, vcc
	v_mul_f32_e32 v2, v138, v1
	v_mul_f32_e32 v6, v6, v2
	v_mul_f32_e32 v2, v137, v1
	v_mul_f32_e32 v7, v7, v2
	v_mul_f32_e32 v2, v136, v1
	v_mul_f32_e32 v1, v135, v1
	v_mul_f32_e32 v1, v4, v1
	v_lshlrev_b32_e32 v4, 16, v165
	v_mul_f32_e32 v5, v5, v2
	v_or_b32_e32 v2, 0x10000, v192
	v_mul_f32_e32 v4, v6, v4
	v_cvt_pk_bf16_f32 v4, v4, v193
	v_lshl_add_u64 v[2:3], v[128:129], 0, v[2:3]
	global_store_short v[2:3], v4, off
	v_lshlrev_b32_e32 v4, 16, v168
	v_mul_f32_e32 v4, v7, v4
	v_cvt_pk_bf16_f32 v4, v4, v193
	global_store_short v[2:3], v4, off offset:64
	v_lshlrev_b32_e32 v4, 16, v167
	v_mul_f32_e32 v4, v5, v4
	v_cvt_pk_bf16_f32 v4, v4, v193
	global_store_short v[2:3], v4, off offset:128
	v_lshlrev_b32_e32 v4, 16, v166
	v_mul_f32_e32 v1, v1, v4
	v_cvt_pk_bf16_f32 v1, v1, v193
	ds_read2_b32 v[4:5], v144 offset0:17 offset1:49
	global_store_short v[2:3], v1, off offset:192
	v_mov_b32_e32 v3, v193
	s_waitcnt lgkmcnt(0)
	v_mov_b32_e32 v6, v5
	v_pk_mul_f32 v[8:9], v[88:89], v[6:7] op_sel_hi:[1,0]
	v_pk_mul_f32 v[6:7], v[104:105], v[6:7] op_sel_hi:[1,0]
	v_pk_fma_f32 v[8:9], v[24:25], v[4:5], v[8:9] op_sel_hi:[1,0,1] neg_lo:[0,0,1] neg_hi:[0,0,1]
	v_pk_fma_f32 v[4:5], v[40:41], v[4:5], v[6:7] op_sel_hi:[1,0,1] neg_lo:[0,0,1] neg_hi:[0,0,1]
	v_pk_mul_f32 v[16:17], v[8:9], v[8:9]
	v_pk_mul_f32 v[6:7], v[4:5], v[4:5]
	v_add_f32_e32 v16, v16, v17
	v_add_f32_e32 v7, v7, v16
	v_add_f32_e32 v6, v6, v7
	ds_bpermute_b32 v7, v139, v6
	v_mov_b32_e32 v16, v58
	v_mov_b32_e32 v17, v42
	v_mov_b32_e32 v42, v59
	s_waitcnt lgkmcnt(0)
	v_add_f32_e32 v6, v6, v7
	ds_bpermute_b32 v7, v0, v6
	s_waitcnt lgkmcnt(0)
	v_add_f32_e32 v6, v6, v7
	ds_bpermute_b32 v7, v48, v6
	s_waitcnt lgkmcnt(0)
	v_add_f32_e32 v6, v6, v7
	ds_bpermute_b32 v7, v64, v6
	s_waitcnt lgkmcnt(0)
	v_add_f32_e32 v6, v6, v7
	ds_bpermute_b32 v7, v112, v6
	s_waitcnt lgkmcnt(0)
; __device__ __forceinline__ unsigned cvtpk(float lo, float hi) { unsigned r; asm volatile("v_cvt_pk_bf16_f32 %0, %1, %2" : "=v"(r) : "v"(lo), "v"(hi)); return r; }
; __device__ __forceinline__ float bf2f(bf16_t v) { return __uint_as_float((unsigned)v << 16); }
; __device__ __forceinline__ int crow(int r, int hi) { return (r & 3) + 8 * (r >> 2) + 4 * hi; }
; template <int MODE, bool FAST>
; __device__ __forceinline__ int attn_item(const AttnP& a, int b, int h, int blk, char* lds) {
;     ...
;     for (int r = 0; r < 16; ++r) {
;         const int cr = crow(r, hi);
;         const float ra = wsf[cr];
;         float v[4];
;         if (MODE == 0) {
;             const float rb = wsf[32 + cr];
;             float ss = 0.f;
; #pragma unroll
;             for (int d = 0; d < 4; ++d) { v[d] = o[0][d][r] * ra - o[NMAP - 1][d][r] * rb; ss += v[d] * v[d]; }
;             ss += __shfl_xor(ss, 1); ss += __shfl_xor(ss, 2); ss += __shfl_xor(ss, 4); ss += __shfl_xor(ss, 8); ss += __shfl_xor(ss, 16);
;             const float rstd = rsqrtf(ss * (1.f / 128.f) + 1e-5f);
; #pragma unroll
;             for (int d = 0; d < 4; ++d) v[d] *= rstd * sg[d];
;         } else {
; #pragma unroll
;             for (int d = 0; d < 4; ++d) v[d] = o[0][d][r] * ra;
;         }
;         const size_t ro = obase + (size_t)cr * DM;
; #pragma unroll
;         for (int d = 0; d < 4; ++d) { const float gg = bf2f(gq[r][d]); a.MIX[ro + d * 32] = (bf16_t)(cvtpk(v[d] * gg, 0.f) & 0xffffu); }
;     }
	v_add_f32_e32 v6, v6, v7
	v_fmamk_f32 v6, v6, 0x3c000000, v202
	v_mul_f32_e32 v7, 0x4b800000, v6
	v_cmp_gt_f32_e32 vcc, s58, v6
	s_nop 1
	v_cndmask_b32_e32 v6, v6, v7, vcc
	v_rsq_f32_e32 v6, v6
	s_nop 0
	v_mul_f32_e32 v1, 0x45800000, v6
	v_cndmask_b32_e32 v1, v6, v1, vcc
	v_mul_f32_e32 v2, v138, v1
	v_mul_f32_e32 v6, v8, v2
	v_mul_f32_e32 v2, v137, v1
	v_mul_f32_e32 v7, v9, v2
	v_mul_f32_e32 v2, v136, v1
	v_mul_f32_e32 v1, v135, v1
	v_mul_f32_e32 v1, v4, v1
	v_lshlrev_b32_e32 v4, 16, v163
	v_mul_f32_e32 v5, v5, v2
	v_or_b32_e32 v2, 0x11000, v192
	v_mul_f32_e32 v4, v6, v4
	v_cvt_pk_bf16_f32 v4, v4, v193
	v_lshl_add_u64 v[2:3], v[128:129], 0, v[2:3]
	global_store_short v[2:3], v4, off
	v_lshlrev_b32_e32 v4, 16, v162
	v_mul_f32_e32 v4, v7, v4
	v_cvt_pk_bf16_f32 v4, v4, v193
	global_store_short v[2:3], v4, off offset:64
	v_lshlrev_b32_e32 v4, 16, v161
	v_mul_f32_e32 v4, v5, v4
	v_cvt_pk_bf16_f32 v4, v4, v193
	global_store_short v[2:3], v4, off offset:128
	v_lshlrev_b32_e32 v4, 16, v164
	v_mul_f32_e32 v1, v1, v4
	v_cvt_pk_bf16_f32 v1, v1, v193
	ds_read2_b32 v[4:5], v144 offset0:18 offset1:50
	v_mov_b32_e32 v6, v10
	v_mov_b32_e32 v8, v74
	v_mov_b32_e32 v9, v90
	v_mov_b32_e32 v7, v26
	s_waitcnt lgkmcnt(0)
	v_mov_b32_e32 v10, v5
	v_pk_mul_f32 v[8:9], v[8:9], v[10:11] op_sel_hi:[1,0]
	v_pk_mul_f32 v[18:19], v[18:19], v[10:11] op_sel_hi:[1,0]
	v_pk_fma_f32 v[6:7], v[6:7], v[4:5], v[8:9] op_sel_hi:[1,0,1] neg_lo:[0,0,1] neg_hi:[0,0,1]
	v_pk_fma_f32 v[4:5], v[16:17], v[4:5], v[18:19] op_sel_hi:[1,0,1] neg_lo:[0,0,1] neg_hi:[0,0,1]
	v_pk_mul_f32 v[8:9], v[6:7], v[6:7]
	v_pk_mul_f32 v[16:17], v[4:5], v[4:5]
	v_add_f32_e32 v8, v8, v9
	v_add_f32_e32 v8, v17, v8
	v_add_f32_e32 v8, v16, v8
	ds_bpermute_b32 v9, v139, v8
	global_store_short v[2:3], v1, off offset:192
	v_mov_b32_e32 v3, v193
	v_mov_b32_e32 v90, v75
	v_mov_b32_e32 v26, v11
	s_waitcnt lgkmcnt(0)
	v_add_f32_e32 v8, v8, v9
	ds_bpermute_b32 v9, v0, v8
	v_mov_b32_e32 v18, v124
	v_mov_b32_e32 v19, v108
	v_mov_b32_e32 v16, v60
	v_mov_b32_e32 v17, v44
	s_waitcnt lgkmcnt(0)
	v_add_f32_e32 v8, v8, v9
	ds_bpermute_b32 v9, v48, v8
	v_mov_b32_e32 v108, v125
	v_mov_b32_e32 v44, v61
	s_waitcnt lgkmcnt(0)
	v_add_f32_e32 v8, v8, v9
	ds_bpermute_b32 v9, v64, v8
	s_waitcnt lgkmcnt(0)
	v_add_f32_e32 v8, v8, v9
	ds_bpermute_b32 v9, v112, v8
	s_waitcnt lgkmcnt(0)
	v_add_f32_e32 v8, v8, v9
	v_fmamk_f32 v8, v8, 0x3c000000, v202
	v_mul_f32_e32 v9, 0x4b800000, v8
	v_cmp_gt_f32_e32 vcc, s58, v8
	s_nop 1
	v_cndmask_b32_e32 v8, v8, v9, vcc
	v_rsq_f32_e32 v8, v8
	s_nop 0
	v_mul_f32_e32 v1, 0x45800000, v8
	v_cndmask_b32_e32 v1, v8, v1, vcc
	v_mul_f32_e32 v2, v138, v1
	v_mul_f32_e32 v6, v6, v2
	v_mul_f32_e32 v2, v137, v1
	v_mul_f32_e32 v7, v7, v2
	v_mul_f32_e32 v2, v136, v1
	v_mul_f32_e32 v1, v135, v1
	v_mul_f32_e32 v1, v4, v1
	v_lshlrev_b32_e32 v4, 16, v160
	v_mul_f32_e32 v5, v5, v2
	v_or_b32_e32 v2, 0x12000, v192
	v_mul_f32_e32 v4, v6, v4
	v_cvt_pk_bf16_f32 v4, v4, v193
	v_lshl_add_u64 v[2:3], v[128:129], 0, v[2:3]
	global_store_short v[2:3], v4, off
	v_lshlrev_b32_e32 v4, 16, v159
	v_mul_f32_e32 v4, v7, v4
	v_cvt_pk_bf16_f32 v4, v4, v193
	global_store_short v[2:3], v4, off offset:64
	v_lshlrev_b32_e32 v4, 16, v158
	v_mul_f32_e32 v4, v5, v4
	v_cvt_pk_bf16_f32 v4, v4, v193
	global_store_short v[2:3], v4, off offset:128
	v_lshlrev_b32_e32 v4, 16, v157
	v_mul_f32_e32 v1, v1, v4
	v_cvt_pk_bf16_f32 v1, v1, v193
	ds_read2_b32 v[4:5], v144 offset0:19 offset1:51
	global_store_short v[2:3], v1, off offset:192
	v_mov_b32_e32 v3, v193
	s_waitcnt lgkmcnt(0)
	v_mov_b32_e32 v6, v5
	v_pk_mul_f32 v[8:9], v[90:91], v[6:7] op_sel_hi:[1,0]
	v_pk_mul_f32 v[6:7], v[106:107], v[6:7] op_sel_hi:[1,0]
	v_pk_fma_f32 v[8:9], v[26:27], v[4:5], v[8:9] op_sel_hi:[1,0,1] neg_lo:[0,0,1] neg_hi:[0,0,1]
	v_pk_fma_f32 v[4:5], v[42:43], v[4:5], v[6:7] op_sel_hi:[1,0,1] neg_lo:[0,0,1] neg_hi:[0,0,1]
	v_pk_mul_f32 v[10:11], v[8:9], v[8:9]
	v_pk_mul_f32 v[6:7], v[4:5], v[4:5]
	v_add_f32_e32 v10, v10, v11
	v_add_f32_e32 v7, v7, v10
	v_add_f32_e32 v6, v6, v7
	ds_bpermute_b32 v7, v139, v6
	s_waitcnt lgkmcnt(0)
	v_add_f32_e32 v6, v6, v7
	ds_bpermute_b32 v7, v0, v6
	s_waitcnt lgkmcnt(0)
	v_add_f32_e32 v6, v6, v7
	ds_bpermute_b32 v7, v48, v6
	s_waitcnt lgkmcnt(0)
	v_add_f32_e32 v6, v6, v7
	ds_bpermute_b32 v7, v64, v6
	s_waitcnt lgkmcnt(0)
	v_add_f32_e32 v6, v6, v7
	ds_bpermute_b32 v7, v112, v6
	s_waitcnt lgkmcnt(0)
	v_add_f32_e32 v6, v6, v7
	v_fmamk_f32 v6, v6, 0x3c000000, v202
	v_mul_f32_e32 v7, 0x4b800000, v6
	v_cmp_gt_f32_e32 vcc, s58, v6
	s_nop 1
	v_cndmask_b32_e32 v6, v6, v7, vcc
	v_rsq_f32_e32 v6, v6
	s_nop 0
	v_mul_f32_e32 v1, 0x45800000, v6
	v_cndmask_b32_e32 v1, v6, v1, vcc
	v_mul_f32_e32 v2, v138, v1
	v_mul_f32_e32 v6, v8, v2
	v_mul_f32_e32 v2, v137, v1
	v_mul_f32_e32 v7, v9, v2
	v_mul_f32_e32 v2, v136, v1
	v_mul_f32_e32 v1, v135, v1
	v_mul_f32_e32 v1, v4, v1
	v_lshlrev_b32_e32 v4, 16, v156
	v_mul_f32_e32 v5, v5, v2
	v_or_b32_e32 v2, 0x13000, v192
	v_mul_f32_e32 v4, v6, v4
	v_cvt_pk_bf16_f32 v4, v4, v193
	v_lshl_add_u64 v[2:3], v[128:129], 0, v[2:3]
	global_store_short v[2:3], v4, off
	v_lshlrev_b32_e32 v4, 16, v155
	v_mul_f32_e32 v4, v7, v4
	v_cvt_pk_bf16_f32 v4, v4, v193
	global_store_short v[2:3], v4, off offset:64
	v_lshlrev_b32_e32 v4, 16, v154
	v_mul_f32_e32 v4, v5, v4
	v_cvt_pk_bf16_f32 v4, v4, v193
	global_store_short v[2:3], v4, off offset:128
	v_lshlrev_b32_e32 v4, 16, v153
	v_mul_f32_e32 v1, v1, v4
	v_cvt_pk_bf16_f32 v1, v1, v193
	ds_read2_b32 v[4:5], v144 offset0:24 offset1:56
	v_mov_b32_e32 v8, v76
	v_mov_b32_e32 v9, v92
	v_mov_b32_e32 v6, v12
	v_mov_b32_e32 v7, v28
	s_waitcnt lgkmcnt(0)
; __device__ __forceinline__ unsigned cvtpk(float lo, float hi) { unsigned r; asm volatile("v_cvt_pk_bf16_f32 %0, %1, %2" : "=v"(r) : "v"(lo), "v"(hi)); return r; }
; __device__ __forceinline__ float bf2f(bf16_t v) { return __uint_as_float((unsigned)v << 16); }
; __device__ __forceinline__ int crow(int r, int hi) { return (r & 3) + 8 * (r >> 2) + 4 * hi; }
; template <int MODE, bool FAST>
; __device__ __forceinline__ int attn_item(const AttnP& a, int b, int h, int blk, char* lds) {
;     ...
;     for (int r = 0; r < 16; ++r) {
;         const int cr = crow(r, hi);
;         const float ra = wsf[cr];
;         float v[4];
;         if (MODE == 0) {
;             const float rb = wsf[32 + cr];
;             float ss = 0.f;
; #pragma unroll
;             for (int d = 0; d < 4; ++d) { v[d] = o[0][d][r] * ra - o[NMAP - 1][d][r] * rb; ss += v[d] * v[d]; }
;             ss += __shfl_xor(ss, 1); ss += __shfl_xor(ss, 2); ss += __shfl_xor(ss, 4); ss += __shfl_xor(ss, 8); ss += __shfl_xor(ss, 16);
;             const float rstd = rsqrtf(ss * (1.f / 128.f) + 1e-5f);
; #pragma unroll
;             for (int d = 0; d < 4; ++d) v[d] *= rstd * sg[d];
;         } else {
; #pragma unroll
;             for (int d = 0; d < 4; ++d) v[d] = o[0][d][r] * ra;
;         }
;         const size_t ro = obase + (size_t)cr * DM;
; #pragma unroll
;         for (int d = 0; d < 4; ++d) { const float gg = bf2f(gq[r][d]); a.MIX[ro + d * 32] = (bf16_t)(cvtpk(v[d] * gg, 0.f) & 0xffffu); }
;     }
	v_mov_b32_e32 v10, v5
	v_pk_mul_f32 v[8:9], v[8:9], v[10:11] op_sel_hi:[1,0]
	v_pk_mul_f32 v[10:11], v[18:19], v[10:11] op_sel_hi:[1,0]
	v_pk_fma_f32 v[6:7], v[6:7], v[4:5], v[8:9] op_sel_hi:[1,0,1] neg_lo:[0,0,1] neg_hi:[0,0,1]
	v_pk_fma_f32 v[4:5], v[16:17], v[4:5], v[10:11] op_sel_hi:[1,0,1] neg_lo:[0,0,1] neg_hi:[0,0,1]
	v_pk_mul_f32 v[8:9], v[6:7], v[6:7]
	v_pk_mul_f32 v[10:11], v[4:5], v[4:5]
	v_add_f32_e32 v8, v8, v9
	v_add_f32_e32 v8, v11, v8
	v_add_f32_e32 v8, v10, v8
	ds_bpermute_b32 v9, v139, v8
	global_store_short v[2:3], v1, off offset:192
	v_mov_b32_e32 v3, v193
	v_mov_b32_e32 v92, v77
	v_mov_b32_e32 v28, v13
	s_waitcnt lgkmcnt(0)
	v_add_f32_e32 v8, v8, v9
	ds_bpermute_b32 v9, v0, v8
	v_mov_b32_e32 v16, v126
	v_mov_b32_e32 v17, v110
	v_mov_b32_e32 v12, v62
	v_mov_b32_e32 v13, v46
	s_waitcnt lgkmcnt(0)
	v_add_f32_e32 v8, v8, v9
	ds_bpermute_b32 v9, v48, v8
	v_mov_b32_e32 v110, v127
	v_mov_b32_e32 v46, v63
	s_waitcnt lgkmcnt(0)
	v_add_f32_e32 v8, v8, v9
	ds_bpermute_b32 v9, v64, v8
	s_waitcnt lgkmcnt(0)
	v_add_f32_e32 v8, v8, v9
	ds_bpermute_b32 v9, v112, v8
	s_waitcnt lgkmcnt(0)
	v_add_f32_e32 v8, v8, v9
	v_fmamk_f32 v8, v8, 0x3c000000, v202
	v_mul_f32_e32 v9, 0x4b800000, v8
	v_cmp_gt_f32_e32 vcc, s58, v8
	s_nop 1
	v_cndmask_b32_e32 v8, v8, v9, vcc
	v_rsq_f32_e32 v8, v8
	s_nop 0
	v_mul_f32_e32 v1, 0x45800000, v8
	v_cndmask_b32_e32 v1, v8, v1, vcc
	v_mul_f32_e32 v2, v138, v1
	v_mul_f32_e32 v6, v6, v2
	v_mul_f32_e32 v2, v137, v1
	v_mul_f32_e32 v7, v7, v2
	v_mul_f32_e32 v2, v136, v1
	v_mul_f32_e32 v1, v135, v1
	v_mul_f32_e32 v1, v4, v1
	v_lshlrev_b32_e32 v4, 16, v150
	v_mul_f32_e32 v5, v5, v2
	v_or_b32_e32 v2, 0x18000, v192
	v_mul_f32_e32 v4, v6, v4
	v_cvt_pk_bf16_f32 v4, v4, v193
	v_lshl_add_u64 v[2:3], v[128:129], 0, v[2:3]
	global_store_short v[2:3], v4, off
	v_lshlrev_b32_e32 v4, 16, v149
	v_mul_f32_e32 v4, v7, v4
	v_cvt_pk_bf16_f32 v4, v4, v193
	global_store_short v[2:3], v4, off offset:64
	s_waitcnt vmcnt(62)
	v_lshlrev_b32_e32 v4, 16, v152
	v_mul_f32_e32 v4, v5, v4
	v_cvt_pk_bf16_f32 v4, v4, v193
	global_store_short v[2:3], v4, off offset:128
	s_waitcnt vmcnt(62)
	v_lshlrev_b32_e32 v4, 16, v151
	v_mul_f32_e32 v1, v1, v4
	v_cvt_pk_bf16_f32 v1, v1, v193
	ds_read2_b32 v[4:5], v144 offset0:25 offset1:57
	global_store_short v[2:3], v1, off offset:192
	v_mov_b32_e32 v3, v193
	s_waitcnt lgkmcnt(0)
	v_mov_b32_e32 v6, v5
	v_pk_mul_f32 v[8:9], v[92:93], v[6:7] op_sel_hi:[1,0]
	v_pk_mul_f32 v[6:7], v[108:109], v[6:7] op_sel_hi:[1,0]
	v_pk_fma_f32 v[8:9], v[28:29], v[4:5], v[8:9] op_sel_hi:[1,0,1] neg_lo:[0,0,1] neg_hi:[0,0,1]
	v_pk_fma_f32 v[4:5], v[44:45], v[4:5], v[6:7] op_sel_hi:[1,0,1] neg_lo:[0,0,1] neg_hi:[0,0,1]
	v_pk_mul_f32 v[10:11], v[8:9], v[8:9]
	v_pk_mul_f32 v[6:7], v[4:5], v[4:5]
	v_add_f32_e32 v10, v10, v11
	v_add_f32_e32 v7, v7, v10
	v_add_f32_e32 v6, v6, v7
	ds_bpermute_b32 v7, v139, v6
	s_waitcnt lgkmcnt(0)
	v_add_f32_e32 v6, v6, v7
	ds_bpermute_b32 v7, v0, v6
	s_waitcnt lgkmcnt(0)
	v_add_f32_e32 v6, v6, v7
	ds_bpermute_b32 v7, v48, v6
	s_waitcnt lgkmcnt(0)
	v_add_f32_e32 v6, v6, v7
	ds_bpermute_b32 v7, v64, v6
	s_waitcnt lgkmcnt(0)
	v_add_f32_e32 v6, v6, v7
	ds_bpermute_b32 v7, v112, v6
	s_waitcnt lgkmcnt(0)
	v_add_f32_e32 v6, v6, v7
	v_fmamk_f32 v6, v6, 0x3c000000, v202
	v_mul_f32_e32 v7, 0x4b800000, v6
	v_cmp_gt_f32_e32 vcc, s58, v6
	s_nop 1
	v_cndmask_b32_e32 v6, v6, v7, vcc
	v_rsq_f32_e32 v6, v6
	s_nop 0
	v_mul_f32_e32 v1, 0x45800000, v6
	v_cndmask_b32_e32 v1, v6, v1, vcc
	v_mul_f32_e32 v2, v138, v1
	v_mul_f32_e32 v6, v8, v2
	v_mul_f32_e32 v2, v137, v1
	v_mul_f32_e32 v7, v9, v2
	v_mul_f32_e32 v2, v136, v1
	v_mul_f32_e32 v1, v135, v1
	v_mul_f32_e32 v1, v4, v1
	v_lshlrev_b32_e32 v4, 16, v145
	v_mul_f32_e32 v5, v5, v2
	v_or_b32_e32 v2, 0x19000, v192
	v_mul_f32_e32 v4, v6, v4
	v_cvt_pk_bf16_f32 v4, v4, v193
	v_lshl_add_u64 v[2:3], v[128:129], 0, v[2:3]
	global_store_short v[2:3], v4, off
	s_waitcnt vmcnt(60)
	v_lshlrev_b32_e32 v4, 16, v148
	v_mul_f32_e32 v4, v7, v4
	v_cvt_pk_bf16_f32 v4, v4, v193
	global_store_short v[2:3], v4, off offset:64
	s_waitcnt vmcnt(60)
	v_lshlrev_b32_e32 v4, 16, v147
	v_mul_f32_e32 v4, v5, v4
	v_cvt_pk_bf16_f32 v4, v4, v193
	global_store_short v[2:3], v4, off offset:128
	s_waitcnt vmcnt(60)
; __device__ __forceinline__ unsigned cvtpk(float lo, float hi) { unsigned r; asm volatile("v_cvt_pk_bf16_f32 %0, %1, %2" : "=v"(r) : "v"(lo), "v"(hi)); return r; }
; __device__ __forceinline__ float bf2f(bf16_t v) { return __uint_as_float((unsigned)v << 16); }
; __device__ __forceinline__ int crow(int r, int hi) { return (r & 3) + 8 * (r >> 2) + 4 * hi; }
; template <int MODE, bool FAST>
; __device__ __forceinline__ int attn_item(const AttnP& a, int b, int h, int blk, char* lds) {
;     ...
;     for (int r = 0; r < 16; ++r) {
;         const int cr = crow(r, hi);
;         const float ra = wsf[cr];
;         float v[4];
;         if (MODE == 0) {
;             const float rb = wsf[32 + cr];
;             float ss = 0.f;
; #pragma unroll
;             for (int d = 0; d < 4; ++d) { v[d] = o[0][d][r] * ra - o[NMAP - 1][d][r] * rb; ss += v[d] * v[d]; }
;             ss += __shfl_xor(ss, 1); ss += __shfl_xor(ss, 2); ss += __shfl_xor(ss, 4); ss += __shfl_xor(ss, 8); ss += __shfl_xor(ss, 16);
;             const float rstd = rsqrtf(ss * (1.f / 128.f) + 1e-5f);
; #pragma unroll
;             for (int d = 0; d < 4; ++d) v[d] *= rstd * sg[d];
;         } else {
; #pragma unroll
;             for (int d = 0; d < 4; ++d) v[d] = o[0][d][r] * ra;
;         }
;         const size_t ro = obase + (size_t)cr * DM;
; #pragma unroll
;         for (int d = 0; d < 4; ++d) { const float gg = bf2f(gq[r][d]); a.MIX[ro + d * 32] = (bf16_t)(cvtpk(v[d] * gg, 0.f) & 0xffffu); }
;     }
	v_lshlrev_b32_e32 v4, 16, v146
	v_mul_f32_e32 v1, v1, v4
	v_cvt_pk_bf16_f32 v1, v1, v193
	ds_read2_b32 v[4:5], v144 offset0:26 offset1:58
	v_mov_b32_e32 v8, v78
	v_mov_b32_e32 v9, v94
	v_mov_b32_e32 v6, v14
	v_mov_b32_e32 v7, v30
	s_waitcnt lgkmcnt(0)
	v_mov_b32_e32 v10, v5
	v_pk_mul_f32 v[8:9], v[8:9], v[10:11] op_sel_hi:[1,0]
	v_pk_mul_f32 v[10:11], v[16:17], v[10:11] op_sel_hi:[1,0]
	v_pk_fma_f32 v[6:7], v[6:7], v[4:5], v[8:9] op_sel_hi:[1,0,1] neg_lo:[0,0,1] neg_hi:[0,0,1]
	v_pk_fma_f32 v[4:5], v[12:13], v[4:5], v[10:11] op_sel_hi:[1,0,1] neg_lo:[0,0,1] neg_hi:[0,0,1]
	v_pk_mul_f32 v[8:9], v[6:7], v[6:7]
	v_pk_mul_f32 v[10:11], v[4:5], v[4:5]
	v_add_f32_e32 v8, v8, v9
	v_add_f32_e32 v8, v11, v8
	v_add_f32_e32 v8, v10, v8
	ds_bpermute_b32 v9, v139, v8
	global_store_short v[2:3], v1, off offset:192
	v_mov_b32_e32 v3, v193
	v_mov_b32_e32 v94, v79
	v_mov_b32_e32 v30, v15
	s_waitcnt lgkmcnt(0)
	v_add_f32_e32 v8, v8, v9
	ds_bpermute_b32 v9, v0, v8
	s_waitcnt lgkmcnt(0)
	v_add_f32_e32 v8, v8, v9
	ds_bpermute_b32 v9, v48, v8
	s_waitcnt lgkmcnt(0)
	v_add_f32_e32 v8, v8, v9
	ds_bpermute_b32 v9, v64, v8
	s_waitcnt lgkmcnt(0)
	v_add_f32_e32 v8, v8, v9
	ds_bpermute_b32 v9, v112, v8
	s_waitcnt lgkmcnt(0)
	v_add_f32_e32 v8, v8, v9
	v_fmamk_f32 v8, v8, 0x3c000000, v202
	v_mul_f32_e32 v9, 0x4b800000, v8
	v_cmp_gt_f32_e32 vcc, s58, v8
	s_nop 1
	v_cndmask_b32_e32 v8, v8, v9, vcc
	v_rsq_f32_e32 v8, v8
	s_nop 0
	v_mul_f32_e32 v1, 0x45800000, v8
	v_cndmask_b32_e32 v1, v8, v1, vcc
	v_mul_f32_e32 v2, v138, v1
	v_mul_f32_e32 v6, v6, v2
	v_mul_f32_e32 v2, v137, v1
	v_mul_f32_e32 v7, v7, v2
	v_mul_f32_e32 v2, v136, v1
	v_mul_f32_e32 v1, v135, v1
	v_mul_f32_e32 v1, v4, v1
	s_waitcnt vmcnt(60)
	v_lshlrev_b32_e32 v4, 16, v143
	v_mul_f32_e32 v5, v5, v2
	v_or_b32_e32 v2, 0x1a000, v192
	v_mul_f32_e32 v4, v6, v4
	v_cvt_pk_bf16_f32 v4, v4, v193
	v_lshl_add_u64 v[2:3], v[128:129], 0, v[2:3]
	global_store_short v[2:3], v4, off
	v_lshlrev_b32_e32 v4, 16, v142
	v_mul_f32_e32 v4, v7, v4
	v_cvt_pk_bf16_f32 v4, v4, v193
	global_store_short v[2:3], v4, off offset:64
	v_lshlrev_b32_e32 v4, 16, v141
	v_mul_f32_e32 v4, v5, v4
	v_cvt_pk_bf16_f32 v4, v4, v193
	global_store_short v[2:3], v4, off offset:128
	v_lshlrev_b32_e32 v4, 16, v140
	v_mul_f32_e32 v1, v1, v4
	v_cvt_pk_bf16_f32 v1, v1, v193
	ds_read2_b32 v[4:5], v144 offset0:27 offset1:59
	global_store_short v[2:3], v1, off offset:192
	v_or_b32_e32 v192, 0x1b000, v192
	s_waitcnt lgkmcnt(0)
	v_mov_b32_e32 v6, v5
	v_pk_mul_f32 v[8:9], v[94:95], v[6:7] op_sel_hi:[1,0]
	v_pk_mul_f32 v[6:7], v[110:111], v[6:7] op_sel_hi:[1,0]
	v_pk_fma_f32 v[8:9], v[30:31], v[4:5], v[8:9] op_sel_hi:[1,0,1] neg_lo:[0,0,1] neg_hi:[0,0,1]
	v_pk_fma_f32 v[4:5], v[46:47], v[4:5], v[6:7] op_sel_hi:[1,0,1] neg_lo:[0,0,1] neg_hi:[0,0,1]
	v_pk_mul_f32 v[10:11], v[8:9], v[8:9]
	v_pk_mul_f32 v[6:7], v[4:5], v[4:5]
	v_add_f32_e32 v10, v10, v11
	v_add_f32_e32 v7, v7, v10
	v_add_f32_e32 v6, v6, v7
	ds_bpermute_b32 v7, v139, v6
	s_waitcnt lgkmcnt(0)
	v_add_f32_e32 v6, v6, v7
	ds_bpermute_b32 v0, v0, v6
	s_waitcnt lgkmcnt(0)
	v_add_f32_e32 v0, v6, v0
	ds_bpermute_b32 v6, v48, v0
	s_waitcnt lgkmcnt(0)
	v_add_f32_e32 v0, v0, v6
	ds_bpermute_b32 v6, v64, v0
	s_waitcnt lgkmcnt(0)
	v_add_f32_e32 v0, v0, v6
	ds_bpermute_b32 v6, v112, v0
	s_waitcnt lgkmcnt(0)
	v_add_f32_e32 v0, v0, v6
	v_fmamk_f32 v0, v0, 0x3c000000, v202
	v_mul_f32_e32 v6, 0x4b800000, v0
	v_cmp_gt_f32_e32 vcc, s58, v0
	s_nop 1
	v_cndmask_b32_e32 v0, v0, v6, vcc
	v_rsq_f32_e32 v0, v0
	s_nop 0
	v_mul_f32_e32 v1, 0x45800000, v0
	v_cndmask_b32_e32 v0, v0, v1, vcc
	v_mul_f32_e32 v1, v138, v0
	v_mul_f32_e32 v2, v137, v0
	v_mul_f32_e32 v3, v136, v0
	v_mul_f32_e32 v0, v135, v0
	v_mul_f32_e32 v1, v8, v1
	v_mul_f32_e32 v4, v4, v0
	s_waitcnt vmcnt(62)
	v_lshlrev_b32_e32 v0, 16, v134
	v_mul_f32_e32 v0, v1, v0
	v_mul_f32_e32 v3, v5, v3
	v_cvt_pk_bf16_f32 v5, v0, v193
	v_lshl_add_u64 v[0:1], v[128:129], 0, v[192:193]
	v_mul_f32_e32 v2, v9, v2
	global_store_short v[0:1], v5, off
	v_lshlrev_b32_e32 v5, 16, v133
	v_mul_f32_e32 v2, v2, v5
	v_cvt_pk_bf16_f32 v2, v2, v193
	global_store_short v[0:1], v2, off offset:64
	s_waitcnt vmcnt(62)
	v_lshlrev_b32_e32 v2, 16, v132
	v_mul_f32_e32 v2, v3, v2
	v_cvt_pk_bf16_f32 v2, v2, v193
	global_store_short v[0:1], v2, off offset:128
	v_lshlrev_b32_e32 v2, 16, v131
	v_mul_f32_e32 v2, v4, v2
	v_cvt_pk_bf16_f32 v2, v2, v193
	global_store_short v[0:1], v2, off offset:192

; #define SBAR() __builtin_amdgcn_sched_barrier(0)
; __device__ __forceinline__ int crow(int r, int hi) { return (r & 3) + 8 * (r >> 2) + 4 * hi; }
; template <int MODE, bool FAST>
; __device__ __forceinline__ int attn_item(const AttnP& a, int b, int h, int blk, char* lds) {
;     ...
;     const float lam = MODE == 0 ? a.lam[0] : 0.f;
;     if (hi == 0) { wsf[r32] = 1.f / l_reg[0]; if (MODE == 0) wsf[32 + r32] = lam / l_reg[NMAP - 1]; }
;     asm volatile("s_waitcnt lgkmcnt(0)" ::: "memory");
;     const size_t obase = ((size_t)b * SEQ + qtok) * DM + (MODE == 0 ? 0 : 1024) + h * 128 + r32;
;     float sg[4];
; #pragma unroll
;     for (int d = 0; d < 4; ++d) sg[d] = MODE == 0 ? a.subln_g[d * 32 + r32] * 0.8f : 1.f;
;     bf16_t gq[16][4];
; #pragma unroll
;     for (int r = 0; r < 16; ++r)
; #pragma unroll
;         for (int d = 0; d < 4; ++d) gq[r][d] = a.G[obase + (size_t)crow(r, hi) * DM + d * 32];
;     asm volatile("s_waitcnt vmcnt(0)" ::: "memory"); SBAR();
.LBB0_175:
	s_or_b64 exec, exec, s[30:31]
	s_ashr_i32 s27, s26, 31
	s_lshl_b64 s[4:5], s[28:29], 11
	s_lshl_b32 s28, s63, 7
	s_lshl_b64 s[26:27], s[26:27], 24
	s_add_u32 s4, s4, s26
	s_addc_u32 s5, s5, s27
	s_or_b32 s4, s4, s28
	v_readlane_b32 s64, v254, 0
	v_or_b32_e32 v2, s4, v205
	v_mov_b32_e32 v3, s5
	s_waitcnt lgkmcnt(0)
	v_lshlrev_b32_e32 v0, 2, v205
	v_readlane_b32 s74, v254, 10
	v_readlane_b32 s75, v254, 11
	v_lshlrev_b64 v[2:3], 1, v[2:3]
	s_nop 3
	global_load_dword v184, v0, s[74:75]
	global_load_dword v185, v0, s[74:75] offset:128
	global_load_dword v186, v0, s[74:75] offset:256
	global_load_dword v187, v0, s[74:75] offset:384
	v_lshl_add_u64 v[4:5], s[12:13], 0, v[2:3]
	v_lshlrev_b32_e32 v0, 14, v204
	v_lshl_add_u64 v[4:5], v[4:5], 0, v[0:1]
	v_add_co_u32_e32 v6, vcc, s1, v4
	v_readlane_b32 s65, v254, 1
	s_nop 0
	v_addc_co_u32_e32 v7, vcc, 0, v5, vcc
	v_add_co_u32_e32 v8, vcc, s47, v4
	v_readlane_b32 s66, v254, 2
	s_nop 0
	v_addc_co_u32_e32 v9, vcc, 0, v5, vcc
	v_add_co_u32_e32 v10, vcc, s50, v4
	v_readlane_b32 s67, v254, 3
	s_nop 0
	v_addc_co_u32_e32 v11, vcc, 0, v5, vcc
	global_load_ushort v192, v[4:5], off nt
	global_load_ushort v193, v[4:5], off offset:64 nt
	global_load_ushort v194, v[4:5], off offset:128 nt
	global_load_ushort v195, v[4:5], off offset:192 nt
	global_load_ushort v196, v[6:7], off offset:64 nt
	global_load_ushort v197, v[6:7], off offset:128 nt
	global_load_ushort v198, v[6:7], off offset:192 nt
	global_load_ushort v199, v[10:11], off nt
	v_add_co_u32_e32 v6, vcc, s45, v4
	v_readlane_b32 s68, v254, 4
	s_nop 0
	v_addc_co_u32_e32 v7, vcc, 0, v5, vcc
	v_add_co_u32_e32 v12, vcc, s51, v4
	v_readlane_b32 s69, v254, 5
	s_nop 0
	v_addc_co_u32_e32 v13, vcc, 0, v5, vcc
	v_add_co_u32_e32 v14, vcc, s46, v4
	v_readlane_b32 s70, v254, 6
	s_nop 0
	v_addc_co_u32_e32 v15, vcc, 0, v5, vcc
	v_add_co_u32_e32 v144, vcc, s52, v4
	v_readlane_b32 s71, v254, 7
	s_nop 0
	v_addc_co_u32_e32 v145, vcc, 0, v5, vcc
	global_load_ushort v205, v[8:9], off offset:128 nt
	global_load_ushort v206, v[8:9], off offset:192 nt
	global_load_ushort v207, v[12:13], off offset:-4096 nt
	global_load_ushort v181, v[12:13], off nt
	global_load_ushort v180, v[12:13], off offset:64 nt
	global_load_ushort v179, v[12:13], off offset:128 nt
	global_load_ushort v178, v[12:13], off offset:192 nt
	global_load_ushort v175, v[144:145], off offset:-4096 nt
	global_load_ushort v208, v[10:11], off offset:64 nt
	global_load_ushort v209, v[10:11], off offset:128 nt
	global_load_ushort v210, v[10:11], off offset:192 nt
	global_load_ushort v211, v[6:7], off offset:64 nt
	global_load_ushort v212, v[6:7], off offset:128 nt
	global_load_ushort v213, v[6:7], off offset:192 nt
	global_load_ushort v176, v[14:15], off offset:64 nt
	global_load_ushort v174, v[14:15], off offset:128 nt
	v_add_co_u32_e32 v6, vcc, s48, v4
	v_readlane_b32 s72, v254, 8
	s_nop 0
	v_addc_co_u32_e32 v7, vcc, 0, v5, vcc
	v_add_co_u32_e32 v10, vcc, s53, v4
	v_readlane_b32 s73, v254, 9
	s_nop 0
	v_addc_co_u32_e32 v11, vcc, 0, v5, vcc
	v_add_co_u32_e32 v12, vcc, s54, v4
	global_load_ushort v173, v[144:145], off nt
	global_load_ushort v172, v[144:145], off offset:64 nt
	global_load_ushort v171, v[144:145], off offset:128 nt
	global_load_ushort v170, v[144:145], off offset:192 nt
	global_load_ushort v166, v[10:11], off offset:-4096 nt
	global_load_ushort v164, v[10:11], off nt
	global_load_ushort v163, v[10:11], off offset:64 nt
	global_load_ushort v162, v[10:11], off offset:128 nt
	v_addc_co_u32_e32 v13, vcc, 0, v5, vcc
	v_add_co_u32_e32 v144, vcc, s55, v4
	v_readlane_b32 s76, v254, 12
	s_nop 0
	v_addc_co_u32_e32 v145, vcc, 0, v5, vcc
	v_add_co_u32_e32 v148, vcc, s56, v4
	v_readlane_b32 s77, v254, 13
	s_nop 0
	v_addc_co_u32_e32 v149, vcc, 0, v5, vcc
	v_add_co_u32_e32 v182, vcc, s57, v4
	v_readlane_b32 s78, v254, 14
	s_nop 0
	v_addc_co_u32_e32 v183, vcc, 0, v5, vcc
	global_load_ushort v177, v[14:15], off offset:192 nt
	global_load_ushort v169, v[6:7], off offset:64 nt
	global_load_ushort v168, v[6:7], off offset:128 nt
	global_load_ushort v167, v[6:7], off offset:192 nt
	global_load_ushort v160, v[12:13], off offset:64 nt
	global_load_ushort v159, v[12:13], off offset:128 nt
	global_load_ushort v158, v[12:13], off offset:192 nt
	global_load_ushort v150, v[148:149], off offset:64 nt
	global_load_ushort v165, v[10:11], off offset:192 nt
	global_load_ushort v161, v[144:145], off offset:-4096 nt
	global_load_ushort v157, v[144:145], off nt
	global_load_ushort v156, v[144:145], off offset:64 nt
	global_load_ushort v155, v[144:145], off offset:128 nt
	global_load_ushort v154, v[144:145], off offset:192 nt
	global_load_ushort v151, v[182:183], off offset:-4096 nt
	global_load_ushort v146, v[182:183], off nt
	v_add_co_u32_e32 v6, vcc, s58, v4
	v_readlane_b32 s79, v254, 15
	s_nop 0
	v_addc_co_u32_e32 v7, vcc, 0, v5, vcc
	v_add_co_u32_e32 v10, vcc, s59, v4
	s_nop 1
	v_addc_co_u32_e32 v11, vcc, 0, v5, vcc
	global_load_ushort v214, v[8:9], off offset:-4096 nt
	global_load_ushort v215, v[8:9], off nt
	global_load_ushort v216, v[8:9], off offset:64 nt
	global_load_ushort v153, v[148:149], off offset:128 nt
	global_load_ushort v152, v[148:149], off offset:192 nt
	global_load_ushort v15, v[6:7], off offset:64 nt
	global_load_ushort v14, v[6:7], off offset:128 nt
	global_load_ushort v13, v[6:7], off offset:192 nt
	s_nop 0
	global_load_ushort v149, v[182:183], off offset:64 nt
	global_load_ushort v148, v[182:183], off offset:128 nt
	global_load_ushort v147, v[182:183], off offset:192 nt
	global_load_ushort v144, v[10:11], off offset:-4096 nt
	global_load_ushort v7, v[10:11], off nt
	global_load_ushort v6, v[10:11], off offset:64 nt
	global_load_ushort v5, v[10:11], off offset:128 nt
	global_load_ushort v4, v[10:11], off offset:192 nt
	s_waitcnt vmcnt(0)
; __device__ __forceinline__ unsigned cvtpk(float lo, float hi) { unsigned r; asm volatile("v_cvt_pk_bf16_f32 %0, %1, %2" : "=v"(r) : "v"(lo), "v"(hi)); return r; }
; __device__ __forceinline__ float bf2f(bf16_t v) { return __uint_as_float((unsigned)v << 16); }
; __device__ __forceinline__ int crow(int r, int hi) { return (r & 3) + 8 * (r >> 2) + 4 * hi; }
; template <int MODE, bool FAST>
; __device__ __forceinline__ int attn_item(const AttnP& a, int b, int h, int blk, char* lds) {
;     ...
;     for (int r = 0; r < 16; ++r) {
;         const int cr = crow(r, hi);
;         const float ra = wsf[cr];
;         float v[4];
;         if (MODE == 0) {
;             const float rb = wsf[32 + cr];
;             float ss = 0.f;
; #pragma unroll
;             for (int d = 0; d < 4; ++d) { v[d] = o[0][d][r] * ra - o[NMAP - 1][d][r] * rb; ss += v[d] * v[d]; }
;             ss += __shfl_xor(ss, 1); ss += __shfl_xor(ss, 2); ss += __shfl_xor(ss, 4); ss += __shfl_xor(ss, 8); ss += __shfl_xor(ss, 16);
;             const float rstd = rsqrtf(ss * (1.f / 128.f) + 1e-5f);
; #pragma unroll
;             for (int d = 0; d < 4; ++d) v[d] *= rstd * sg[d];
;         } else {
; #pragma unroll
;             for (int d = 0; d < 4; ++d) v[d] = o[0][d][r] * ra;
;         }
;         const size_t ro = obase + (size_t)cr * DM;
; #pragma unroll
;         for (int d = 0; d < 4; ++d) { const float gg = bf2f(gq[r][d]); a.MIX[ro + d * 32] = (bf16_t)(cvtpk(v[d] * gg, 0.f) & 0xffffu); }
;     }
	s_waitcnt vmcnt(62)
	v_mul_f32_e32 v11, 0x3f4ccccd, v184
	v_mul_f32_e32 v10, 0x3f4ccccd, v185
	v_mul_f32_e32 v9, 0x3f4ccccd, v186
	v_mul_f32_e32 v8, 0x3f4ccccd, v187
	v_and_b32_e32 v145, 64, v203
	v_add_u32_e32 v217, 64, v145
	v_lshl_add_u32 v145, v204, 4, s2
	ds_read2_b32 v[182:183], v145 offset1:32
	v_mov_b32_e32 v185, v64
	v_mov_b32_e32 v186, v128
	v_mov_b32_e32 v187, v96
	v_mov_b32_e32 v184, v112
	s_waitcnt lgkmcnt(0)
	v_mov_b32_e32 v64, v183
	v_pk_mul_f32 v[186:187], v[186:187], v[64:65] op_sel_hi:[1,0]
	v_mov_b32_e32 v190, v80
	v_mov_b32_e32 v191, v32
	v_pk_fma_f32 v[184:185], v[184:185], v[182:183], v[186:187] op_sel_hi:[1,0,1] neg_lo:[0,0,1] neg_hi:[0,0,1]
	v_mov_b32_e32 v188, v48
	v_mov_b32_e32 v189, v16
	v_pk_mul_f32 v[190:191], v[190:191], v[64:65] op_sel_hi:[1,0]
	v_xor_b32_e32 v12, 1, v203
	v_pk_mul_f32 v[186:187], v[184:185], v[184:185]
	v_pk_fma_f32 v[182:183], v[188:189], v[182:183], v[190:191] op_sel_hi:[1,0,1] neg_lo:[0,0,1] neg_hi:[0,0,1]
	v_cmp_lt_i32_e32 vcc, v12, v217
	v_pk_mul_f32 v[188:189], v[182:183], v[182:183]
	v_add_f32_e32 v16, v186, v187
	v_cndmask_b32_e32 v12, v203, v12, vcc
	v_add_f32_e32 v16, v189, v16
	v_lshlrev_b32_e32 v12, 2, v12
	v_add_f32_e32 v16, v188, v16
	ds_bpermute_b32 v32, v12, v16
	v_xor_b32_e32 v48, 2, v203
	v_cmp_lt_i32_e32 vcc, v48, v217
	v_xor_b32_e32 v64, 4, v203
	v_lshl_add_u64 v[2:3], s[14:15], 0, v[2:3]
	v_cndmask_b32_e32 v48, v203, v48, vcc
	v_lshlrev_b32_e32 v48, 2, v48
	s_waitcnt lgkmcnt(0)
	v_add_f32_e32 v16, v16, v32
	ds_bpermute_b32 v32, v48, v16
	v_cmp_lt_i32_e32 vcc, v64, v217
	s_waitcnt vmcnt(10)
	v_lshlrev_b32_e32 v15, 16, v15
	s_waitcnt vmcnt(9)
	v_lshlrev_b32_e32 v14, 16, v14
	v_cndmask_b32_e32 v64, v203, v64, vcc
	v_lshlrev_b32_e32 v80, 2, v64
	s_waitcnt lgkmcnt(0)
	v_add_f32_e32 v16, v16, v32
	ds_bpermute_b32 v32, v80, v16
	v_xor_b32_e32 v64, 8, v203
	v_cmp_lt_i32_e32 vcc, v64, v217
	s_waitcnt vmcnt(8)
	v_lshlrev_b32_e32 v13, 16, v13
	s_waitcnt vmcnt(3)
	v_lshlrev_b32_e32 v7, 16, v7
	v_cndmask_b32_e32 v64, v203, v64, vcc
	v_lshlrev_b32_e32 v112, 2, v64
	s_waitcnt lgkmcnt(0)
	v_add_f32_e32 v16, v16, v32
	ds_bpermute_b32 v32, v112, v16
	v_xor_b32_e32 v64, 16, v203
	v_cmp_lt_i32_e32 vcc, v64, v217
	s_waitcnt lgkmcnt(0)
	v_add_f32_e32 v16, v16, v32
	v_cndmask_b32_e32 v64, v203, v64, vcc
	v_lshlrev_b32_e32 v128, 2, v64
	ds_bpermute_b32 v32, v128, v16
	s_waitcnt lgkmcnt(0)
	v_add_f32_e32 v16, v16, v32
	v_fmamk_f32 v16, v16, 0x3c000000, v202
	v_mul_f32_e32 v32, 0x4b800000, v16
	v_cmp_gt_f32_e32 vcc, s60, v16
	s_nop 1
	v_cndmask_b32_e32 v16, v16, v32, vcc
	v_rsq_f32_e32 v16, v16
	s_nop 0
	v_mul_f32_e32 v32, 0x45800000, v16
	v_cndmask_b32_e32 v16, v16, v32, vcc
	v_mul_f32_e32 v32, v11, v16
	v_mul_f32_e32 v64, v10, v16
	v_mul_f32_e32 v96, v9, v16
	v_mul_f32_e32 v16, v8, v16
	v_mul_f32_e32 v32, v184, v32
	v_mul_f32_e32 v16, v182, v16
	v_lshlrev_b32_e32 v182, 16, v192
	v_mul_f32_e32 v32, v32, v182
	v_mul_f32_e32 v96, v183, v96
	v_cvt_pk_bf16_f32 v32, v32, v1
	v_lshl_add_u64 v[182:183], v[2:3], 0, v[0:1]
	v_mul_f32_e32 v64, v185, v64
	global_store_short v[182:183], v32, off
	v_lshlrev_b32_e32 v32, 16, v193
	v_mul_f32_e32 v32, v64, v32
	v_cvt_pk_bf16_f32 v32, v32, v1
	global_store_short v[182:183], v32, off offset:64
	v_lshlrev_b32_e32 v32, 16, v194
	v_mul_f32_e32 v32, v96, v32
	v_cvt_pk_bf16_f32 v32, v32, v1
	global_store_short v[182:183], v32, off offset:128
	v_lshlrev_b32_e32 v32, 16, v195
	v_mul_f32_e32 v16, v16, v32
	v_cvt_pk_bf16_f32 v187, v16, v1
	ds_read2_b32 v[184:185], v145 offset0:1 offset1:33
	v_mov_b32_e32 v96, v129
	v_mov_b32_e32 v64, v113
	v_mov_b32_e32 v32, v81
	v_mov_b32_e32 v16, v49
	s_waitcnt lgkmcnt(0)
	v_mov_b32_e32 v186, v185
	v_pk_mul_f32 v[96:97], v[96:97], v[186:187] op_sel_hi:[1,0]
	v_pk_mul_f32 v[32:33], v[32:33], v[186:187] op_sel_hi:[1,0]
	v_pk_fma_f32 v[64:65], v[64:65], v[184:185], v[96:97] op_sel_hi:[1,0,1] neg_lo:[0,0,1] neg_hi:[0,0,1]
	v_pk_fma_f32 v[16:17], v[16:17], v[184:185], v[32:33] op_sel_hi:[1,0,1] neg_lo:[0,0,1] neg_hi:[0,0,1]
	v_pk_mul_f32 v[96:97], v[64:65], v[64:65]
	v_pk_mul_f32 v[32:33], v[16:17], v[16:17]
	v_add_f32_e32 v49, v96, v97
	v_add_f32_e32 v33, v33, v49
	v_add_f32_e32 v32, v32, v33
	ds_bpermute_b32 v33, v12, v32
	global_store_short v[182:183], v187, off offset:192
	v_mov_b32_e32 v96, v130
	v_mov_b32_e32 v97, v98
	v_mov_b32_e32 v184, v82
	s_waitcnt lgkmcnt(0)
	v_add_f32_e32 v32, v32, v33
	ds_bpermute_b32 v33, v48, v32
	v_mov_b32_e32 v185, v34
	v_mov_b32_e32 v182, v50
	v_mov_b32_e32 v183, v18
	v_mov_b32_e32 v98, v131
	s_waitcnt lgkmcnt(0)
	v_add_f32_e32 v32, v32, v33
	ds_bpermute_b32 v33, v80, v32
	s_waitcnt lgkmcnt(0)
	v_add_f32_e32 v32, v32, v33
	ds_bpermute_b32 v33, v112, v32
	s_waitcnt lgkmcnt(0)
	v_add_f32_e32 v32, v32, v33
	ds_bpermute_b32 v33, v128, v32
	s_waitcnt lgkmcnt(0)
	v_add_f32_e32 v32, v32, v33
	v_fmamk_f32 v32, v32, 0x3c000000, v202
	v_mul_f32_e32 v33, 0x4b800000, v32
	v_cmp_gt_f32_e32 vcc, s60, v32
	s_nop 1
	v_cndmask_b32_e32 v32, v32, v33, vcc
	v_rsq_f32_e32 v32, v32
	s_nop 0
	v_mul_f32_e32 v33, 0x45800000, v32
	v_cndmask_b32_e32 v32, v32, v33, vcc
	v_mul_f32_e32 v33, v11, v32
	v_mul_f32_e32 v33, v64, v33
	v_mul_f32_e32 v49, v10, v32
	v_mul_f32_e32 v64, v9, v32
	v_mul_f32_e32 v49, v65, v49
	v_mul_f32_e32 v64, v17, v64
	v_mul_f32_e32 v17, v8, v32
	v_lshlrev_b32_e32 v65, 16, v214
	v_mul_f32_e32 v32, v16, v17
	v_or_b32_e32 v16, 0x1000, v0
	v_mov_b32_e32 v17, v1
	v_mul_f32_e32 v33, v33, v65
	v_cvt_pk_bf16_f32 v33, v33, v1
	v_lshl_add_u64 v[16:17], v[2:3], 0, v[16:17]
	global_store_short v[16:17], v33, off
	v_lshlrev_b32_e32 v33, 16, v196
	v_mul_f32_e32 v33, v49, v33
	v_cvt_pk_bf16_f32 v33, v33, v1
	global_store_short v[16:17], v33, off offset:64
	v_lshlrev_b32_e32 v33, 16, v197
	v_mul_f32_e32 v33, v64, v33
	v_cvt_pk_bf16_f32 v33, v33, v1
	global_store_short v[16:17], v33, off offset:128
	v_lshlrev_b32_e32 v33, 16, v198
	v_mul_f32_e32 v32, v32, v33
	v_cvt_pk_bf16_f32 v49, v32, v1
	ds_read2_b32 v[32:33], v145 offset0:2 offset1:34
	v_mov_b32_e32 v65, v66
	v_mov_b32_e32 v64, v114
	global_store_short v[16:17], v49, off offset:192
	v_lshlrev_b32_e32 v49, 16, v215
	s_waitcnt lgkmcnt(0)
; __device__ __forceinline__ unsigned cvtpk(float lo, float hi) { unsigned r; asm volatile("v_cvt_pk_bf16_f32 %0, %1, %2" : "=v"(r) : "v"(lo), "v"(hi)); return r; }
; __device__ __forceinline__ float bf2f(bf16_t v) { return __uint_as_float((unsigned)v << 16); }
; __device__ __forceinline__ int crow(int r, int hi) { return (r & 3) + 8 * (r >> 2) + 4 * hi; }
; template <int MODE, bool FAST>
; __device__ __forceinline__ int attn_item(const AttnP& a, int b, int h, int blk, char* lds) {
;     ...
;     for (int r = 0; r < 16; ++r) {
;         const int cr = crow(r, hi);
;         const float ra = wsf[cr];
;         float v[4];
;         if (MODE == 0) {
;             const float rb = wsf[32 + cr];
;             float ss = 0.f;
; #pragma unroll
;             for (int d = 0; d < 4; ++d) { v[d] = o[0][d][r] * ra - o[NMAP - 1][d][r] * rb; ss += v[d] * v[d]; }
;             ss += __shfl_xor(ss, 1); ss += __shfl_xor(ss, 2); ss += __shfl_xor(ss, 4); ss += __shfl_xor(ss, 8); ss += __shfl_xor(ss, 16);
;             const float rstd = rsqrtf(ss * (1.f / 128.f) + 1e-5f);
; #pragma unroll
;             for (int d = 0; d < 4; ++d) v[d] *= rstd * sg[d];
;         } else {
; #pragma unroll
;             for (int d = 0; d < 4; ++d) v[d] = o[0][d][r] * ra;
;         }
;         const size_t ro = obase + (size_t)cr * DM;
; #pragma unroll
;         for (int d = 0; d < 4; ++d) { const float gg = bf2f(gq[r][d]); a.MIX[ro + d * 32] = (bf16_t)(cvtpk(v[d] * gg, 0.f) & 0xffffu); }
;     }
	v_mov_b32_e32 v66, v33
	v_pk_mul_f32 v[96:97], v[96:97], v[66:67] op_sel_hi:[1,0]
	v_pk_mul_f32 v[184:185], v[184:185], v[66:67] op_sel_hi:[1,0]
	v_pk_fma_f32 v[64:65], v[64:65], v[32:33], v[96:97] op_sel_hi:[1,0,1] neg_lo:[0,0,1] neg_hi:[0,0,1]
	v_pk_fma_f32 v[32:33], v[182:183], v[32:33], v[184:185] op_sel_hi:[1,0,1] neg_lo:[0,0,1] neg_hi:[0,0,1]
	v_pk_mul_f32 v[96:97], v[64:65], v[64:65]
	v_pk_mul_f32 v[182:183], v[32:33], v[32:33]
	v_add_f32_e32 v18, v96, v97
	v_add_f32_e32 v18, v183, v18
	v_add_f32_e32 v18, v182, v18
	ds_bpermute_b32 v34, v12, v18
	v_mov_b32_e32 v66, v115
	s_waitcnt lgkmcnt(0)
	v_add_f32_e32 v18, v18, v34
	ds_bpermute_b32 v34, v48, v18
	s_waitcnt lgkmcnt(0)
	v_add_f32_e32 v18, v18, v34
	ds_bpermute_b32 v34, v80, v18
	s_waitcnt lgkmcnt(0)
	v_add_f32_e32 v18, v18, v34
	ds_bpermute_b32 v34, v112, v18
	s_waitcnt lgkmcnt(0)
	v_add_f32_e32 v18, v18, v34
	ds_bpermute_b32 v34, v128, v18
	s_waitcnt lgkmcnt(0)
	v_add_f32_e32 v18, v18, v34
	v_fmamk_f32 v18, v18, 0x3c000000, v202
	v_mul_f32_e32 v34, 0x4b800000, v18
	v_cmp_gt_f32_e32 vcc, s60, v18
	s_nop 1
	v_cndmask_b32_e32 v18, v18, v34, vcc
	v_rsq_f32_e32 v18, v18
	s_nop 0
	v_mul_f32_e32 v16, 0x45800000, v18
	v_cndmask_b32_e32 v16, v18, v16, vcc
	v_mul_f32_e32 v17, v11, v16
	v_mul_f32_e32 v18, v64, v17
	v_mul_f32_e32 v17, v10, v16
	v_mul_f32_e32 v34, v65, v17
	v_mul_f32_e32 v17, v9, v16
	v_mul_f32_e32 v16, v8, v16
	v_mul_f32_e32 v33, v33, v17
	v_mul_f32_e32 v32, v32, v16
	v_or_b32_e32 v16, 0x2000, v0
	v_mov_b32_e32 v17, v1
	v_mul_f32_e32 v18, v18, v49
	v_cvt_pk_bf16_f32 v18, v18, v1
	v_lshl_add_u64 v[16:17], v[2:3], 0, v[16:17]
	global_store_short v[16:17], v18, off
	v_lshlrev_b32_e32 v18, 16, v216
	v_mul_f32_e32 v18, v34, v18
	v_cvt_pk_bf16_f32 v18, v18, v1
	global_store_short v[16:17], v18, off offset:64
	v_lshlrev_b32_e32 v18, 16, v205
	v_mul_f32_e32 v18, v33, v18
	v_cvt_pk_bf16_f32 v18, v18, v1
	global_store_short v[16:17], v18, off offset:128
	v_lshlrev_b32_e32 v18, 16, v206
	v_mul_f32_e32 v18, v32, v18
	v_cvt_pk_bf16_f32 v49, v18, v1
	ds_read2_b32 v[32:33], v145 offset0:3 offset1:35
	v_mov_b32_e32 v34, v83
	v_mov_b32_e32 v18, v51
	global_store_short v[16:17], v49, off offset:192
	s_waitcnt lgkmcnt(0)
	v_mov_b32_e32 v50, v33
	v_pk_mul_f32 v[64:65], v[98:99], v[50:51] op_sel_hi:[1,0]
	v_pk_mul_f32 v[34:35], v[34:35], v[50:51] op_sel_hi:[1,0]
	v_pk_fma_f32 v[64:65], v[66:67], v[32:33], v[64:65] op_sel_hi:[1,0,1] neg_lo:[0,0,1] neg_hi:[0,0,1]
	v_pk_fma_f32 v[18:19], v[18:19], v[32:33], v[34:35] op_sel_hi:[1,0,1] neg_lo:[0,0,1] neg_hi:[0,0,1]
	v_pk_mul_f32 v[66:67], v[64:65], v[64:65]
	v_pk_mul_f32 v[32:33], v[18:19], v[18:19]
	v_add_f32_e32 v34, v66, v67
	v_add_f32_e32 v33, v33, v34
	v_add_f32_e32 v32, v32, v33
	ds_bpermute_b32 v33, v12, v32
	v_lshlrev_b32_e32 v34, 16, v199
	v_mov_b32_e32 v35, v100
	v_mov_b32_e32 v66, v84
	v_mov_b32_e32 v67, v36
	s_waitcnt lgkmcnt(0)
	v_add_f32_e32 v32, v32, v33
	ds_bpermute_b32 v33, v48, v32
	v_mov_b32_e32 v100, v133
	v_mov_b32_e32 v36, v85
	s_waitcnt lgkmcnt(0)
	v_add_f32_e32 v32, v32, v33
	ds_bpermute_b32 v33, v80, v32
	s_waitcnt lgkmcnt(0)
	v_add_f32_e32 v32, v32, v33
	ds_bpermute_b32 v33, v112, v32
	s_waitcnt lgkmcnt(0)
	v_add_f32_e32 v32, v32, v33
	ds_bpermute_b32 v33, v128, v32
	s_waitcnt lgkmcnt(0)
	v_add_f32_e32 v32, v32, v33
	v_fmamk_f32 v32, v32, 0x3c000000, v202
	v_mul_f32_e32 v33, 0x4b800000, v32
	v_cmp_gt_f32_e32 vcc, s60, v32
	s_nop 1
	v_cndmask_b32_e32 v32, v32, v33, vcc
	v_rsq_f32_e32 v32, v32
	s_nop 0
	v_mul_f32_e32 v16, 0x45800000, v32
	v_cndmask_b32_e32 v16, v32, v16, vcc
	v_mul_f32_e32 v17, v11, v16
	v_mul_f32_e32 v32, v64, v17
	v_mul_f32_e32 v17, v10, v16
	v_mul_f32_e32 v33, v65, v17
	v_mul_f32_e32 v17, v9, v16
	v_mul_f32_e32 v16, v8, v16
	v_mul_f32_e32 v19, v19, v17
	v_mul_f32_e32 v18, v18, v16
	v_or_b32_e32 v16, 0x3000, v0
	v_mov_b32_e32 v17, v1
	v_mul_f32_e32 v32, v32, v34
	v_cvt_pk_bf16_f32 v32, v32, v1
	v_lshl_add_u64 v[16:17], v[2:3], 0, v[16:17]
	global_store_short v[16:17], v32, off
	v_lshlrev_b32_e32 v32, 16, v208
	v_mul_f32_e32 v32, v33, v32
	v_cvt_pk_bf16_f32 v32, v32, v1
	global_store_short v[16:17], v32, off offset:64
	v_lshlrev_b32_e32 v32, 16, v209
	v_mul_f32_e32 v19, v19, v32
	v_cvt_pk_bf16_f32 v19, v19, v1
	global_store_short v[16:17], v19, off offset:128
	v_lshlrev_b32_e32 v19, 16, v210
	v_mul_f32_e32 v18, v18, v19
	v_cvt_pk_bf16_f32 v49, v18, v1
	ds_read2_b32 v[18:19], v145 offset0:8 offset1:40
	v_mov_b32_e32 v34, v132
	v_mov_b32_e32 v32, v116
	v_mov_b32_e32 v33, v68
	v_mov_b32_e32 v64, v52
	s_waitcnt lgkmcnt(0)
	v_mov_b32_e32 v50, v19
	v_pk_mul_f32 v[34:35], v[34:35], v[50:51] op_sel_hi:[1,0]
	v_mov_b32_e32 v65, v20
	v_pk_fma_f32 v[32:33], v[32:33], v[18:19], v[34:35] op_sel_hi:[1,0,1] neg_lo:[0,0,1] neg_hi:[0,0,1]
	v_pk_mul_f32 v[50:51], v[66:67], v[50:51] op_sel_hi:[1,0]
	v_pk_mul_f32 v[34:35], v[32:33], v[32:33]
	v_pk_fma_f32 v[18:19], v[64:65], v[18:19], v[50:51] op_sel_hi:[1,0,1] neg_lo:[0,0,1] neg_hi:[0,0,1]
	v_add_f32_e32 v20, v34, v35
	v_pk_mul_f32 v[50:51], v[18:19], v[18:19]
	global_store_short v[16:17], v49, off offset:192
	v_add_f32_e32 v20, v51, v20
	v_add_f32_e32 v20, v50, v20
	ds_bpermute_b32 v34, v12, v20
	v_mov_b32_e32 v68, v117
	s_waitcnt lgkmcnt(0)
	v_add_f32_e32 v20, v20, v34
	ds_bpermute_b32 v34, v48, v20
	s_waitcnt lgkmcnt(0)
	v_add_f32_e32 v20, v20, v34
	ds_bpermute_b32 v34, v80, v20
	s_waitcnt lgkmcnt(0)
	v_add_f32_e32 v20, v20, v34
	ds_bpermute_b32 v34, v112, v20
	s_waitcnt lgkmcnt(0)
	v_add_f32_e32 v20, v20, v34
	ds_bpermute_b32 v34, v128, v20
	s_waitcnt lgkmcnt(0)
; __device__ __forceinline__ unsigned cvtpk(float lo, float hi) { unsigned r; asm volatile("v_cvt_pk_bf16_f32 %0, %1, %2" : "=v"(r) : "v"(lo), "v"(hi)); return r; }
; __device__ __forceinline__ float bf2f(bf16_t v) { return __uint_as_float((unsigned)v << 16); }
; __device__ __forceinline__ int crow(int r, int hi) { return (r & 3) + 8 * (r >> 2) + 4 * hi; }
; template <int MODE, bool FAST>
; __device__ __forceinline__ int attn_item(const AttnP& a, int b, int h, int blk, char* lds) {
;     ...
;     for (int r = 0; r < 16; ++r) {
;         const int cr = crow(r, hi);
;         const float ra = wsf[cr];
;         float v[4];
;         if (MODE == 0) {
;             const float rb = wsf[32 + cr];
;             float ss = 0.f;
; #pragma unroll
;             for (int d = 0; d < 4; ++d) { v[d] = o[0][d][r] * ra - o[NMAP - 1][d][r] * rb; ss += v[d] * v[d]; }
;             ss += __shfl_xor(ss, 1); ss += __shfl_xor(ss, 2); ss += __shfl_xor(ss, 4); ss += __shfl_xor(ss, 8); ss += __shfl_xor(ss, 16);
;             const float rstd = rsqrtf(ss * (1.f / 128.f) + 1e-5f);
; #pragma unroll
;             for (int d = 0; d < 4; ++d) v[d] *= rstd * sg[d];
;         } else {
; #pragma unroll
;             for (int d = 0; d < 4; ++d) v[d] = o[0][d][r] * ra;
;         }
;         const size_t ro = obase + (size_t)cr * DM;
; #pragma unroll
;         for (int d = 0; d < 4; ++d) { const float gg = bf2f(gq[r][d]); a.MIX[ro + d * 32] = (bf16_t)(cvtpk(v[d] * gg, 0.f) & 0xffffu); }
;     }
	v_add_f32_e32 v20, v20, v34
	v_fmamk_f32 v20, v20, 0x3c000000, v202
	v_mul_f32_e32 v34, 0x4b800000, v20
	v_cmp_gt_f32_e32 vcc, s60, v20
	s_nop 1
	v_cndmask_b32_e32 v20, v20, v34, vcc
	v_rsq_f32_e32 v20, v20
	s_nop 0
	v_mul_f32_e32 v16, 0x45800000, v20
	v_cndmask_b32_e32 v16, v20, v16, vcc
	v_mul_f32_e32 v17, v11, v16
	v_mul_f32_e32 v20, v32, v17
	v_mul_f32_e32 v17, v10, v16
	v_mul_f32_e32 v32, v33, v17
	v_mul_f32_e32 v17, v9, v16
	v_mul_f32_e32 v16, v8, v16
	v_lshlrev_b32_e32 v33, 16, v207
	v_mul_f32_e32 v19, v19, v17
	v_mul_f32_e32 v18, v18, v16
	v_or_b32_e32 v16, 0x8000, v0
	v_mov_b32_e32 v17, v1
	v_mul_f32_e32 v20, v20, v33
	v_cvt_pk_bf16_f32 v20, v20, v1
	v_lshl_add_u64 v[16:17], v[2:3], 0, v[16:17]
	global_store_short v[16:17], v20, off
	v_lshlrev_b32_e32 v20, 16, v211
	v_mul_f32_e32 v20, v32, v20
	v_cvt_pk_bf16_f32 v20, v20, v1
	global_store_short v[16:17], v20, off offset:64
	v_lshlrev_b32_e32 v20, 16, v212
	v_mul_f32_e32 v19, v19, v20
	v_cvt_pk_bf16_f32 v19, v19, v1
	global_store_short v[16:17], v19, off offset:128
	v_lshlrev_b32_e32 v19, 16, v213
	v_mul_f32_e32 v18, v18, v19
	v_cvt_pk_bf16_f32 v49, v18, v1
	ds_read2_b32 v[18:19], v145 offset0:9 offset1:41
	v_mov_b32_e32 v20, v53
	global_store_short v[16:17], v49, off offset:192
	s_waitcnt lgkmcnt(0)
	v_mov_b32_e32 v32, v19
	v_pk_mul_f32 v[34:35], v[100:101], v[32:33] op_sel_hi:[1,0]
	v_pk_mul_f32 v[32:33], v[36:37], v[32:33] op_sel_hi:[1,0]
	v_pk_fma_f32 v[34:35], v[68:69], v[18:19], v[34:35] op_sel_hi:[1,0,1] neg_lo:[0,0,1] neg_hi:[0,0,1]
	v_pk_fma_f32 v[18:19], v[20:21], v[18:19], v[32:33] op_sel_hi:[1,0,1] neg_lo:[0,0,1] neg_hi:[0,0,1]
	v_pk_mul_f32 v[50:51], v[34:35], v[34:35]
	v_pk_mul_f32 v[20:21], v[18:19], v[18:19]
	v_add_f32_e32 v32, v50, v51
	v_add_f32_e32 v21, v21, v32
	v_add_f32_e32 v20, v20, v21
	ds_bpermute_b32 v21, v12, v20
	v_lshlrev_b32_e32 v32, 16, v181
	v_mov_b32_e32 v33, v102
	v_mov_b32_e32 v50, v86
	v_mov_b32_e32 v51, v38
	s_waitcnt lgkmcnt(0)
	v_add_f32_e32 v20, v20, v21
	ds_bpermute_b32 v21, v48, v20
	v_mov_b32_e32 v36, v54
	v_mov_b32_e32 v37, v22
	v_mov_b32_e32 v102, v135
	v_mov_b32_e32 v38, v87
	s_waitcnt lgkmcnt(0)
	v_add_f32_e32 v20, v20, v21
	ds_bpermute_b32 v21, v80, v20
	s_waitcnt lgkmcnt(0)
	v_add_f32_e32 v20, v20, v21
	ds_bpermute_b32 v21, v112, v20
	s_waitcnt lgkmcnt(0)
	v_add_f32_e32 v20, v20, v21
	ds_bpermute_b32 v21, v128, v20
	s_waitcnt lgkmcnt(0)
	v_add_f32_e32 v20, v20, v21
	v_fmamk_f32 v20, v20, 0x3c000000, v202
	v_mul_f32_e32 v21, 0x4b800000, v20
	v_cmp_gt_f32_e32 vcc, s60, v20
	s_nop 1
	v_cndmask_b32_e32 v20, v20, v21, vcc
	v_rsq_f32_e32 v20, v20
	s_nop 0
	v_mul_f32_e32 v16, 0x45800000, v20
	v_cndmask_b32_e32 v16, v20, v16, vcc
	v_mul_f32_e32 v17, v11, v16
	v_mul_f32_e32 v20, v34, v17
	v_mul_f32_e32 v17, v10, v16
	v_mul_f32_e32 v21, v35, v17
	v_mul_f32_e32 v17, v9, v16
	v_mul_f32_e32 v16, v8, v16
	v_mul_f32_e32 v19, v19, v17
	v_mul_f32_e32 v18, v18, v16
	v_or_b32_e32 v16, 0x9000, v0
	v_mov_b32_e32 v17, v1
	v_mul_f32_e32 v20, v20, v32
	v_cvt_pk_bf16_f32 v20, v20, v1
	v_lshl_add_u64 v[16:17], v[2:3], 0, v[16:17]
	global_store_short v[16:17], v20, off
	v_lshlrev_b32_e32 v20, 16, v180
	v_mul_f32_e32 v20, v21, v20
	v_cvt_pk_bf16_f32 v20, v20, v1
	global_store_short v[16:17], v20, off offset:64
	v_lshlrev_b32_e32 v20, 16, v179
	v_mul_f32_e32 v19, v19, v20
	v_cvt_pk_bf16_f32 v19, v19, v1
	global_store_short v[16:17], v19, off offset:128
	v_lshlrev_b32_e32 v19, 16, v178
	v_mul_f32_e32 v18, v18, v19
	v_cvt_pk_bf16_f32 v49, v18, v1
	ds_read2_b32 v[18:19], v145 offset0:10 offset1:42
	v_mov_b32_e32 v32, v134
	v_mov_b32_e32 v20, v118
	v_mov_b32_e32 v21, v70
	global_store_short v[16:17], v49, off offset:192
	s_waitcnt lgkmcnt(0)
	v_mov_b32_e32 v34, v19
	v_pk_mul_f32 v[32:33], v[32:33], v[34:35] op_sel_hi:[1,0]
	v_pk_mul_f32 v[34:35], v[50:51], v[34:35] op_sel_hi:[1,0]
	v_pk_fma_f32 v[20:21], v[20:21], v[18:19], v[32:33] op_sel_hi:[1,0,1] neg_lo:[0,0,1] neg_hi:[0,0,1]
	v_pk_fma_f32 v[18:19], v[36:37], v[18:19], v[34:35] op_sel_hi:[1,0,1] neg_lo:[0,0,1] neg_hi:[0,0,1]
	v_pk_mul_f32 v[32:33], v[20:21], v[20:21]
	v_pk_mul_f32 v[34:35], v[18:19], v[18:19]
	v_add_f32_e32 v22, v32, v33
	v_add_f32_e32 v22, v35, v22
	v_add_f32_e32 v22, v34, v22
	ds_bpermute_b32 v32, v12, v22
	v_mov_b32_e32 v70, v119
	v_mov_b32_e32 v37, v40
	v_mov_b32_e32 v40, v89
	s_waitcnt lgkmcnt(0)
	v_add_f32_e32 v22, v22, v32
	ds_bpermute_b32 v32, v48, v22
	s_waitcnt lgkmcnt(0)
	v_add_f32_e32 v22, v22, v32
	ds_bpermute_b32 v32, v80, v22
	s_waitcnt lgkmcnt(0)
	v_add_f32_e32 v22, v22, v32
	ds_bpermute_b32 v32, v112, v22
	s_waitcnt lgkmcnt(0)
	v_add_f32_e32 v22, v22, v32
	ds_bpermute_b32 v32, v128, v22
	s_waitcnt lgkmcnt(0)
	v_add_f32_e32 v22, v22, v32
	v_fmamk_f32 v22, v22, 0x3c000000, v202
	v_mul_f32_e32 v32, 0x4b800000, v22
	v_cmp_gt_f32_e32 vcc, s60, v22
	s_nop 1
	v_cndmask_b32_e32 v22, v22, v32, vcc
	v_rsq_f32_e32 v22, v22
	s_nop 0
	v_mul_f32_e32 v16, 0x45800000, v22
	v_cndmask_b32_e32 v16, v22, v16, vcc
	v_mul_f32_e32 v17, v11, v16
	v_mul_f32_e32 v20, v20, v17
	v_mul_f32_e32 v17, v10, v16
	v_mul_f32_e32 v21, v21, v17
	v_mul_f32_e32 v17, v9, v16
	v_mul_f32_e32 v16, v8, v16
	v_lshlrev_b32_e32 v22, 16, v175
	v_mul_f32_e32 v19, v19, v17
	v_mul_f32_e32 v18, v18, v16
	v_or_b32_e32 v16, 0xa000, v0
	v_mov_b32_e32 v17, v1
	v_mul_f32_e32 v20, v20, v22
	v_cvt_pk_bf16_f32 v20, v20, v1
	v_lshl_add_u64 v[16:17], v[2:3], 0, v[16:17]
	global_store_short v[16:17], v20, off
	v_lshlrev_b32_e32 v20, 16, v176
	v_mul_f32_e32 v20, v21, v20
	v_cvt_pk_bf16_f32 v20, v20, v1
	global_store_short v[16:17], v20, off offset:64
	v_lshlrev_b32_e32 v20, 16, v174
	v_mul_f32_e32 v19, v19, v20
	v_cvt_pk_bf16_f32 v19, v19, v1
	global_store_short v[16:17], v19, off offset:128
	v_lshlrev_b32_e32 v19, 16, v177
	v_mul_f32_e32 v18, v18, v19
	v_cvt_pk_bf16_f32 v36, v18, v1
	ds_read2_b32 v[18:19], v145 offset0:11 offset1:43
	v_mov_b32_e32 v22, v55
	global_store_short v[16:17], v36, off offset:192
	v_mov_b32_e32 v36, v88
	s_waitcnt lgkmcnt(0)
; __device__ __forceinline__ unsigned cvtpk(float lo, float hi) { unsigned r; asm volatile("v_cvt_pk_bf16_f32 %0, %1, %2" : "=v"(r) : "v"(lo), "v"(hi)); return r; }
; __device__ __forceinline__ float bf2f(bf16_t v) { return __uint_as_float((unsigned)v << 16); }
; __device__ __forceinline__ int crow(int r, int hi) { return (r & 3) + 8 * (r >> 2) + 4 * hi; }
; template <int MODE, bool FAST>
; __device__ __forceinline__ int attn_item(const AttnP& a, int b, int h, int blk, char* lds) {
;     ...
;     for (int r = 0; r < 16; ++r) {
;         const int cr = crow(r, hi);
;         const float ra = wsf[cr];
;         float v[4];
;         if (MODE == 0) {
;             const float rb = wsf[32 + cr];
;             float ss = 0.f;
; #pragma unroll
;             for (int d = 0; d < 4; ++d) { v[d] = o[0][d][r] * ra - o[NMAP - 1][d][r] * rb; ss += v[d] * v[d]; }
;             ss += __shfl_xor(ss, 1); ss += __shfl_xor(ss, 2); ss += __shfl_xor(ss, 4); ss += __shfl_xor(ss, 8); ss += __shfl_xor(ss, 16);
;             const float rstd = rsqrtf(ss * (1.f / 128.f) + 1e-5f);
; #pragma unroll
;             for (int d = 0; d < 4; ++d) v[d] *= rstd * sg[d];
;         } else {
; #pragma unroll
;             for (int d = 0; d < 4; ++d) v[d] = o[0][d][r] * ra;
;         }
;         const size_t ro = obase + (size_t)cr * DM;
; #pragma unroll
;         for (int d = 0; d < 4; ++d) { const float gg = bf2f(gq[r][d]); a.MIX[ro + d * 32] = (bf16_t)(cvtpk(v[d] * gg, 0.f) & 0xffffu); }
;     }
	v_mov_b32_e32 v20, v19
	v_pk_mul_f32 v[32:33], v[102:103], v[20:21] op_sel_hi:[1,0]
	v_pk_mul_f32 v[20:21], v[38:39], v[20:21] op_sel_hi:[1,0]
	v_pk_fma_f32 v[32:33], v[70:71], v[18:19], v[32:33] op_sel_hi:[1,0,1] neg_lo:[0,0,1] neg_hi:[0,0,1]
	v_pk_fma_f32 v[18:19], v[22:23], v[18:19], v[20:21] op_sel_hi:[1,0,1] neg_lo:[0,0,1] neg_hi:[0,0,1]
	v_pk_mul_f32 v[34:35], v[32:33], v[32:33]
	v_pk_mul_f32 v[20:21], v[18:19], v[18:19]
	v_add_f32_e32 v22, v34, v35
	v_add_f32_e32 v21, v21, v22
	v_add_f32_e32 v20, v20, v21
	ds_bpermute_b32 v21, v12, v20
	v_lshlrev_b32_e32 v22, 16, v173
	v_mov_b32_e32 v23, v104
	v_mov_b32_e32 v34, v56
	v_mov_b32_e32 v35, v24
	s_waitcnt lgkmcnt(0)
	v_add_f32_e32 v20, v20, v21
	ds_bpermute_b32 v21, v48, v20
	v_mov_b32_e32 v104, v137
	v_mov_b32_e32 v24, v57
	s_waitcnt lgkmcnt(0)
	v_add_f32_e32 v20, v20, v21
	ds_bpermute_b32 v21, v80, v20
	s_waitcnt lgkmcnt(0)
	v_add_f32_e32 v20, v20, v21
	ds_bpermute_b32 v21, v112, v20
	s_waitcnt lgkmcnt(0)
	v_add_f32_e32 v20, v20, v21
	ds_bpermute_b32 v21, v128, v20
	s_waitcnt lgkmcnt(0)
	v_add_f32_e32 v20, v20, v21
	v_fmamk_f32 v20, v20, 0x3c000000, v202
	v_mul_f32_e32 v21, 0x4b800000, v20
	v_cmp_gt_f32_e32 vcc, s60, v20
	s_nop 1
	v_cndmask_b32_e32 v20, v20, v21, vcc
	v_rsq_f32_e32 v20, v20
	s_nop 0
	v_mul_f32_e32 v16, 0x45800000, v20
	v_cndmask_b32_e32 v16, v20, v16, vcc
	v_mul_f32_e32 v17, v11, v16
	v_mul_f32_e32 v20, v32, v17
	v_mul_f32_e32 v17, v10, v16
	v_mul_f32_e32 v21, v33, v17
	v_mul_f32_e32 v17, v9, v16
	v_mul_f32_e32 v16, v8, v16
	v_mul_f32_e32 v19, v19, v17
	v_mul_f32_e32 v18, v18, v16
	v_or_b32_e32 v16, 0xb000, v0
	v_mov_b32_e32 v17, v1
	v_mul_f32_e32 v20, v20, v22
	v_cvt_pk_bf16_f32 v20, v20, v1
	v_lshl_add_u64 v[16:17], v[2:3], 0, v[16:17]
	global_store_short v[16:17], v20, off
	v_lshlrev_b32_e32 v20, 16, v172
	v_mul_f32_e32 v20, v21, v20
	v_cvt_pk_bf16_f32 v20, v20, v1
	global_store_short v[16:17], v20, off offset:64
	v_lshlrev_b32_e32 v20, 16, v171
	v_mul_f32_e32 v19, v19, v20
	v_cvt_pk_bf16_f32 v19, v19, v1
	global_store_short v[16:17], v19, off offset:128
	v_lshlrev_b32_e32 v19, 16, v170
	v_mul_f32_e32 v18, v18, v19
	v_cvt_pk_bf16_f32 v38, v18, v1
	ds_read2_b32 v[18:19], v145 offset0:16 offset1:48
	v_mov_b32_e32 v22, v136
	v_mov_b32_e32 v20, v120
	v_mov_b32_e32 v21, v72
	global_store_short v[16:17], v38, off offset:192
	s_waitcnt lgkmcnt(0)
	v_mov_b32_e32 v32, v19
	v_pk_mul_f32 v[22:23], v[22:23], v[32:33] op_sel_hi:[1,0]
	v_pk_mul_f32 v[32:33], v[36:37], v[32:33] op_sel_hi:[1,0]
	v_pk_fma_f32 v[20:21], v[20:21], v[18:19], v[22:23] op_sel_hi:[1,0,1] neg_lo:[0,0,1] neg_hi:[0,0,1]
	v_pk_fma_f32 v[18:19], v[34:35], v[18:19], v[32:33] op_sel_hi:[1,0,1] neg_lo:[0,0,1] neg_hi:[0,0,1]
	v_pk_mul_f32 v[22:23], v[20:21], v[20:21]
	v_pk_mul_f32 v[32:33], v[18:19], v[18:19]
	v_add_f32_e32 v22, v22, v23
	v_add_f32_e32 v22, v33, v22
	v_add_f32_e32 v22, v32, v22
	ds_bpermute_b32 v23, v12, v22
	v_mov_b32_e32 v72, v121
	v_mov_b32_e32 v35, v42
	v_mov_b32_e32 v42, v91
	s_waitcnt lgkmcnt(0)
	v_add_f32_e32 v22, v22, v23
	ds_bpermute_b32 v23, v48, v22
	s_waitcnt lgkmcnt(0)
	v_add_f32_e32 v22, v22, v23
	ds_bpermute_b32 v23, v80, v22
	s_waitcnt lgkmcnt(0)
	v_add_f32_e32 v22, v22, v23
	ds_bpermute_b32 v23, v112, v22
	s_waitcnt lgkmcnt(0)
	v_add_f32_e32 v22, v22, v23
	ds_bpermute_b32 v23, v128, v22
	s_waitcnt lgkmcnt(0)
	v_add_f32_e32 v22, v22, v23
	v_fmamk_f32 v22, v22, 0x3c000000, v202
	v_mul_f32_e32 v23, 0x4b800000, v22
	v_cmp_gt_f32_e32 vcc, s60, v22
	s_nop 1
	v_cndmask_b32_e32 v22, v22, v23, vcc
	v_rsq_f32_e32 v22, v22
	s_nop 0
	v_mul_f32_e32 v16, 0x45800000, v22
	v_cndmask_b32_e32 v16, v22, v16, vcc
	v_mul_f32_e32 v17, v11, v16
	v_mul_f32_e32 v20, v20, v17
	v_mul_f32_e32 v17, v10, v16
	v_mul_f32_e32 v21, v21, v17
	v_mul_f32_e32 v17, v9, v16
	v_mul_f32_e32 v16, v8, v16
	v_lshlrev_b32_e32 v22, 16, v166
	v_mul_f32_e32 v19, v19, v17
	v_mul_f32_e32 v18, v18, v16
	v_or_b32_e32 v16, 0x10000, v0
	v_mov_b32_e32 v17, v1
	v_mul_f32_e32 v20, v20, v22
	v_cvt_pk_bf16_f32 v20, v20, v1
	v_lshl_add_u64 v[16:17], v[2:3], 0, v[16:17]
	global_store_short v[16:17], v20, off
	v_lshlrev_b32_e32 v20, 16, v169
	v_mul_f32_e32 v20, v21, v20
	v_cvt_pk_bf16_f32 v20, v20, v1
	global_store_short v[16:17], v20, off offset:64
	v_lshlrev_b32_e32 v20, 16, v168
	v_mul_f32_e32 v19, v19, v20
	v_cvt_pk_bf16_f32 v19, v19, v1
	global_store_short v[16:17], v19, off offset:128
	v_lshlrev_b32_e32 v19, 16, v167
	v_mul_f32_e32 v18, v18, v19
	v_cvt_pk_bf16_f32 v34, v18, v1
	ds_read2_b32 v[18:19], v145 offset0:17 offset1:49
	global_store_short v[16:17], v34, off offset:192
	v_mov_b32_e32 v34, v90
	s_waitcnt lgkmcnt(0)
	v_mov_b32_e32 v20, v19
	v_pk_mul_f32 v[22:23], v[104:105], v[20:21] op_sel_hi:[1,0]
	v_pk_mul_f32 v[20:21], v[40:41], v[20:21] op_sel_hi:[1,0]
	v_pk_fma_f32 v[22:23], v[72:73], v[18:19], v[22:23] op_sel_hi:[1,0,1] neg_lo:[0,0,1] neg_hi:[0,0,1]
	v_pk_fma_f32 v[18:19], v[24:25], v[18:19], v[20:21] op_sel_hi:[1,0,1] neg_lo:[0,0,1] neg_hi:[0,0,1]
	v_pk_mul_f32 v[32:33], v[22:23], v[22:23]
	v_pk_mul_f32 v[20:21], v[18:19], v[18:19]
	v_add_f32_e32 v24, v32, v33
	v_add_f32_e32 v21, v21, v24
	v_add_f32_e32 v20, v20, v21
	ds_bpermute_b32 v21, v12, v20
	v_mov_b32_e32 v32, v58
	v_mov_b32_e32 v33, v26
	v_mov_b32_e32 v26, v59
	s_waitcnt lgkmcnt(0)
	v_add_f32_e32 v20, v20, v21
	ds_bpermute_b32 v21, v48, v20
	s_waitcnt lgkmcnt(0)
	v_add_f32_e32 v20, v20, v21
	ds_bpermute_b32 v21, v80, v20
	s_waitcnt lgkmcnt(0)
	v_add_f32_e32 v20, v20, v21
	ds_bpermute_b32 v21, v112, v20
	s_waitcnt lgkmcnt(0)
	v_add_f32_e32 v20, v20, v21
	ds_bpermute_b32 v21, v128, v20
	s_waitcnt lgkmcnt(0)
; __device__ __forceinline__ unsigned cvtpk(float lo, float hi) { unsigned r; asm volatile("v_cvt_pk_bf16_f32 %0, %1, %2" : "=v"(r) : "v"(lo), "v"(hi)); return r; }
; __device__ __forceinline__ float bf2f(bf16_t v) { return __uint_as_float((unsigned)v << 16); }
; __device__ __forceinline__ int crow(int r, int hi) { return (r & 3) + 8 * (r >> 2) + 4 * hi; }
; template <int MODE, bool FAST>
; __device__ __forceinline__ int attn_item(const AttnP& a, int b, int h, int blk, char* lds) {
;     ...
;     for (int r = 0; r < 16; ++r) {
;         const int cr = crow(r, hi);
;         const float ra = wsf[cr];
;         float v[4];
;         if (MODE == 0) {
;             const float rb = wsf[32 + cr];
;             float ss = 0.f;
; #pragma unroll
;             for (int d = 0; d < 4; ++d) { v[d] = o[0][d][r] * ra - o[NMAP - 1][d][r] * rb; ss += v[d] * v[d]; }
;             ss += __shfl_xor(ss, 1); ss += __shfl_xor(ss, 2); ss += __shfl_xor(ss, 4); ss += __shfl_xor(ss, 8); ss += __shfl_xor(ss, 16);
;             const float rstd = rsqrtf(ss * (1.f / 128.f) + 1e-5f);
; #pragma unroll
;             for (int d = 0; d < 4; ++d) v[d] *= rstd * sg[d];
;         } else {
; #pragma unroll
;             for (int d = 0; d < 4; ++d) v[d] = o[0][d][r] * ra;
;         }
;         const size_t ro = obase + (size_t)cr * DM;
; #pragma unroll
;         for (int d = 0; d < 4; ++d) { const float gg = bf2f(gq[r][d]); a.MIX[ro + d * 32] = (bf16_t)(cvtpk(v[d] * gg, 0.f) & 0xffffu); }
;     }
	v_add_f32_e32 v20, v20, v21
	v_fmamk_f32 v20, v20, 0x3c000000, v202
	v_mul_f32_e32 v21, 0x4b800000, v20
	v_cmp_gt_f32_e32 vcc, s60, v20
	s_nop 1
	v_cndmask_b32_e32 v20, v20, v21, vcc
	v_rsq_f32_e32 v20, v20
	s_nop 0
	v_mul_f32_e32 v16, 0x45800000, v20
	v_cndmask_b32_e32 v16, v20, v16, vcc
	v_mul_f32_e32 v17, v11, v16
	v_mul_f32_e32 v20, v22, v17
	v_mul_f32_e32 v17, v10, v16
	v_mul_f32_e32 v21, v23, v17
	v_mul_f32_e32 v17, v9, v16
	v_mul_f32_e32 v16, v8, v16
	v_lshlrev_b32_e32 v22, 16, v164
	v_mul_f32_e32 v19, v19, v17
	v_mul_f32_e32 v18, v18, v16
	v_or_b32_e32 v16, 0x11000, v0
	v_mov_b32_e32 v17, v1
	v_mul_f32_e32 v20, v20, v22
	v_cvt_pk_bf16_f32 v20, v20, v1
	v_lshl_add_u64 v[16:17], v[2:3], 0, v[16:17]
	global_store_short v[16:17], v20, off
	v_lshlrev_b32_e32 v20, 16, v163
	v_mul_f32_e32 v20, v21, v20
	v_cvt_pk_bf16_f32 v20, v20, v1
	global_store_short v[16:17], v20, off offset:64
	v_lshlrev_b32_e32 v20, 16, v162
	v_mul_f32_e32 v19, v19, v20
	v_cvt_pk_bf16_f32 v19, v19, v1
	global_store_short v[16:17], v19, off offset:128
	v_lshlrev_b32_e32 v19, 16, v165
	v_mul_f32_e32 v18, v18, v19
	v_cvt_pk_bf16_f32 v36, v18, v1
	ds_read2_b32 v[18:19], v145 offset0:18 offset1:50
	v_mov_b32_e32 v22, v138
	v_mov_b32_e32 v23, v106
	v_mov_b32_e32 v20, v122
	v_mov_b32_e32 v21, v74
	s_waitcnt lgkmcnt(0)
	v_mov_b32_e32 v24, v19
	v_pk_mul_f32 v[22:23], v[22:23], v[24:25] op_sel_hi:[1,0]
	v_pk_mul_f32 v[24:25], v[34:35], v[24:25] op_sel_hi:[1,0]
	v_pk_fma_f32 v[20:21], v[20:21], v[18:19], v[22:23] op_sel_hi:[1,0,1] neg_lo:[0,0,1] neg_hi:[0,0,1]
	v_pk_fma_f32 v[18:19], v[32:33], v[18:19], v[24:25] op_sel_hi:[1,0,1] neg_lo:[0,0,1] neg_hi:[0,0,1]
	v_pk_mul_f32 v[22:23], v[20:21], v[20:21]
	v_pk_mul_f32 v[24:25], v[18:19], v[18:19]
	v_add_f32_e32 v22, v22, v23
	v_add_f32_e32 v22, v25, v22
	v_add_f32_e32 v22, v24, v22
	ds_bpermute_b32 v23, v12, v22
	global_store_short v[16:17], v36, off offset:192
	v_mov_b32_e32 v106, v139
	v_mov_b32_e32 v74, v123
	v_mov_b32_e32 v33, v44
	s_waitcnt lgkmcnt(0)
	v_add_f32_e32 v22, v22, v23
	ds_bpermute_b32 v23, v48, v22
	v_mov_b32_e32 v44, v93
	s_waitcnt lgkmcnt(0)
	v_add_f32_e32 v22, v22, v23
	ds_bpermute_b32 v23, v80, v22
	s_waitcnt lgkmcnt(0)
	v_add_f32_e32 v22, v22, v23
	ds_bpermute_b32 v23, v112, v22
	s_waitcnt lgkmcnt(0)
	v_add_f32_e32 v22, v22, v23
	ds_bpermute_b32 v23, v128, v22
	s_waitcnt lgkmcnt(0)
	v_add_f32_e32 v22, v22, v23
	v_fmamk_f32 v22, v22, 0x3c000000, v202
	v_mul_f32_e32 v23, 0x4b800000, v22
	v_cmp_gt_f32_e32 vcc, s60, v22
	s_nop 1
	v_cndmask_b32_e32 v22, v22, v23, vcc
	v_rsq_f32_e32 v22, v22
	s_nop 0
	v_mul_f32_e32 v16, 0x45800000, v22
	v_cndmask_b32_e32 v16, v22, v16, vcc
	v_mul_f32_e32 v17, v11, v16
	v_mul_f32_e32 v20, v20, v17
	v_mul_f32_e32 v17, v10, v16
	v_mul_f32_e32 v21, v21, v17
	v_mul_f32_e32 v17, v9, v16
	v_mul_f32_e32 v16, v8, v16
	v_lshlrev_b32_e32 v22, 16, v161
	v_mul_f32_e32 v19, v19, v17
	v_mul_f32_e32 v18, v18, v16
	v_or_b32_e32 v16, 0x12000, v0
	v_mov_b32_e32 v17, v1
	v_mul_f32_e32 v20, v20, v22
	v_cvt_pk_bf16_f32 v20, v20, v1
	v_lshl_add_u64 v[16:17], v[2:3], 0, v[16:17]
	global_store_short v[16:17], v20, off
	v_lshlrev_b32_e32 v20, 16, v160
	v_mul_f32_e32 v20, v21, v20
	v_cvt_pk_bf16_f32 v20, v20, v1
	global_store_short v[16:17], v20, off offset:64
	v_lshlrev_b32_e32 v20, 16, v159
	v_mul_f32_e32 v19, v19, v20
	v_cvt_pk_bf16_f32 v19, v19, v1
	global_store_short v[16:17], v19, off offset:128
	v_lshlrev_b32_e32 v19, 16, v158
	v_mul_f32_e32 v18, v18, v19
	v_cvt_pk_bf16_f32 v32, v18, v1
	ds_read2_b32 v[18:19], v145 offset0:19 offset1:51
	global_store_short v[16:17], v32, off offset:192
	v_mov_b32_e32 v32, v92
	s_waitcnt lgkmcnt(0)
	v_mov_b32_e32 v20, v19
	v_pk_mul_f32 v[22:23], v[106:107], v[20:21] op_sel_hi:[1,0]
	v_pk_mul_f32 v[20:21], v[42:43], v[20:21] op_sel_hi:[1,0]
	v_pk_fma_f32 v[22:23], v[74:75], v[18:19], v[22:23] op_sel_hi:[1,0,1] neg_lo:[0,0,1] neg_hi:[0,0,1]
	v_pk_fma_f32 v[18:19], v[26:27], v[18:19], v[20:21] op_sel_hi:[1,0,1] neg_lo:[0,0,1] neg_hi:[0,0,1]
	v_pk_mul_f32 v[24:25], v[22:23], v[22:23]
	v_pk_mul_f32 v[20:21], v[18:19], v[18:19]
	v_add_f32_e32 v24, v24, v25
	v_add_f32_e32 v21, v21, v24
	v_add_f32_e32 v20, v20, v21
	ds_bpermute_b32 v21, v12, v20
	v_mov_b32_e32 v26, v60
	v_mov_b32_e32 v27, v28
	v_mov_b32_e32 v28, v61
	s_waitcnt lgkmcnt(0)
	v_add_f32_e32 v20, v20, v21
	ds_bpermute_b32 v21, v48, v20
	s_waitcnt lgkmcnt(0)
	v_add_f32_e32 v20, v20, v21
	ds_bpermute_b32 v21, v80, v20
	s_waitcnt lgkmcnt(0)
	v_add_f32_e32 v20, v20, v21
	ds_bpermute_b32 v21, v112, v20
	s_waitcnt lgkmcnt(0)
	v_add_f32_e32 v20, v20, v21
	ds_bpermute_b32 v21, v128, v20
	s_waitcnt lgkmcnt(0)
	v_add_f32_e32 v20, v20, v21
	v_fmamk_f32 v20, v20, 0x3c000000, v202
	v_mul_f32_e32 v21, 0x4b800000, v20
	v_cmp_gt_f32_e32 vcc, s60, v20
	s_nop 1
	v_cndmask_b32_e32 v20, v20, v21, vcc
	v_rsq_f32_e32 v20, v20
	s_nop 0
	v_mul_f32_e32 v16, 0x45800000, v20
	v_cndmask_b32_e32 v16, v20, v16, vcc
	v_mul_f32_e32 v17, v11, v16
	v_mul_f32_e32 v20, v22, v17
	v_mul_f32_e32 v17, v10, v16
	v_mul_f32_e32 v21, v23, v17
	v_mul_f32_e32 v17, v9, v16
	v_mul_f32_e32 v16, v8, v16
	v_lshlrev_b32_e32 v22, 16, v157
	v_mul_f32_e32 v19, v19, v17
	v_mul_f32_e32 v18, v18, v16
	v_or_b32_e32 v16, 0x13000, v0
	v_mov_b32_e32 v17, v1
	v_mul_f32_e32 v20, v20, v22
	v_cvt_pk_bf16_f32 v20, v20, v1
	v_lshl_add_u64 v[16:17], v[2:3], 0, v[16:17]
	global_store_short v[16:17], v20, off
	v_lshlrev_b32_e32 v20, 16, v156
	v_mul_f32_e32 v20, v21, v20
	v_cvt_pk_bf16_f32 v20, v20, v1
	global_store_short v[16:17], v20, off offset:64
	v_lshlrev_b32_e32 v20, 16, v155
	v_mul_f32_e32 v19, v19, v20
	v_cvt_pk_bf16_f32 v19, v19, v1
	global_store_short v[16:17], v19, off offset:128
	v_lshlrev_b32_e32 v19, 16, v154
	v_mul_f32_e32 v18, v18, v19
	v_cvt_pk_bf16_f32 v34, v18, v1
	ds_read2_b32 v[18:19], v145 offset0:24 offset1:56
	v_mov_b32_e32 v22, v140
	v_mov_b32_e32 v23, v108
	v_mov_b32_e32 v20, v124
	v_mov_b32_e32 v21, v76
	s_waitcnt lgkmcnt(0)
; __device__ __forceinline__ unsigned cvtpk(float lo, float hi) { unsigned r; asm volatile("v_cvt_pk_bf16_f32 %0, %1, %2" : "=v"(r) : "v"(lo), "v"(hi)); return r; }
; __device__ __forceinline__ float bf2f(bf16_t v) { return __uint_as_float((unsigned)v << 16); }
; __device__ __forceinline__ int crow(int r, int hi) { return (r & 3) + 8 * (r >> 2) + 4 * hi; }
; template <int MODE, bool FAST>
; __device__ __forceinline__ int attn_item(const AttnP& a, int b, int h, int blk, char* lds) {
;     ...
;     for (int r = 0; r < 16; ++r) {
;         const int cr = crow(r, hi);
;         const float ra = wsf[cr];
;         float v[4];
;         if (MODE == 0) {
;             const float rb = wsf[32 + cr];
;             float ss = 0.f;
; #pragma unroll
;             for (int d = 0; d < 4; ++d) { v[d] = o[0][d][r] * ra - o[NMAP - 1][d][r] * rb; ss += v[d] * v[d]; }
;             ss += __shfl_xor(ss, 1); ss += __shfl_xor(ss, 2); ss += __shfl_xor(ss, 4); ss += __shfl_xor(ss, 8); ss += __shfl_xor(ss, 16);
;             const float rstd = rsqrtf(ss * (1.f / 128.f) + 1e-5f);
; #pragma unroll
;             for (int d = 0; d < 4; ++d) v[d] *= rstd * sg[d];
;         } else {
; #pragma unroll
;             for (int d = 0; d < 4; ++d) v[d] = o[0][d][r] * ra;
;         }
;         const size_t ro = obase + (size_t)cr * DM;
; #pragma unroll
;         for (int d = 0; d < 4; ++d) { const float gg = bf2f(gq[r][d]); a.MIX[ro + d * 32] = (bf16_t)(cvtpk(v[d] * gg, 0.f) & 0xffffu); }
;     }
	v_mov_b32_e32 v24, v19
	v_pk_mul_f32 v[22:23], v[22:23], v[24:25] op_sel_hi:[1,0]
	v_pk_mul_f32 v[24:25], v[32:33], v[24:25] op_sel_hi:[1,0]
	v_pk_fma_f32 v[20:21], v[20:21], v[18:19], v[22:23] op_sel_hi:[1,0,1] neg_lo:[0,0,1] neg_hi:[0,0,1]
	v_pk_fma_f32 v[18:19], v[26:27], v[18:19], v[24:25] op_sel_hi:[1,0,1] neg_lo:[0,0,1] neg_hi:[0,0,1]
	v_pk_mul_f32 v[22:23], v[20:21], v[20:21]
	v_pk_mul_f32 v[24:25], v[18:19], v[18:19]
	v_add_f32_e32 v22, v22, v23
	v_add_f32_e32 v22, v25, v22
	v_add_f32_e32 v22, v24, v22
	ds_bpermute_b32 v23, v12, v22
	global_store_short v[16:17], v34, off offset:192
	v_mov_b32_e32 v108, v141
	v_mov_b32_e32 v76, v125
	v_mov_b32_e32 v27, v30
	s_waitcnt lgkmcnt(0)
	v_add_f32_e32 v22, v22, v23
	ds_bpermute_b32 v23, v48, v22
	v_mov_b32_e32 v30, v63
	s_waitcnt lgkmcnt(0)
	v_add_f32_e32 v22, v22, v23
	ds_bpermute_b32 v23, v80, v22
	s_waitcnt lgkmcnt(0)
	v_add_f32_e32 v22, v22, v23
	ds_bpermute_b32 v23, v112, v22
	s_waitcnt lgkmcnt(0)
	v_add_f32_e32 v22, v22, v23
	ds_bpermute_b32 v23, v128, v22
	s_waitcnt lgkmcnt(0)
	v_add_f32_e32 v22, v22, v23
	v_fmamk_f32 v22, v22, 0x3c000000, v202
	v_mul_f32_e32 v23, 0x4b800000, v22
	v_cmp_gt_f32_e32 vcc, s60, v22
	s_nop 1
	v_cndmask_b32_e32 v22, v22, v23, vcc
	v_rsq_f32_e32 v22, v22
	s_nop 0
	v_mul_f32_e32 v16, 0x45800000, v22
	v_cndmask_b32_e32 v16, v22, v16, vcc
	v_mul_f32_e32 v17, v11, v16
	v_mul_f32_e32 v20, v20, v17
	v_mul_f32_e32 v17, v10, v16
	v_mul_f32_e32 v21, v21, v17
	v_mul_f32_e32 v17, v9, v16
	v_mul_f32_e32 v16, v8, v16
	v_lshlrev_b32_e32 v22, 16, v151
	v_mul_f32_e32 v19, v19, v17
	v_mul_f32_e32 v18, v18, v16
	v_or_b32_e32 v16, 0x18000, v0
	v_mov_b32_e32 v17, v1
	v_mul_f32_e32 v20, v20, v22
	v_cvt_pk_bf16_f32 v20, v20, v1
	v_lshl_add_u64 v[16:17], v[2:3], 0, v[16:17]
	global_store_short v[16:17], v20, off
	v_lshlrev_b32_e32 v20, 16, v150
	v_mul_f32_e32 v20, v21, v20
	v_cvt_pk_bf16_f32 v20, v20, v1
	global_store_short v[16:17], v20, off offset:64
	v_lshlrev_b32_e32 v20, 16, v153
	v_mul_f32_e32 v19, v19, v20
	v_cvt_pk_bf16_f32 v19, v19, v1
	global_store_short v[16:17], v19, off offset:128
	v_lshlrev_b32_e32 v19, 16, v152
	v_mul_f32_e32 v18, v18, v19
	v_cvt_pk_bf16_f32 v26, v18, v1
	ds_read2_b32 v[18:19], v145 offset0:25 offset1:57
	global_store_short v[16:17], v26, off offset:192
	v_mov_b32_e32 v26, v62
	s_waitcnt lgkmcnt(0)
	v_mov_b32_e32 v20, v19
	v_pk_mul_f32 v[22:23], v[108:109], v[20:21] op_sel_hi:[1,0]
	v_pk_mul_f32 v[20:21], v[44:45], v[20:21] op_sel_hi:[1,0]
	v_pk_fma_f32 v[22:23], v[76:77], v[18:19], v[22:23] op_sel_hi:[1,0,1] neg_lo:[0,0,1] neg_hi:[0,0,1]
	v_pk_fma_f32 v[18:19], v[28:29], v[18:19], v[20:21] op_sel_hi:[1,0,1] neg_lo:[0,0,1] neg_hi:[0,0,1]
	v_pk_mul_f32 v[24:25], v[22:23], v[22:23]
	v_pk_mul_f32 v[20:21], v[18:19], v[18:19]
	v_add_f32_e32 v24, v24, v25
	v_add_f32_e32 v21, v21, v24
	v_add_f32_e32 v20, v20, v21
	ds_bpermute_b32 v21, v12, v20
	v_mov_b32_e32 v28, v94
	v_mov_b32_e32 v29, v46
	v_mov_b32_e32 v46, v95
	s_waitcnt lgkmcnt(0)
	v_add_f32_e32 v20, v20, v21
	ds_bpermute_b32 v21, v48, v20
	s_waitcnt lgkmcnt(0)
	v_add_f32_e32 v20, v20, v21
	ds_bpermute_b32 v21, v80, v20
	s_waitcnt lgkmcnt(0)
	v_add_f32_e32 v20, v20, v21
	ds_bpermute_b32 v21, v112, v20
	s_waitcnt lgkmcnt(0)
	v_add_f32_e32 v20, v20, v21
	ds_bpermute_b32 v21, v128, v20
	s_waitcnt lgkmcnt(0)
	v_add_f32_e32 v20, v20, v21
	v_fmamk_f32 v20, v20, 0x3c000000, v202
	v_mul_f32_e32 v21, 0x4b800000, v20
	v_cmp_gt_f32_e32 vcc, s60, v20
	s_nop 1
	v_cndmask_b32_e32 v20, v20, v21, vcc
	v_rsq_f32_e32 v20, v20
	s_nop 0
	v_mul_f32_e32 v16, 0x45800000, v20
	v_cndmask_b32_e32 v16, v20, v16, vcc
	v_mul_f32_e32 v17, v11, v16
	v_mul_f32_e32 v20, v22, v17
	v_mul_f32_e32 v17, v10, v16
	v_mul_f32_e32 v21, v23, v17
	v_mul_f32_e32 v17, v9, v16
	v_mul_f32_e32 v16, v8, v16
	v_lshlrev_b32_e32 v22, 16, v146
	v_mul_f32_e32 v19, v19, v17
	v_mul_f32_e32 v18, v18, v16
	v_or_b32_e32 v16, 0x19000, v0
	v_mov_b32_e32 v17, v1
	v_mul_f32_e32 v20, v20, v22
	v_cvt_pk_bf16_f32 v20, v20, v1
	v_lshl_add_u64 v[16:17], v[2:3], 0, v[16:17]
	global_store_short v[16:17], v20, off
	v_lshlrev_b32_e32 v20, 16, v149
	v_mul_f32_e32 v20, v21, v20
	v_cvt_pk_bf16_f32 v20, v20, v1
	global_store_short v[16:17], v20, off offset:64
	v_lshlrev_b32_e32 v20, 16, v148
	v_mul_f32_e32 v19, v19, v20
	v_cvt_pk_bf16_f32 v19, v19, v1
	global_store_short v[16:17], v19, off offset:128
	v_lshlrev_b32_e32 v19, 16, v147
	v_mul_f32_e32 v18, v18, v19
	v_cvt_pk_bf16_f32 v32, v18, v1
	ds_read2_b32 v[18:19], v145 offset0:26 offset1:58
	v_mov_b32_e32 v22, v142
	v_mov_b32_e32 v23, v110
	v_mov_b32_e32 v20, v126
	v_mov_b32_e32 v21, v78
	s_waitcnt lgkmcnt(0)
; __device__ __forceinline__ unsigned cvtpk(float lo, float hi) { unsigned r; asm volatile("v_cvt_pk_bf16_f32 %0, %1, %2" : "=v"(r) : "v"(lo), "v"(hi)); return r; }
; __device__ __forceinline__ float bf2f(bf16_t v) { return __uint_as_float((unsigned)v << 16); }
; __device__ __forceinline__ int crow(int r, int hi) { return (r & 3) + 8 * (r >> 2) + 4 * hi; }
; template <int MODE, bool FAST>
; __device__ __forceinline__ int attn_item(const AttnP& a, int b, int h, int blk, char* lds) {
;     ...
;     for (int r = 0; r < 16; ++r) {
;         const int cr = crow(r, hi);
;         const float ra = wsf[cr];
;         float v[4];
;         if (MODE == 0) {
;             const float rb = wsf[32 + cr];
;             float ss = 0.f;
; #pragma unroll
;             for (int d = 0; d < 4; ++d) { v[d] = o[0][d][r] * ra - o[NMAP - 1][d][r] * rb; ss += v[d] * v[d]; }
;             ss += __shfl_xor(ss, 1); ss += __shfl_xor(ss, 2); ss += __shfl_xor(ss, 4); ss += __shfl_xor(ss, 8); ss += __shfl_xor(ss, 16);
;             const float rstd = rsqrtf(ss * (1.f / 128.f) + 1e-5f);
; #pragma unroll
;             for (int d = 0; d < 4; ++d) v[d] *= rstd * sg[d];
;         } else {
; #pragma unroll
;             for (int d = 0; d < 4; ++d) v[d] = o[0][d][r] * ra;
;         }
;         const size_t ro = obase + (size_t)cr * DM;
; #pragma unroll
;         for (int d = 0; d < 4; ++d) { const float gg = bf2f(gq[r][d]); a.MIX[ro + d * 32] = (bf16_t)(cvtpk(v[d] * gg, 0.f) & 0xffffu); }
;     }
	v_mov_b32_e32 v24, v19
	v_pk_mul_f32 v[22:23], v[22:23], v[24:25] op_sel_hi:[1,0]
	v_pk_mul_f32 v[24:25], v[28:29], v[24:25] op_sel_hi:[1,0]
	v_pk_fma_f32 v[20:21], v[20:21], v[18:19], v[22:23] op_sel_hi:[1,0,1] neg_lo:[0,0,1] neg_hi:[0,0,1]
	v_pk_fma_f32 v[18:19], v[26:27], v[18:19], v[24:25] op_sel_hi:[1,0,1] neg_lo:[0,0,1] neg_hi:[0,0,1]
	v_pk_mul_f32 v[22:23], v[20:21], v[20:21]
	v_pk_mul_f32 v[24:25], v[18:19], v[18:19]
	v_add_f32_e32 v22, v22, v23
	v_add_f32_e32 v22, v25, v22
	v_add_f32_e32 v22, v24, v22
	ds_bpermute_b32 v23, v12, v22
	global_store_short v[16:17], v32, off offset:192
	v_mov_b32_e32 v110, v143
	v_mov_b32_e32 v78, v127
	s_waitcnt lgkmcnt(0)
	v_add_f32_e32 v22, v22, v23
	ds_bpermute_b32 v23, v48, v22
	s_waitcnt lgkmcnt(0)
	v_add_f32_e32 v22, v22, v23
	ds_bpermute_b32 v23, v80, v22
	s_waitcnt lgkmcnt(0)
	v_add_f32_e32 v22, v22, v23
	ds_bpermute_b32 v23, v112, v22
	s_waitcnt lgkmcnt(0)
	v_add_f32_e32 v22, v22, v23
	ds_bpermute_b32 v23, v128, v22
	s_waitcnt lgkmcnt(0)
	v_add_f32_e32 v22, v22, v23
	v_fmamk_f32 v22, v22, 0x3c000000, v202
	v_mul_f32_e32 v23, 0x4b800000, v22
	v_cmp_gt_f32_e32 vcc, s60, v22
	s_nop 1
	v_cndmask_b32_e32 v22, v22, v23, vcc
	v_rsq_f32_e32 v22, v22
	s_nop 0
	v_mul_f32_e32 v16, 0x45800000, v22
	v_cndmask_b32_e32 v16, v22, v16, vcc
	v_mul_f32_e32 v17, v11, v16
	v_mul_f32_e32 v20, v20, v17
	v_mul_f32_e32 v17, v10, v16
	v_mul_f32_e32 v21, v21, v17
	v_mul_f32_e32 v17, v9, v16
	v_mul_f32_e32 v16, v8, v16
	v_mul_f32_e32 v19, v19, v17
	v_mul_f32_e32 v18, v18, v16
	v_or_b32_e32 v16, 0x1a000, v0
	v_mov_b32_e32 v17, v1
	v_lshlrev_b32_e32 v22, 16, v144
	v_mul_f32_e32 v20, v20, v22
	v_lshl_add_u64 v[16:17], v[2:3], 0, v[16:17]
	v_mul_f32_e32 v15, v21, v15
	v_mul_f32_e32 v14, v19, v14
	v_cvt_pk_bf16_f32 v20, v20, v1
	global_store_short v[16:17], v20, off
	v_cvt_pk_bf16_f32 v15, v15, v1
	global_store_short v[16:17], v15, off offset:64
	v_cvt_pk_bf16_f32 v14, v14, v1
	v_mul_f32_e32 v13, v18, v13
	global_store_short v[16:17], v14, off offset:128
	v_cvt_pk_bf16_f32 v13, v13, v1
	ds_read2_b32 v[14:15], v145 offset0:27 offset1:59
	global_store_short v[16:17], v13, off offset:192
	v_or_b32_e32 v0, 0x1b000, v0
	v_lshl_add_u64 v[2:3], v[2:3], 0, v[0:1]
	s_waitcnt vmcnt(62)
	v_lshlrev_b32_e32 v0, 16, v6
	s_waitcnt lgkmcnt(0)
	v_mov_b32_e32 v18, v15
	v_pk_mul_f32 v[20:21], v[110:111], v[18:19] op_sel_hi:[1,0]
	v_pk_mul_f32 v[18:19], v[46:47], v[18:19] op_sel_hi:[1,0]
	v_pk_fma_f32 v[20:21], v[78:79], v[14:15], v[20:21] op_sel_hi:[1,0,1] neg_lo:[0,0,1] neg_hi:[0,0,1]
	v_pk_fma_f32 v[14:15], v[30:31], v[14:15], v[18:19] op_sel_hi:[1,0,1] neg_lo:[0,0,1] neg_hi:[0,0,1]
	v_pk_mul_f32 v[22:23], v[20:21], v[20:21]
	v_pk_mul_f32 v[18:19], v[14:15], v[14:15]
	v_add_f32_e32 v22, v22, v23
	v_add_f32_e32 v19, v19, v22
	v_add_f32_e32 v18, v18, v19
	ds_bpermute_b32 v12, v12, v18
	s_waitcnt lgkmcnt(0)
	v_add_f32_e32 v12, v18, v12
	ds_bpermute_b32 v18, v48, v12
	s_waitcnt lgkmcnt(0)
	v_add_f32_e32 v12, v12, v18
	ds_bpermute_b32 v18, v80, v12
	s_waitcnt lgkmcnt(0)
	v_add_f32_e32 v12, v12, v18
	ds_bpermute_b32 v18, v112, v12
	s_waitcnt lgkmcnt(0)
	v_add_f32_e32 v12, v12, v18
	ds_bpermute_b32 v18, v128, v12
	s_waitcnt lgkmcnt(0)
	v_add_f32_e32 v12, v12, v18
	v_fmamk_f32 v12, v12, 0x3c000000, v202
	v_mul_f32_e32 v18, 0x4b800000, v12
	v_cmp_gt_f32_e32 vcc, s60, v12
	s_nop 1
	v_cndmask_b32_e32 v12, v12, v18, vcc
	v_rsq_f32_e32 v12, v12
	s_nop 0
	v_mul_f32_e32 v13, 0x45800000, v12
	v_cndmask_b32_e32 v12, v12, v13, vcc
	v_mul_f32_e32 v11, v11, v12
	v_mul_f32_e32 v10, v10, v12
	v_mul_f32_e32 v11, v20, v11
	v_mul_f32_e32 v10, v21, v10
	v_mul_f32_e32 v7, v11, v7
	v_mul_f32_e32 v0, v10, v0
	v_mul_f32_e32 v9, v9, v12
	v_cvt_pk_bf16_f32 v7, v7, v1
	global_store_short v[2:3], v7, off
	v_cvt_pk_bf16_f32 v0, v0, v1
	v_mul_f32_e32 v9, v15, v9
	global_store_short v[2:3], v0, off offset:64
	s_waitcnt vmcnt(62)
	v_lshlrev_b32_e32 v0, 16, v5
	v_mul_f32_e32 v0, v9, v0
	v_mul_f32_e32 v8, v8, v12
	v_cvt_pk_bf16_f32 v0, v0, v1
	v_mul_f32_e32 v8, v14, v8
	global_store_short v[2:3], v0, off offset:128
	v_lshlrev_b32_e32 v0, 16, v4
	v_mul_f32_e32 v0, v8, v0
	v_cvt_pk_bf16_f32 v0, v0, v1
	global_store_short v[2:3], v0, off offset:192

; __device__ __forceinline__ unsigned cvtpk(float lo, float hi) { unsigned r; asm volatile("v_cvt_pk_bf16_f32 %0, %1, %2" : "=v"(r) : "v"(lo), "v"(hi)); return r; }
; __device__ __forceinline__ float bf2f(bf16_t v) { return __uint_as_float((unsigned)v << 16); }
; #define SBAR() __builtin_amdgcn_sched_barrier(0)
; __device__ __forceinline__ int crow(int r, int hi) { return (r & 3) + 8 * (r >> 2) + 4 * hi; }
; template <int MODE, bool FAST>
; __device__ __forceinline__ int attn_item(const AttnP& a, int b, int h, int blk, char* lds) {
;     ...
;     const float lam = MODE == 0 ? a.lam[0] : 0.f;
;     if (hi == 0) { wsf[r32] = 1.f / l_reg[0]; if (MODE == 0) wsf[32 + r32] = lam / l_reg[NMAP - 1]; }
;     asm volatile("s_waitcnt lgkmcnt(0)" ::: "memory");
;     const size_t obase = ((size_t)b * SEQ + qtok) * DM + (MODE == 0 ? 0 : 1024) + h * 128 + r32;
;     float sg[4];
; #pragma unroll
;     for (int d = 0; d < 4; ++d) sg[d] = MODE == 0 ? a.subln_g[d * 32 + r32] * 0.8f : 1.f;
;     bf16_t gq[16][4];
; #pragma unroll
;     for (int r = 0; r < 16; ++r)
; #pragma unroll
;         for (int d = 0; d < 4; ++d) gq[r][d] = a.G[obase + (size_t)crow(r, hi) * DM + d * 32];
;     asm volatile("s_waitcnt vmcnt(0)" ::: "memory"); SBAR();
; #pragma unroll
;     for (int r = 0; r < 16; ++r) {
;         const int cr = crow(r, hi);
;         const float ra = wsf[cr];
;         float v[4];
;         if (MODE == 0) {
;             const float rb = wsf[32 + cr];
;             float ss = 0.f;
; #pragma unroll
;             for (int d = 0; d < 4; ++d) { v[d] = o[0][d][r] * ra - o[NMAP - 1][d][r] * rb; ss += v[d] * v[d]; }
;             ss += __shfl_xor(ss, 1); ss += __shfl_xor(ss, 2); ss += __shfl_xor(ss, 4); ss += __shfl_xor(ss, 8); ss += __shfl_xor(ss, 16);
;             const float rstd = rsqrtf(ss * (1.f / 128.f) + 1e-5f);
; #pragma unroll
;             for (int d = 0; d < 4; ++d) v[d] *= rstd * sg[d];
;         } else {
; #pragma unroll
;             for (int d = 0; d < 4; ++d) v[d] = o[0][d][r] * ra;
;         }
;         const size_t ro = obase + (size_t)cr * DM;
; #pragma unroll
;         for (int d = 0; d < 4; ++d) { const float gg = bf2f(gq[r][d]); a.MIX[ro + d * 32] = (bf16_t)(cvtpk(v[d] * gg, 0.f) & 0xffffu); }
.LBB0_194:
	s_or_b64 exec, exec, s[4:5]
	s_ashr_i32 s15, s14, 31
	s_lshl_b64 s[4:5], s[14:15], 24
	s_lshl_b64 s[14:15], s[16:17], 11
	s_add_u32 s4, s14, s4
	s_addc_u32 s5, s15, s5
	s_lshl_b32 s0, s0, 7
	s_or_b32 s0, s4, s0
	v_or_b32_e32 v2, s0, v182
	v_mov_b32_e32 v3, s5
	v_lshlrev_b64 v[2:3], 1, v[2:3]
	v_lshlrev_b32_e32 v0, 14, v181
	v_lshl_add_u64 v[6:7], s[88:89], 0, v[0:1]
	v_or_b32_e32 v2, 0x800, v2
	v_lshl_add_u64 v[6:7], v[6:7], 0, v[2:3]
	v_add_co_u32_e32 v8, vcc, s2, v6
	s_waitcnt lgkmcnt(0)
	s_nop 1
	v_addc_co_u32_e32 v9, vcc, 0, v7, vcc
	v_add_co_u32_e32 v10, vcc, s31, v6
	s_nop 1
	v_addc_co_u32_e32 v11, vcc, 0, v7, vcc
	v_add_co_u32_e32 v12, vcc, s38, v6
	s_nop 1
	v_addc_co_u32_e32 v13, vcc, 0, v7, vcc
	global_load_ushort v5, v[6:7], off nt
	global_load_ushort v88, v[6:7], off offset:64 nt
	global_load_ushort v89, v[6:7], off offset:128 nt
	global_load_ushort v90, v[6:7], off offset:192 nt
	global_load_ushort v91, v[8:9], off offset:64 nt
	global_load_ushort v92, v[8:9], off offset:128 nt
	global_load_ushort v93, v[8:9], off offset:192 nt
	global_load_ushort v94, v[12:13], off nt
	v_add_co_u32_e32 v8, vcc, s29, v6
	s_nop 1
	v_addc_co_u32_e32 v9, vcc, 0, v7, vcc
	v_add_co_u32_e32 v14, vcc, s39, v6
	s_nop 1
	v_addc_co_u32_e32 v15, vcc, 0, v7, vcc
	v_add_co_u32_e32 v80, vcc, s30, v6
	s_nop 1
	v_addc_co_u32_e32 v81, vcc, 0, v7, vcc
	v_add_co_u32_e32 v82, vcc, s40, v6
	s_nop 1
	v_addc_co_u32_e32 v83, vcc, 0, v7, vcc
	global_load_ushort v95, v[10:11], off offset:128 nt
	global_load_ushort v96, v[10:11], off offset:192 nt
	global_load_ushort v97, v[14:15], off offset:-4096 nt
	global_load_ushort v98, v[14:15], off nt
	global_load_ushort v99, v[14:15], off offset:64 nt
	global_load_ushort v100, v[14:15], off offset:128 nt
	global_load_ushort v101, v[14:15], off offset:192 nt
	global_load_ushort v102, v[82:83], off offset:-4096 nt
	global_load_ushort v103, v[12:13], off offset:64 nt
	global_load_ushort v104, v[12:13], off offset:128 nt
	global_load_ushort v105, v[12:13], off offset:192 nt
	global_load_ushort v106, v[8:9], off offset:64 nt
	global_load_ushort v107, v[8:9], off offset:128 nt
	global_load_ushort v108, v[8:9], off offset:192 nt
	global_load_ushort v109, v[80:81], off offset:64 nt
	global_load_ushort v110, v[80:81], off offset:128 nt
	v_add_co_u32_e32 v8, vcc, s37, v6
	s_nop 1
	v_addc_co_u32_e32 v9, vcc, 0, v7, vcc
	v_add_co_u32_e32 v12, vcc, s41, v6
	s_nop 1
	v_addc_co_u32_e32 v13, vcc, 0, v7, vcc
	v_add_co_u32_e32 v14, vcc, s42, v6
	global_load_ushort v111, v[82:83], off nt
	global_load_ushort v112, v[82:83], off offset:64 nt
	global_load_ushort v113, v[82:83], off offset:128 nt
	global_load_ushort v114, v[82:83], off offset:192 nt
	global_load_ushort v115, v[12:13], off offset:-4096 nt
	global_load_ushort v116, v[12:13], off nt
	global_load_ushort v117, v[12:13], off offset:64 nt
	global_load_ushort v118, v[12:13], off offset:128 nt
	v_addc_co_u32_e32 v15, vcc, 0, v7, vcc
	v_add_co_u32_e32 v82, vcc, s43, v6
	s_nop 1
	v_addc_co_u32_e32 v83, vcc, 0, v7, vcc
	v_add_co_u32_e32 v84, vcc, s44, v6
	s_nop 1
	v_addc_co_u32_e32 v85, vcc, 0, v7, vcc
	v_add_co_u32_e32 v86, vcc, s45, v6
	s_nop 1
	v_addc_co_u32_e32 v87, vcc, 0, v7, vcc
	global_load_ushort v80, v[80:81], off offset:192 nt
	s_nop 0
	global_load_ushort v81, v[8:9], off offset:64 nt
	global_load_ushort v119, v[8:9], off offset:128 nt
	global_load_ushort v120, v[8:9], off offset:192 nt
	global_load_ushort v121, v[14:15], off offset:64 nt
	global_load_ushort v122, v[14:15], off offset:128 nt
	s_nop 0
	global_load_ushort v14, v[14:15], off offset:192 nt
	s_nop 0
	global_load_ushort v15, v[84:85], off offset:64 nt
	s_nop 0
	global_load_ushort v12, v[12:13], off offset:192 nt
	s_nop 0
	global_load_ushort v13, v[82:83], off offset:-4096 nt
	global_load_ushort v123, v[82:83], off nt
	global_load_ushort v124, v[82:83], off offset:64 nt
	global_load_ushort v125, v[82:83], off offset:128 nt
	s_nop 0
	global_load_ushort v82, v[82:83], off offset:192 nt
	s_nop 0
	global_load_ushort v83, v[86:87], off offset:-4096 nt
	global_load_ushort v126, v[86:87], off nt
	v_add_co_u32_e32 v8, vcc, s46, v6
	s_nop 1
	v_addc_co_u32_e32 v9, vcc, 0, v7, vcc
	v_add_co_u32_e32 v6, vcc, s47, v6
	s_nop 1
	v_addc_co_u32_e32 v7, vcc, 0, v7, vcc
	global_load_ushort v127, v[10:11], off offset:-4096 nt
	global_load_ushort v128, v[10:11], off nt
	s_nop 0
	global_load_ushort v10, v[10:11], off offset:64 nt
	s_nop 0
	global_load_ushort v11, v[84:85], off offset:128 nt
	s_nop 0
	global_load_ushort v84, v[84:85], off offset:192 nt
	s_nop 0
	global_load_ushort v85, v[8:9], off offset:64 nt
	global_load_ushort v129, v[8:9], off offset:128 nt
	s_nop 0
	global_load_ushort v8, v[8:9], off offset:192 nt
	s_nop 0
	global_load_ushort v9, v[86:87], off offset:64 nt
	global_load_ushort v130, v[86:87], off offset:128 nt
	s_nop 0
	global_load_ushort v86, v[86:87], off offset:192 nt
	s_nop 0
	global_load_ushort v87, v[6:7], off offset:-4096 nt
	global_load_ushort v131, v[6:7], off nt
	global_load_ushort v132, v[6:7], off offset:64 nt
	global_load_ushort v133, v[6:7], off offset:128 nt
	global_load_ushort v134, v[6:7], off offset:192 nt
	s_waitcnt vmcnt(0)
	v_lshl_add_u32 v135, v180, 2, s1
	ds_read_b32 v6, v135
	s_waitcnt vmcnt(62)
	v_lshlrev_b32_e32 v5, 16, v5
	s_waitcnt lgkmcnt(0)
	v_mul_f32_e32 v7, v16, v6
	v_mul_f32_e32 v16, v32, v6
	v_mul_f32_e32 v32, v48, v6
	v_mul_f32_e32 v48, v64, v6
	v_mul_f32_e32 v5, v7, v5
	v_lshl_add_u64 v[6:7], s[80:81], 0, v[0:1]
	v_lshlrev_b32_e32 v0, 16, v88
	v_lshl_add_u64 v[6:7], v[6:7], 0, v[2:3]
	v_mul_f32_e32 v0, v16, v0
	v_cvt_pk_bf16_f32 v5, v5, v1
	global_store_short v[6:7], v5, off
	v_cvt_pk_bf16_f32 v0, v0, v1
	global_store_short v[6:7], v0, off offset:64
	s_waitcnt vmcnt(62)
; __device__ __forceinline__ unsigned cvtpk(float lo, float hi) { unsigned r; asm volatile("v_cvt_pk_bf16_f32 %0, %1, %2" : "=v"(r) : "v"(lo), "v"(hi)); return r; }
; __device__ __forceinline__ float bf2f(bf16_t v) { return __uint_as_float((unsigned)v << 16); }
; __device__ __forceinline__ int crow(int r, int hi) { return (r & 3) + 8 * (r >> 2) + 4 * hi; }
; template <int MODE, bool FAST>
; __device__ __forceinline__ int attn_item(const AttnP& a, int b, int h, int blk, char* lds) {
;     ...
;     for (int r = 0; r < 16; ++r) {
;         const int cr = crow(r, hi);
;         const float ra = wsf[cr];
;         float v[4];
;         if (MODE == 0) {
;             const float rb = wsf[32 + cr];
;             float ss = 0.f;
; #pragma unroll
;             for (int d = 0; d < 4; ++d) { v[d] = o[0][d][r] * ra - o[NMAP - 1][d][r] * rb; ss += v[d] * v[d]; }
;             ss += __shfl_xor(ss, 1); ss += __shfl_xor(ss, 2); ss += __shfl_xor(ss, 4); ss += __shfl_xor(ss, 8); ss += __shfl_xor(ss, 16);
;             const float rstd = rsqrtf(ss * (1.f / 128.f) + 1e-5f);
; #pragma unroll
;             for (int d = 0; d < 4; ++d) v[d] *= rstd * sg[d];
;         } else {
; #pragma unroll
;             for (int d = 0; d < 4; ++d) v[d] = o[0][d][r] * ra;
;         }
;         const size_t ro = obase + (size_t)cr * DM;
; #pragma unroll
;         for (int d = 0; d < 4; ++d) { const float gg = bf2f(gq[r][d]); a.MIX[ro + d * 32] = (bf16_t)(cvtpk(v[d] * gg, 0.f) & 0xffffu); }
;     }
	v_lshlrev_b32_e32 v0, 16, v89
	v_mul_f32_e32 v0, v32, v0
	v_cvt_pk_bf16_f32 v0, v0, v1
	global_store_short v[6:7], v0, off offset:128
	v_lshlrev_b32_e32 v0, 16, v90
	v_mul_f32_e32 v0, v48, v0
	v_cvt_pk_bf16_f32 v0, v0, v1
	ds_read_b32 v5, v135 offset:4
	global_store_short v[6:7], v0, off offset:192
	s_waitcnt vmcnt(19)
	v_lshlrev_b32_e32 v7, 16, v127
	v_lshlrev_b32_e32 v0, 12, v179
	s_waitcnt lgkmcnt(0)
	v_mul_f32_e32 v6, v17, v5
	v_mul_f32_e32 v6, v6, v7
	v_mul_f32_e32 v16, v33, v5
	v_cvt_pk_bf16_f32 v32, v6, v1
	v_lshl_add_u64 v[6:7], s[80:81], 0, v[0:1]
	v_lshlrev_b32_e32 v0, 16, v91
	v_lshl_add_u64 v[6:7], v[6:7], 0, v[2:3]
	v_mul_f32_e32 v0, v16, v0
	global_store_short v[6:7], v32, off
	v_cvt_pk_bf16_f32 v0, v0, v1
	v_mul_f32_e32 v17, v49, v5
	global_store_short v[6:7], v0, off offset:64
	v_lshlrev_b32_e32 v0, 16, v92
	v_mul_f32_e32 v0, v17, v0
	v_cvt_pk_bf16_f32 v0, v0, v1
	v_mul_f32_e32 v5, v65, v5
	global_store_short v[6:7], v0, off offset:128
	v_lshlrev_b32_e32 v0, 16, v93
	v_mul_f32_e32 v0, v5, v0
	v_cvt_pk_bf16_f32 v0, v0, v1
	ds_read_b32 v5, v135 offset:8
	global_store_short v[6:7], v0, off offset:192
	s_waitcnt vmcnt(22)
	v_lshlrev_b32_e32 v7, 16, v128
	v_lshlrev_b32_e32 v0, 12, v178
	s_waitcnt lgkmcnt(0)
	v_mul_f32_e32 v6, v18, v5
	v_mul_f32_e32 v6, v6, v7
	v_mul_f32_e32 v16, v34, v5
	v_cvt_pk_bf16_f32 v18, v6, v1
	v_lshl_add_u64 v[6:7], s[80:81], 0, v[0:1]
	s_waitcnt vmcnt(21)
	v_lshlrev_b32_e32 v0, 16, v10
	v_lshl_add_u64 v[6:7], v[6:7], 0, v[2:3]
	v_mul_f32_e32 v0, v16, v0
	global_store_short v[6:7], v18, off
	v_cvt_pk_bf16_f32 v0, v0, v1
	v_mul_f32_e32 v17, v50, v5
	global_store_short v[6:7], v0, off offset:64
	v_lshlrev_b32_e32 v0, 16, v95
	v_mul_f32_e32 v0, v17, v0
	v_cvt_pk_bf16_f32 v0, v0, v1
	v_mul_f32_e32 v5, v66, v5
	global_store_short v[6:7], v0, off offset:128
	v_lshlrev_b32_e32 v0, 16, v96
	v_mul_f32_e32 v0, v5, v0
	v_cvt_pk_bf16_f32 v0, v0, v1
	ds_read_b32 v5, v135 offset:12
	global_store_short v[6:7], v0, off offset:192
	v_lshlrev_b32_e32 v7, 16, v94
	v_lshlrev_b32_e32 v0, 12, v177
	s_waitcnt lgkmcnt(0)
	v_mul_f32_e32 v6, v19, v5
	v_mul_f32_e32 v6, v6, v7
	v_mul_f32_e32 v10, v35, v5
	v_cvt_pk_bf16_f32 v17, v6, v1
	v_lshl_add_u64 v[6:7], s[80:81], 0, v[0:1]
	v_lshlrev_b32_e32 v0, 16, v103
	v_lshl_add_u64 v[6:7], v[6:7], 0, v[2:3]
	v_mul_f32_e32 v0, v10, v0
	global_store_short v[6:7], v17, off
	v_cvt_pk_bf16_f32 v0, v0, v1
	v_mul_f32_e32 v16, v51, v5
	global_store_short v[6:7], v0, off offset:64
	v_lshlrev_b32_e32 v0, 16, v104
	v_mul_f32_e32 v0, v16, v0
	v_cvt_pk_bf16_f32 v0, v0, v1
	v_mul_f32_e32 v5, v67, v5
	global_store_short v[6:7], v0, off offset:128
	v_lshlrev_b32_e32 v0, 16, v105
	v_mul_f32_e32 v0, v5, v0
	v_cvt_pk_bf16_f32 v0, v0, v1
	ds_read_b32 v5, v135 offset:32
	global_store_short v[6:7], v0, off offset:192
	v_lshlrev_b32_e32 v7, 16, v97
	v_lshlrev_b32_e32 v0, 12, v176
	s_waitcnt lgkmcnt(0)
	v_mul_f32_e32 v6, v20, v5
	v_mul_f32_e32 v6, v6, v7
	v_mul_f32_e32 v10, v36, v5
	v_cvt_pk_bf16_f32 v17, v6, v1
	v_lshl_add_u64 v[6:7], s[80:81], 0, v[0:1]
	v_lshlrev_b32_e32 v0, 16, v106
	v_lshl_add_u64 v[6:7], v[6:7], 0, v[2:3]
	v_mul_f32_e32 v0, v10, v0
	global_store_short v[6:7], v17, off
	v_cvt_pk_bf16_f32 v0, v0, v1
	v_mul_f32_e32 v16, v52, v5
	global_store_short v[6:7], v0, off offset:64
	v_lshlrev_b32_e32 v0, 16, v107
	v_mul_f32_e32 v0, v16, v0
	v_cvt_pk_bf16_f32 v0, v0, v1
	v_mul_f32_e32 v5, v68, v5
	global_store_short v[6:7], v0, off offset:128
	v_lshlrev_b32_e32 v0, 16, v108
	v_mul_f32_e32 v0, v5, v0
	v_cvt_pk_bf16_f32 v0, v0, v1
	ds_read_b32 v5, v135 offset:36
	global_store_short v[6:7], v0, off offset:192
	v_lshlrev_b32_e32 v7, 16, v98
	v_lshlrev_b32_e32 v0, 12, v175
	s_waitcnt lgkmcnt(0)
	v_mul_f32_e32 v6, v21, v5
	v_mul_f32_e32 v6, v6, v7
	v_mul_f32_e32 v10, v37, v5
	v_cvt_pk_bf16_f32 v17, v6, v1
	v_lshl_add_u64 v[6:7], s[80:81], 0, v[0:1]
	v_lshlrev_b32_e32 v0, 16, v99
	v_lshl_add_u64 v[6:7], v[6:7], 0, v[2:3]
	v_mul_f32_e32 v0, v10, v0
	global_store_short v[6:7], v17, off
	v_cvt_pk_bf16_f32 v0, v0, v1
	v_mul_f32_e32 v16, v53, v5
	global_store_short v[6:7], v0, off offset:64
	v_lshlrev_b32_e32 v0, 16, v100
	v_mul_f32_e32 v0, v16, v0
	v_cvt_pk_bf16_f32 v0, v0, v1
	v_mul_f32_e32 v5, v69, v5
	global_store_short v[6:7], v0, off offset:128
	v_lshlrev_b32_e32 v0, 16, v101
	v_mul_f32_e32 v0, v5, v0
	v_cvt_pk_bf16_f32 v0, v0, v1
	ds_read_b32 v5, v135 offset:40
	global_store_short v[6:7], v0, off offset:192
	v_lshlrev_b32_e32 v7, 16, v102
	v_lshlrev_b32_e32 v0, 12, v174
	s_waitcnt lgkmcnt(0)
	v_mul_f32_e32 v6, v22, v5
	v_mul_f32_e32 v6, v6, v7
	v_mul_f32_e32 v10, v38, v5
	v_cvt_pk_bf16_f32 v17, v6, v1
	v_lshl_add_u64 v[6:7], s[80:81], 0, v[0:1]
	v_lshlrev_b32_e32 v0, 16, v109
	v_lshl_add_u64 v[6:7], v[6:7], 0, v[2:3]
	v_mul_f32_e32 v0, v10, v0
	global_store_short v[6:7], v17, off
	v_cvt_pk_bf16_f32 v0, v0, v1
	v_mul_f32_e32 v16, v54, v5
	global_store_short v[6:7], v0, off offset:64
	v_lshlrev_b32_e32 v0, 16, v110
	v_mul_f32_e32 v0, v16, v0
	v_cvt_pk_bf16_f32 v0, v0, v1
	v_mul_f32_e32 v5, v70, v5
	global_store_short v[6:7], v0, off offset:128
	v_lshlrev_b32_e32 v0, 16, v80
	v_mul_f32_e32 v0, v5, v0
	v_cvt_pk_bf16_f32 v0, v0, v1
	ds_read_b32 v5, v135 offset:44
	global_store_short v[6:7], v0, off offset:192
	v_lshlrev_b32_e32 v7, 16, v111
	v_lshlrev_b32_e32 v0, 12, v173
	s_waitcnt lgkmcnt(0)
; __device__ __forceinline__ unsigned cvtpk(float lo, float hi) { unsigned r; asm volatile("v_cvt_pk_bf16_f32 %0, %1, %2" : "=v"(r) : "v"(lo), "v"(hi)); return r; }
; __device__ __forceinline__ float bf2f(bf16_t v) { return __uint_as_float((unsigned)v << 16); }
; __device__ __forceinline__ int crow(int r, int hi) { return (r & 3) + 8 * (r >> 2) + 4 * hi; }
; template <int MODE, bool FAST>
; __device__ __forceinline__ int attn_item(const AttnP& a, int b, int h, int blk, char* lds) {
;     ...
;     for (int r = 0; r < 16; ++r) {
;         const int cr = crow(r, hi);
;         const float ra = wsf[cr];
;         float v[4];
;         if (MODE == 0) {
;             const float rb = wsf[32 + cr];
;             float ss = 0.f;
; #pragma unroll
;             for (int d = 0; d < 4; ++d) { v[d] = o[0][d][r] * ra - o[NMAP - 1][d][r] * rb; ss += v[d] * v[d]; }
;             ss += __shfl_xor(ss, 1); ss += __shfl_xor(ss, 2); ss += __shfl_xor(ss, 4); ss += __shfl_xor(ss, 8); ss += __shfl_xor(ss, 16);
;             const float rstd = rsqrtf(ss * (1.f / 128.f) + 1e-5f);
; #pragma unroll
;             for (int d = 0; d < 4; ++d) v[d] *= rstd * sg[d];
;         } else {
; #pragma unroll
;             for (int d = 0; d < 4; ++d) v[d] = o[0][d][r] * ra;
;         }
;         const size_t ro = obase + (size_t)cr * DM;
; #pragma unroll
;         for (int d = 0; d < 4; ++d) { const float gg = bf2f(gq[r][d]); a.MIX[ro + d * 32] = (bf16_t)(cvtpk(v[d] * gg, 0.f) & 0xffffu); }
;     }
	v_mul_f32_e32 v6, v23, v5
	v_mul_f32_e32 v6, v6, v7
	v_mul_f32_e32 v10, v39, v5
	v_cvt_pk_bf16_f32 v17, v6, v1
	v_lshl_add_u64 v[6:7], s[80:81], 0, v[0:1]
	v_lshlrev_b32_e32 v0, 16, v112
	v_lshl_add_u64 v[6:7], v[6:7], 0, v[2:3]
	v_mul_f32_e32 v0, v10, v0
	global_store_short v[6:7], v17, off
	v_cvt_pk_bf16_f32 v0, v0, v1
	v_mul_f32_e32 v16, v55, v5
	global_store_short v[6:7], v0, off offset:64
	v_lshlrev_b32_e32 v0, 16, v113
	v_mul_f32_e32 v0, v16, v0
	v_cvt_pk_bf16_f32 v0, v0, v1
	v_mul_f32_e32 v5, v71, v5
	global_store_short v[6:7], v0, off offset:128
	v_lshlrev_b32_e32 v0, 16, v114
	v_mul_f32_e32 v0, v5, v0
	v_cvt_pk_bf16_f32 v0, v0, v1
	ds_read_b32 v5, v135 offset:64
	global_store_short v[6:7], v0, off offset:192
	v_lshlrev_b32_e32 v7, 16, v115
	v_lshlrev_b32_e32 v0, 12, v172
	s_waitcnt lgkmcnt(0)
	v_mul_f32_e32 v6, v24, v5
	v_mul_f32_e32 v6, v6, v7
	v_mul_f32_e32 v10, v40, v5
	v_cvt_pk_bf16_f32 v17, v6, v1
	v_lshl_add_u64 v[6:7], s[80:81], 0, v[0:1]
	v_lshlrev_b32_e32 v0, 16, v81
	v_lshl_add_u64 v[6:7], v[6:7], 0, v[2:3]
	v_mul_f32_e32 v0, v10, v0
	global_store_short v[6:7], v17, off
	v_cvt_pk_bf16_f32 v0, v0, v1
	v_mul_f32_e32 v16, v56, v5
	global_store_short v[6:7], v0, off offset:64
	v_lshlrev_b32_e32 v0, 16, v119
	v_mul_f32_e32 v0, v16, v0
	v_cvt_pk_bf16_f32 v0, v0, v1
	v_mul_f32_e32 v5, v72, v5
	global_store_short v[6:7], v0, off offset:128
	v_lshlrev_b32_e32 v0, 16, v120
	v_mul_f32_e32 v0, v5, v0
	v_cvt_pk_bf16_f32 v0, v0, v1
	ds_read_b32 v5, v135 offset:68
	global_store_short v[6:7], v0, off offset:192
	v_lshlrev_b32_e32 v7, 16, v116
	v_lshlrev_b32_e32 v0, 12, v171
	s_waitcnt lgkmcnt(0)
	v_mul_f32_e32 v6, v25, v5
	v_mul_f32_e32 v6, v6, v7
	v_mul_f32_e32 v10, v41, v5
	v_cvt_pk_bf16_f32 v17, v6, v1
	v_lshl_add_u64 v[6:7], s[80:81], 0, v[0:1]
	v_lshlrev_b32_e32 v0, 16, v117
	v_lshl_add_u64 v[6:7], v[6:7], 0, v[2:3]
	v_mul_f32_e32 v0, v10, v0
	global_store_short v[6:7], v17, off
	v_cvt_pk_bf16_f32 v0, v0, v1
	v_mul_f32_e32 v16, v57, v5
	global_store_short v[6:7], v0, off offset:64
	v_lshlrev_b32_e32 v0, 16, v118
	v_mul_f32_e32 v0, v16, v0
	v_cvt_pk_bf16_f32 v0, v0, v1
	v_mul_f32_e32 v5, v73, v5
	global_store_short v[6:7], v0, off offset:128
	v_lshlrev_b32_e32 v0, 16, v12
	v_mul_f32_e32 v0, v5, v0
	v_cvt_pk_bf16_f32 v0, v0, v1
	ds_read_b32 v5, v135 offset:72
	global_store_short v[6:7], v0, off offset:192
	v_lshlrev_b32_e32 v7, 16, v13
	v_lshlrev_b32_e32 v0, 12, v170
	s_waitcnt lgkmcnt(0)
	v_mul_f32_e32 v6, v26, v5
	v_mul_f32_e32 v6, v6, v7
	v_mul_f32_e32 v10, v42, v5
	v_cvt_pk_bf16_f32 v13, v6, v1
	v_lshl_add_u64 v[6:7], s[80:81], 0, v[0:1]
	v_lshlrev_b32_e32 v0, 16, v121
	v_lshl_add_u64 v[6:7], v[6:7], 0, v[2:3]
	v_mul_f32_e32 v0, v10, v0
	global_store_short v[6:7], v13, off
	v_cvt_pk_bf16_f32 v0, v0, v1
	v_mul_f32_e32 v12, v58, v5
	global_store_short v[6:7], v0, off offset:64
	v_lshlrev_b32_e32 v0, 16, v122
	v_mul_f32_e32 v0, v12, v0
	v_cvt_pk_bf16_f32 v0, v0, v1
	v_mul_f32_e32 v5, v74, v5
	global_store_short v[6:7], v0, off offset:128
	v_lshlrev_b32_e32 v0, 16, v14
	v_mul_f32_e32 v0, v5, v0
	v_cvt_pk_bf16_f32 v0, v0, v1
	ds_read_b32 v5, v135 offset:76
	global_store_short v[6:7], v0, off offset:192
	v_lshlrev_b32_e32 v7, 16, v123
	v_lshlrev_b32_e32 v0, 12, v169
	s_waitcnt lgkmcnt(0)
	v_mul_f32_e32 v6, v27, v5
	v_mul_f32_e32 v6, v6, v7
	v_mul_f32_e32 v10, v43, v5
	v_cvt_pk_bf16_f32 v13, v6, v1
	v_lshl_add_u64 v[6:7], s[80:81], 0, v[0:1]
	v_lshlrev_b32_e32 v0, 16, v124
	v_lshl_add_u64 v[6:7], v[6:7], 0, v[2:3]
	v_mul_f32_e32 v0, v10, v0
	global_store_short v[6:7], v13, off
	v_cvt_pk_bf16_f32 v0, v0, v1
	v_mul_f32_e32 v12, v59, v5
	global_store_short v[6:7], v0, off offset:64
	v_lshlrev_b32_e32 v0, 16, v125
	v_mul_f32_e32 v0, v12, v0
	v_cvt_pk_bf16_f32 v0, v0, v1
	v_mul_f32_e32 v5, v75, v5
	global_store_short v[6:7], v0, off offset:128
	v_lshlrev_b32_e32 v0, 16, v82
	v_mul_f32_e32 v0, v5, v0
	v_cvt_pk_bf16_f32 v0, v0, v1
	ds_read_b32 v5, v135 offset:96
	global_store_short v[6:7], v0, off offset:192
	v_lshlrev_b32_e32 v7, 16, v83
	v_lshlrev_b32_e32 v0, 12, v168
	s_waitcnt lgkmcnt(0)
; __device__ __forceinline__ unsigned cvtpk(float lo, float hi) { unsigned r; asm volatile("v_cvt_pk_bf16_f32 %0, %1, %2" : "=v"(r) : "v"(lo), "v"(hi)); return r; }
; __device__ __forceinline__ float bf2f(bf16_t v) { return __uint_as_float((unsigned)v << 16); }
; __device__ __forceinline__ int crow(int r, int hi) { return (r & 3) + 8 * (r >> 2) + 4 * hi; }
; template <int MODE, bool FAST>
; __device__ __forceinline__ int attn_item(const AttnP& a, int b, int h, int blk, char* lds) {
;     ...
;     for (int r = 0; r < 16; ++r) {
;         const int cr = crow(r, hi);
;         const float ra = wsf[cr];
;         float v[4];
;         if (MODE == 0) {
;             const float rb = wsf[32 + cr];
;             float ss = 0.f;
; #pragma unroll
;             for (int d = 0; d < 4; ++d) { v[d] = o[0][d][r] * ra - o[NMAP - 1][d][r] * rb; ss += v[d] * v[d]; }
;             ss += __shfl_xor(ss, 1); ss += __shfl_xor(ss, 2); ss += __shfl_xor(ss, 4); ss += __shfl_xor(ss, 8); ss += __shfl_xor(ss, 16);
;             const float rstd = rsqrtf(ss * (1.f / 128.f) + 1e-5f);
; #pragma unroll
;             for (int d = 0; d < 4; ++d) v[d] *= rstd * sg[d];
;         } else {
; #pragma unroll
;             for (int d = 0; d < 4; ++d) v[d] = o[0][d][r] * ra;
;         }
;         const size_t ro = obase + (size_t)cr * DM;
; #pragma unroll
;         for (int d = 0; d < 4; ++d) { const float gg = bf2f(gq[r][d]); a.MIX[ro + d * 32] = (bf16_t)(cvtpk(v[d] * gg, 0.f) & 0xffffu); }
;     }
	v_mul_f32_e32 v6, v28, v5
	v_mul_f32_e32 v6, v6, v7
	v_mul_f32_e32 v10, v44, v5
	v_cvt_pk_bf16_f32 v13, v6, v1
	v_lshl_add_u64 v[6:7], s[80:81], 0, v[0:1]
	v_lshlrev_b32_e32 v0, 16, v15
	v_lshl_add_u64 v[6:7], v[6:7], 0, v[2:3]
	v_mul_f32_e32 v0, v10, v0
	global_store_short v[6:7], v13, off
	v_cvt_pk_bf16_f32 v0, v0, v1
	v_mul_f32_e32 v12, v60, v5
	global_store_short v[6:7], v0, off offset:64
	s_waitcnt vmcnt(62)
	v_lshlrev_b32_e32 v0, 16, v11
	v_mul_f32_e32 v0, v12, v0
	v_cvt_pk_bf16_f32 v0, v0, v1
	v_mul_f32_e32 v5, v76, v5
	global_store_short v[6:7], v0, off offset:128
	s_waitcnt vmcnt(62)
	v_lshlrev_b32_e32 v0, 16, v84
	v_mul_f32_e32 v0, v5, v0
	v_cvt_pk_bf16_f32 v0, v0, v1
	ds_read_b32 v5, v135 offset:100
	global_store_short v[6:7], v0, off offset:192
	v_lshlrev_b32_e32 v7, 16, v126
	v_lshlrev_b32_e32 v0, 12, v167
	s_waitcnt lgkmcnt(0)
	v_mul_f32_e32 v6, v29, v5
	v_mul_f32_e32 v6, v6, v7
	v_mul_f32_e32 v10, v45, v5
	v_cvt_pk_bf16_f32 v12, v6, v1
	v_lshl_add_u64 v[6:7], s[80:81], 0, v[0:1]
	s_waitcnt vmcnt(59)
	v_lshlrev_b32_e32 v0, 16, v9
	v_lshl_add_u64 v[6:7], v[6:7], 0, v[2:3]
	v_mul_f32_e32 v0, v10, v0
	global_store_short v[6:7], v12, off
	v_cvt_pk_bf16_f32 v0, v0, v1
	v_mul_f32_e32 v11, v61, v5
	global_store_short v[6:7], v0, off offset:64
	s_waitcnt vmcnt(60)
	v_lshlrev_b32_e32 v0, 16, v130
	v_mul_f32_e32 v0, v11, v0
	v_cvt_pk_bf16_f32 v0, v0, v1
	v_mul_f32_e32 v5, v77, v5
	global_store_short v[6:7], v0, off offset:128
	s_waitcnt vmcnt(60)
	v_lshlrev_b32_e32 v0, 16, v86
	v_mul_f32_e32 v0, v5, v0
	v_cvt_pk_bf16_f32 v0, v0, v1
	ds_read_b32 v5, v135 offset:104
	global_store_short v[6:7], v0, off offset:192
	s_waitcnt vmcnt(60)
	v_lshlrev_b32_e32 v7, 16, v87
	v_lshlrev_b32_e32 v0, 12, v166
	s_waitcnt lgkmcnt(0)
	v_mul_f32_e32 v6, v30, v5
	v_mul_f32_e32 v6, v6, v7
	v_mul_f32_e32 v9, v46, v5
	v_cvt_pk_bf16_f32 v11, v6, v1
	v_lshl_add_u64 v[6:7], s[80:81], 0, v[0:1]
	v_lshlrev_b32_e32 v0, 16, v85
	v_lshl_add_u64 v[6:7], v[6:7], 0, v[2:3]
	v_mul_f32_e32 v0, v9, v0
	global_store_short v[6:7], v11, off
	v_cvt_pk_bf16_f32 v0, v0, v1
	v_mul_f32_e32 v10, v62, v5
	global_store_short v[6:7], v0, off offset:64
	v_lshlrev_b32_e32 v0, 16, v129
	v_mul_f32_e32 v0, v10, v0
	v_cvt_pk_bf16_f32 v0, v0, v1
	v_mul_f32_e32 v5, v78, v5
	global_store_short v[6:7], v0, off offset:128
	v_lshlrev_b32_e32 v0, 16, v8
	v_mul_f32_e32 v0, v5, v0
	v_cvt_pk_bf16_f32 v0, v0, v1
	ds_read_b32 v5, v135 offset:108
	global_store_short v[6:7], v0, off offset:192
	s_waitcnt vmcnt(62)
	v_lshlrev_b32_e32 v7, 16, v131
	v_lshlrev_b32_e32 v0, 12, v165
	s_waitcnt lgkmcnt(0)
	v_mul_f32_e32 v6, v31, v5
	v_mul_f32_e32 v6, v6, v7
	v_mul_f32_e32 v8, v47, v5
	v_cvt_pk_bf16_f32 v10, v6, v1
	v_lshl_add_u64 v[6:7], s[80:81], 0, v[0:1]
	v_lshlrev_b32_e32 v0, 16, v132
	v_lshl_add_u64 v[2:3], v[6:7], 0, v[2:3]
	v_mul_f32_e32 v0, v8, v0
	global_store_short v[2:3], v10, off
	v_cvt_pk_bf16_f32 v0, v0, v1
	v_mul_f32_e32 v9, v63, v5
	global_store_short v[2:3], v0, off offset:64
	s_waitcnt vmcnt(62)
	v_lshlrev_b32_e32 v0, 16, v133
	v_mul_f32_e32 v0, v9, v0
	v_cvt_pk_bf16_f32 v0, v0, v1
	v_mul_f32_e32 v5, v79, v5
	global_store_short v[2:3], v0, off offset:128
	v_lshlrev_b32_e32 v0, 16, v134
	v_mul_f32_e32 v0, v5, v0
	v_cvt_pk_bf16_f32 v0, v0, v1
	global_store_short v[2:3], v0, off offset:192

; #define SBAR() __builtin_amdgcn_sched_barrier(0)
; __device__ __forceinline__ int crow(int r, int hi) { return (r & 3) + 8 * (r >> 2) + 4 * hi; }
; template <int MODE, bool FAST>
; __device__ __forceinline__ int attn_item(const AttnP& a, int b, int h, int blk, char* lds) {
;     ...
;     const float lam = MODE == 0 ? a.lam[0] : 0.f;
;     if (hi == 0) { wsf[r32] = 1.f / l_reg[0]; if (MODE == 0) wsf[32 + r32] = lam / l_reg[NMAP - 1]; }
;     asm volatile("s_waitcnt lgkmcnt(0)" ::: "memory");
;     const size_t obase = ((size_t)b * SEQ + qtok) * DM + (MODE == 0 ? 0 : 1024) + h * 128 + r32;
;     float sg[4];
; #pragma unroll
;     for (int d = 0; d < 4; ++d) sg[d] = MODE == 0 ? a.subln_g[d * 32 + r32] * 0.8f : 1.f;
;     bf16_t gq[16][4];
; #pragma unroll
;     for (int r = 0; r < 16; ++r)
; #pragma unroll
;         for (int d = 0; d < 4; ++d) gq[r][d] = a.G[obase + (size_t)crow(r, hi) * DM + d * 32];
;     asm volatile("s_waitcnt vmcnt(0)" ::: "memory"); SBAR();
.LBB0_218:
	s_or_b64 exec, exec, s[4:5]
	s_ashr_i32 s89, s88, 31
	s_lshl_b64 s[0:1], s[88:89], 24
	s_lshl_b64 s[4:5], s[90:91], 11
	s_add_u32 s0, s4, s0
	s_addc_u32 s1, s5, s1
	s_lshl_b32 s4, s82, 7
	s_or_b32 s0, s0, s4
	v_or_b32_e32 v2, s0, v166
	v_mov_b32_e32 v3, s1
	v_lshlrev_b64 v[2:3], 1, v[2:3]
	v_lshlrev_b32_e32 v0, 14, v167
	s_mov_b64 s[88:89], s[74:75]
	v_lshl_add_u64 v[4:5], s[88:89], 0, v[0:1]
	v_or_b32_e32 v2, 0x800, v2
	v_lshl_add_u64 v[4:5], v[4:5], 0, v[2:3]
	s_movk_i32 s0, 0x1000
	v_add_co_u32_e32 v6, vcc, s0, v4
	s_movk_i32 s0, 0x2000
	s_nop 0
	v_addc_co_u32_e32 v7, vcc, 0, v5, vcc
	v_add_co_u32_e32 v8, vcc, s0, v4
	s_movk_i32 s0, 0x3000
	s_nop 0
	v_addc_co_u32_e32 v9, vcc, 0, v5, vcc
	v_add_co_u32_e32 v10, vcc, s0, v4
	s_waitcnt lgkmcnt(0)
	s_mov_b32 s0, 0x8000
	s_nop 0
	v_addc_co_u32_e32 v11, vcc, 0, v5, vcc
	global_load_ushort v86, v[4:5], off nt
	global_load_ushort v87, v[4:5], off offset:64 nt
	global_load_ushort v88, v[4:5], off offset:128 nt
	global_load_ushort v89, v[4:5], off offset:192 nt
	global_load_ushort v90, v[6:7], off offset:64 nt
	global_load_ushort v91, v[6:7], off offset:128 nt
	global_load_ushort v92, v[6:7], off offset:192 nt
	global_load_ushort v93, v[10:11], off nt
	v_add_co_u32_e32 v6, vcc, s0, v4
	s_mov_b32 s0, 0x9000
	s_nop 0
	v_addc_co_u32_e32 v7, vcc, 0, v5, vcc
	v_add_co_u32_e32 v12, vcc, s0, v4
	s_mov_b32 s0, 0xa000
	s_nop 0
	v_addc_co_u32_e32 v13, vcc, 0, v5, vcc
	v_add_co_u32_e32 v14, vcc, s0, v4
	s_mov_b32 s0, 0xb000
	s_nop 0
	v_addc_co_u32_e32 v15, vcc, 0, v5, vcc
	v_add_co_u32_e32 v80, vcc, s0, v4
	s_mov_b32 s0, 0x10000
	s_nop 0
	v_addc_co_u32_e32 v81, vcc, 0, v5, vcc
	global_load_ushort v94, v[8:9], off offset:128 nt
	global_load_ushort v95, v[8:9], off offset:192 nt
	global_load_ushort v96, v[12:13], off offset:-4096 nt
	global_load_ushort v97, v[12:13], off nt
	global_load_ushort v98, v[12:13], off offset:64 nt
	global_load_ushort v99, v[12:13], off offset:128 nt
	global_load_ushort v100, v[12:13], off offset:192 nt
	global_load_ushort v101, v[80:81], off offset:-4096 nt
	global_load_ushort v102, v[10:11], off offset:64 nt
	global_load_ushort v103, v[10:11], off offset:128 nt
	global_load_ushort v104, v[10:11], off offset:192 nt
	global_load_ushort v105, v[6:7], off offset:64 nt
	global_load_ushort v106, v[6:7], off offset:128 nt
	global_load_ushort v107, v[6:7], off offset:192 nt
	global_load_ushort v108, v[14:15], off offset:64 nt
	global_load_ushort v109, v[14:15], off offset:128 nt
	v_add_co_u32_e32 v6, vcc, s0, v4
	s_mov_b32 s0, 0x11000
	s_nop 0
	v_addc_co_u32_e32 v7, vcc, 0, v5, vcc
	v_add_co_u32_e32 v10, vcc, s0, v4
	s_mov_b32 s0, 0x12000
	s_nop 0
	v_addc_co_u32_e32 v11, vcc, 0, v5, vcc
	v_add_co_u32_e32 v12, vcc, s0, v4
	s_mov_b32 s0, 0x13000
	s_nop 0
	v_addc_co_u32_e32 v13, vcc, 0, v5, vcc
	global_load_ushort v110, v[80:81], off nt
	global_load_ushort v111, v[80:81], off offset:64 nt
	global_load_ushort v112, v[80:81], off offset:128 nt
	global_load_ushort v113, v[80:81], off offset:192 nt
	global_load_ushort v114, v[10:11], off offset:-4096 nt
	global_load_ushort v115, v[10:11], off nt
	global_load_ushort v116, v[10:11], off offset:64 nt
	global_load_ushort v117, v[10:11], off offset:128 nt
	v_add_co_u32_e32 v80, vcc, s0, v4
	s_mov_b32 s0, 0x18000
	s_nop 0
	v_addc_co_u32_e32 v81, vcc, 0, v5, vcc
	v_add_co_u32_e32 v82, vcc, s0, v4
	s_mov_b32 s0, 0x19000
	s_nop 0
	v_addc_co_u32_e32 v83, vcc, 0, v5, vcc
	v_add_co_u32_e32 v84, vcc, s0, v4
	s_mov_b32 s0, 0x1a000
	s_nop 0
	v_addc_co_u32_e32 v85, vcc, 0, v5, vcc
	global_load_ushort v14, v[14:15], off offset:192 nt
	s_nop 0
	global_load_ushort v15, v[6:7], off offset:64 nt
	global_load_ushort v118, v[6:7], off offset:128 nt
	global_load_ushort v119, v[6:7], off offset:192 nt
	global_load_ushort v120, v[12:13], off offset:64 nt
	global_load_ushort v121, v[12:13], off offset:128 nt
	s_nop 0
	global_load_ushort v12, v[12:13], off offset:192 nt
	s_nop 0
	global_load_ushort v13, v[82:83], off offset:64 nt
	s_nop 0
	global_load_ushort v10, v[10:11], off offset:192 nt
	s_nop 0
	global_load_ushort v11, v[80:81], off offset:-4096 nt
	global_load_ushort v122, v[80:81], off nt
	global_load_ushort v123, v[80:81], off offset:64 nt
	global_load_ushort v124, v[80:81], off offset:128 nt
	s_nop 0
	global_load_ushort v80, v[80:81], off offset:192 nt
	s_nop 0
	global_load_ushort v81, v[84:85], off offset:-4096 nt
	global_load_ushort v125, v[84:85], off nt
	v_add_co_u32_e32 v6, vcc, s0, v4
	s_mov_b32 s0, 0x1b000
	s_nop 0
	v_addc_co_u32_e32 v7, vcc, 0, v5, vcc
	v_add_co_u32_e32 v4, vcc, s0, v4
	s_nop 1
	v_addc_co_u32_e32 v5, vcc, 0, v5, vcc
	global_load_ushort v126, v[8:9], off offset:-4096 nt
	global_load_ushort v127, v[8:9], off nt
	s_nop 0
	global_load_ushort v8, v[8:9], off offset:64 nt
	s_nop 0
	global_load_ushort v9, v[82:83], off offset:128 nt
	s_nop 0
	global_load_ushort v82, v[82:83], off offset:192 nt
	s_nop 0
	global_load_ushort v83, v[6:7], off offset:64 nt
	global_load_ushort v128, v[6:7], off offset:128 nt
	s_nop 0
	global_load_ushort v6, v[6:7], off offset:192 nt
	s_nop 0
	global_load_ushort v7, v[84:85], off offset:64 nt
	global_load_ushort v129, v[84:85], off offset:128 nt
	s_nop 0
	global_load_ushort v84, v[84:85], off offset:192 nt
	s_nop 0
	global_load_ushort v85, v[4:5], off offset:-4096 nt
	global_load_ushort v130, v[4:5], off nt
	global_load_ushort v131, v[4:5], off offset:64 nt
	global_load_ushort v132, v[4:5], off offset:128 nt
	global_load_ushort v133, v[4:5], off offset:192 nt
	s_waitcnt vmcnt(0)
	v_lshl_add_u32 v134, v165, 2, s83
	ds_read_b32 v4, v134
	s_waitcnt vmcnt(62)
; __device__ __forceinline__ unsigned cvtpk(float lo, float hi) { unsigned r; asm volatile("v_cvt_pk_bf16_f32 %0, %1, %2" : "=v"(r) : "v"(lo), "v"(hi)); return r; }
; __device__ __forceinline__ float bf2f(bf16_t v) { return __uint_as_float((unsigned)v << 16); }
; __device__ __forceinline__ int crow(int r, int hi) { return (r & 3) + 8 * (r >> 2) + 4 * hi; }
; template <int MODE, bool FAST>
; __device__ __forceinline__ int attn_item(const AttnP& a, int b, int h, int blk, char* lds) {
;     ...
;     for (int r = 0; r < 16; ++r) {
;         const int cr = crow(r, hi);
;         const float ra = wsf[cr];
;         float v[4];
;         if (MODE == 0) {
;             const float rb = wsf[32 + cr];
;             float ss = 0.f;
; #pragma unroll
;             for (int d = 0; d < 4; ++d) { v[d] = o[0][d][r] * ra - o[NMAP - 1][d][r] * rb; ss += v[d] * v[d]; }
;             ss += __shfl_xor(ss, 1); ss += __shfl_xor(ss, 2); ss += __shfl_xor(ss, 4); ss += __shfl_xor(ss, 8); ss += __shfl_xor(ss, 16);
;             const float rstd = rsqrtf(ss * (1.f / 128.f) + 1e-5f);
; #pragma unroll
;             for (int d = 0; d < 4; ++d) v[d] *= rstd * sg[d];
;         } else {
; #pragma unroll
;             for (int d = 0; d < 4; ++d) v[d] = o[0][d][r] * ra;
;         }
;         const size_t ro = obase + (size_t)cr * DM;
; #pragma unroll
;         for (int d = 0; d < 4; ++d) { const float gg = bf2f(gq[r][d]); a.MIX[ro + d * 32] = (bf16_t)(cvtpk(v[d] * gg, 0.f) & 0xffffu); }
;     }
	v_lshlrev_b32_e32 v5, 16, v86
	v_readlane_b32 s78, v254, 44
	v_readlane_b32 s79, v254, 43
	v_readlane_b32 s92, v254, 45
	s_waitcnt lgkmcnt(0)
	v_mul_f32_e32 v16, v16, v4
	v_mul_f32_e32 v32, v32, v4
	v_mul_f32_e32 v48, v48, v4
	v_mul_f32_e32 v64, v64, v4
	v_mul_f32_e32 v4, v16, v5
	v_cvt_pk_bf16_f32 v16, v4, v1
	v_lshl_add_u64 v[4:5], s[80:81], 0, v[0:1]
	v_lshlrev_b32_e32 v0, 16, v87
	v_lshl_add_u64 v[4:5], v[4:5], 0, v[2:3]
	v_mul_f32_e32 v0, v32, v0
	global_store_short v[4:5], v16, off
	v_cvt_pk_bf16_f32 v0, v0, v1
	global_store_short v[4:5], v0, off offset:64
	s_waitcnt vmcnt(62)
	v_lshlrev_b32_e32 v0, 16, v88
	v_mul_f32_e32 v0, v48, v0
	v_cvt_pk_bf16_f32 v0, v0, v1
	global_store_short v[4:5], v0, off offset:128
	v_lshlrev_b32_e32 v0, 16, v89
	v_mul_f32_e32 v0, v64, v0
	v_cvt_pk_bf16_f32 v0, v0, v1
	ds_read_b32 v16, v134 offset:4
	global_store_short v[4:5], v0, off offset:192
	s_waitcnt vmcnt(19)
	v_lshlrev_b32_e32 v5, 16, v126
	v_lshlrev_b32_e32 v0, 12, v164
	s_mov_b32 s93, s3
	s_waitcnt lgkmcnt(0)
	v_mul_f32_e32 v4, v17, v16
	v_mul_f32_e32 v4, v4, v5
	v_mul_f32_e32 v17, v33, v16
	v_cvt_pk_bf16_f32 v33, v4, v1
	v_lshl_add_u64 v[4:5], s[80:81], 0, v[0:1]
	v_lshlrev_b32_e32 v0, 16, v90
	v_lshl_add_u64 v[4:5], v[4:5], 0, v[2:3]
	v_mul_f32_e32 v0, v17, v0
	global_store_short v[4:5], v33, off
	v_cvt_pk_bf16_f32 v0, v0, v1
	v_mul_f32_e32 v32, v49, v16
	global_store_short v[4:5], v0, off offset:64
	v_lshlrev_b32_e32 v0, 16, v91
	v_mul_f32_e32 v0, v32, v0
	v_cvt_pk_bf16_f32 v0, v0, v1
	v_mul_f32_e32 v16, v65, v16
	global_store_short v[4:5], v0, off offset:128
	v_lshlrev_b32_e32 v0, 16, v92
	v_mul_f32_e32 v0, v16, v0
	v_cvt_pk_bf16_f32 v0, v0, v1
	ds_read_b32 v16, v134 offset:8
	global_store_short v[4:5], v0, off offset:192
	s_waitcnt vmcnt(22)
	v_lshlrev_b32_e32 v5, 16, v127
	v_lshlrev_b32_e32 v0, 12, v163
	v_readlane_b32 s3, v254, 42
	s_waitcnt lgkmcnt(0)
	v_mul_f32_e32 v4, v18, v16
	v_mul_f32_e32 v4, v4, v5
	v_mul_f32_e32 v17, v34, v16
	v_cvt_pk_bf16_f32 v32, v4, v1
	v_lshl_add_u64 v[4:5], s[80:81], 0, v[0:1]
	s_waitcnt vmcnt(21)
	v_lshlrev_b32_e32 v0, 16, v8
	v_lshl_add_u64 v[4:5], v[4:5], 0, v[2:3]
	v_mul_f32_e32 v0, v17, v0
	global_store_short v[4:5], v32, off
	v_cvt_pk_bf16_f32 v0, v0, v1
	v_mul_f32_e32 v18, v50, v16
	global_store_short v[4:5], v0, off offset:64
	v_lshlrev_b32_e32 v0, 16, v94
	v_mul_f32_e32 v0, v18, v0
	v_cvt_pk_bf16_f32 v0, v0, v1
	v_mul_f32_e32 v16, v66, v16
	global_store_short v[4:5], v0, off offset:128
	v_lshlrev_b32_e32 v0, 16, v95
	v_mul_f32_e32 v0, v16, v0
	v_cvt_pk_bf16_f32 v0, v0, v1
	ds_read_b32 v8, v134 offset:12
	global_store_short v[4:5], v0, off offset:192
	v_lshlrev_b32_e32 v5, 16, v93
	v_lshlrev_b32_e32 v0, 12, v162
	s_mov_b32 s94, s95
	s_waitcnt lgkmcnt(0)
	v_mul_f32_e32 v4, v19, v8
	v_mul_f32_e32 v4, v4, v5
	v_mul_f32_e32 v16, v35, v8
	v_cvt_pk_bf16_f32 v18, v4, v1
	v_lshl_add_u64 v[4:5], s[80:81], 0, v[0:1]
	v_lshlrev_b32_e32 v0, 16, v102
	v_lshl_add_u64 v[4:5], v[4:5], 0, v[2:3]
	v_mul_f32_e32 v0, v16, v0
	global_store_short v[4:5], v18, off
	v_cvt_pk_bf16_f32 v0, v0, v1
	v_mul_f32_e32 v17, v51, v8
	global_store_short v[4:5], v0, off offset:64
	v_lshlrev_b32_e32 v0, 16, v103
	v_mul_f32_e32 v0, v17, v0
	v_cvt_pk_bf16_f32 v0, v0, v1
	v_mul_f32_e32 v8, v67, v8
	global_store_short v[4:5], v0, off offset:128
	v_lshlrev_b32_e32 v0, 16, v104
	v_mul_f32_e32 v0, v8, v0
	v_cvt_pk_bf16_f32 v0, v0, v1
	ds_read_b32 v8, v134 offset:32
	global_store_short v[4:5], v0, off offset:192
	v_lshlrev_b32_e32 v5, 16, v96
	v_lshlrev_b32_e32 v0, 12, v161
	s_waitcnt lgkmcnt(0)
	v_mul_f32_e32 v4, v20, v8
	v_mul_f32_e32 v4, v4, v5
	v_mul_f32_e32 v16, v36, v8
	v_cvt_pk_bf16_f32 v18, v4, v1
	v_lshl_add_u64 v[4:5], s[80:81], 0, v[0:1]
	v_lshlrev_b32_e32 v0, 16, v105
	v_lshl_add_u64 v[4:5], v[4:5], 0, v[2:3]
	v_mul_f32_e32 v0, v16, v0
	global_store_short v[4:5], v18, off
	v_cvt_pk_bf16_f32 v0, v0, v1
	v_mul_f32_e32 v17, v52, v8
	global_store_short v[4:5], v0, off offset:64
	v_lshlrev_b32_e32 v0, 16, v106
	v_mul_f32_e32 v0, v17, v0
	v_cvt_pk_bf16_f32 v0, v0, v1
	v_mul_f32_e32 v8, v68, v8
	global_store_short v[4:5], v0, off offset:128
	v_lshlrev_b32_e32 v0, 16, v107
	v_mul_f32_e32 v0, v8, v0
	v_cvt_pk_bf16_f32 v0, v0, v1
	ds_read_b32 v8, v134 offset:36
	global_store_short v[4:5], v0, off offset:192
	v_lshlrev_b32_e32 v5, 16, v97
	v_lshlrev_b32_e32 v0, 12, v160
	s_waitcnt lgkmcnt(0)
	v_mul_f32_e32 v4, v21, v8
	v_mul_f32_e32 v4, v4, v5
	v_mul_f32_e32 v16, v37, v8
	v_cvt_pk_bf16_f32 v18, v4, v1
	v_lshl_add_u64 v[4:5], s[80:81], 0, v[0:1]
	v_lshlrev_b32_e32 v0, 16, v98
	v_lshl_add_u64 v[4:5], v[4:5], 0, v[2:3]
	v_mul_f32_e32 v0, v16, v0
	global_store_short v[4:5], v18, off
	v_cvt_pk_bf16_f32 v0, v0, v1
	v_mul_f32_e32 v17, v53, v8
	global_store_short v[4:5], v0, off offset:64
	v_lshlrev_b32_e32 v0, 16, v99
	v_mul_f32_e32 v0, v17, v0
	v_cvt_pk_bf16_f32 v0, v0, v1
	v_mul_f32_e32 v8, v69, v8
	global_store_short v[4:5], v0, off offset:128
	v_lshlrev_b32_e32 v0, 16, v100
	v_mul_f32_e32 v0, v8, v0
	v_cvt_pk_bf16_f32 v0, v0, v1
	ds_read_b32 v8, v134 offset:40
	global_store_short v[4:5], v0, off offset:192
	v_lshlrev_b32_e32 v5, 16, v101
	v_lshlrev_b32_e32 v0, 12, v159
	s_waitcnt lgkmcnt(0)
	v_mul_f32_e32 v4, v22, v8
	v_mul_f32_e32 v4, v4, v5
	v_mul_f32_e32 v16, v38, v8
	v_cvt_pk_bf16_f32 v18, v4, v1
	v_lshl_add_u64 v[4:5], s[80:81], 0, v[0:1]
	v_lshlrev_b32_e32 v0, 16, v108
	v_lshl_add_u64 v[4:5], v[4:5], 0, v[2:3]
	v_mul_f32_e32 v0, v16, v0
	global_store_short v[4:5], v18, off
	v_cvt_pk_bf16_f32 v0, v0, v1
	v_mul_f32_e32 v17, v54, v8
	global_store_short v[4:5], v0, off offset:64
	v_lshlrev_b32_e32 v0, 16, v109
	v_mul_f32_e32 v0, v17, v0
	v_cvt_pk_bf16_f32 v0, v0, v1
	v_mul_f32_e32 v8, v70, v8
	global_store_short v[4:5], v0, off offset:128
	v_lshlrev_b32_e32 v0, 16, v14
	v_mul_f32_e32 v0, v8, v0
	v_cvt_pk_bf16_f32 v0, v0, v1
	ds_read_b32 v8, v134 offset:44
	global_store_short v[4:5], v0, off offset:192
	v_lshlrev_b32_e32 v5, 16, v110
	v_lshlrev_b32_e32 v0, 12, v158
	s_waitcnt lgkmcnt(0)
; __device__ __forceinline__ unsigned cvtpk(float lo, float hi) { unsigned r; asm volatile("v_cvt_pk_bf16_f32 %0, %1, %2" : "=v"(r) : "v"(lo), "v"(hi)); return r; }
; __device__ __forceinline__ float bf2f(bf16_t v) { return __uint_as_float((unsigned)v << 16); }
; __device__ __forceinline__ int crow(int r, int hi) { return (r & 3) + 8 * (r >> 2) + 4 * hi; }
; template <int MODE, bool FAST>
; __device__ __forceinline__ int attn_item(const AttnP& a, int b, int h, int blk, char* lds) {
;     ...
;     for (int r = 0; r < 16; ++r) {
;         const int cr = crow(r, hi);
;         const float ra = wsf[cr];
;         float v[4];
;         if (MODE == 0) {
;             const float rb = wsf[32 + cr];
;             float ss = 0.f;
; #pragma unroll
;             for (int d = 0; d < 4; ++d) { v[d] = o[0][d][r] * ra - o[NMAP - 1][d][r] * rb; ss += v[d] * v[d]; }
;             ss += __shfl_xor(ss, 1); ss += __shfl_xor(ss, 2); ss += __shfl_xor(ss, 4); ss += __shfl_xor(ss, 8); ss += __shfl_xor(ss, 16);
;             const float rstd = rsqrtf(ss * (1.f / 128.f) + 1e-5f);
; #pragma unroll
;             for (int d = 0; d < 4; ++d) v[d] *= rstd * sg[d];
;         } else {
; #pragma unroll
;             for (int d = 0; d < 4; ++d) v[d] = o[0][d][r] * ra;
;         }
;         const size_t ro = obase + (size_t)cr * DM;
; #pragma unroll
;         for (int d = 0; d < 4; ++d) { const float gg = bf2f(gq[r][d]); a.MIX[ro + d * 32] = (bf16_t)(cvtpk(v[d] * gg, 0.f) & 0xffffu); }
;     }
	v_mul_f32_e32 v4, v23, v8
	v_mul_f32_e32 v4, v4, v5
	v_mul_f32_e32 v14, v39, v8
	v_cvt_pk_bf16_f32 v17, v4, v1
	v_lshl_add_u64 v[4:5], s[80:81], 0, v[0:1]
	v_lshlrev_b32_e32 v0, 16, v111
	v_lshl_add_u64 v[4:5], v[4:5], 0, v[2:3]
	v_mul_f32_e32 v0, v14, v0
	global_store_short v[4:5], v17, off
	v_cvt_pk_bf16_f32 v0, v0, v1
	v_mul_f32_e32 v16, v55, v8
	global_store_short v[4:5], v0, off offset:64
	v_lshlrev_b32_e32 v0, 16, v112
	v_mul_f32_e32 v0, v16, v0
	v_cvt_pk_bf16_f32 v0, v0, v1
	v_mul_f32_e32 v8, v71, v8
	global_store_short v[4:5], v0, off offset:128
	v_lshlrev_b32_e32 v0, 16, v113
	v_mul_f32_e32 v0, v8, v0
	v_cvt_pk_bf16_f32 v0, v0, v1
	ds_read_b32 v8, v134 offset:64
	global_store_short v[4:5], v0, off offset:192
	v_lshlrev_b32_e32 v5, 16, v114
	v_lshlrev_b32_e32 v0, 12, v157
	s_waitcnt lgkmcnt(0)
	v_mul_f32_e32 v4, v24, v8
	v_mul_f32_e32 v4, v4, v5
	v_mul_f32_e32 v14, v40, v8
	v_cvt_pk_bf16_f32 v17, v4, v1
	v_lshl_add_u64 v[4:5], s[80:81], 0, v[0:1]
	v_lshlrev_b32_e32 v0, 16, v15
	v_lshl_add_u64 v[4:5], v[4:5], 0, v[2:3]
	v_mul_f32_e32 v0, v14, v0
	global_store_short v[4:5], v17, off
	v_cvt_pk_bf16_f32 v0, v0, v1
	v_mul_f32_e32 v16, v56, v8
	global_store_short v[4:5], v0, off offset:64
	v_lshlrev_b32_e32 v0, 16, v118
	v_mul_f32_e32 v0, v16, v0
	v_cvt_pk_bf16_f32 v0, v0, v1
	v_mul_f32_e32 v8, v72, v8
	global_store_short v[4:5], v0, off offset:128
	v_lshlrev_b32_e32 v0, 16, v119
	v_mul_f32_e32 v0, v8, v0
	v_cvt_pk_bf16_f32 v0, v0, v1
	ds_read_b32 v8, v134 offset:68
	global_store_short v[4:5], v0, off offset:192
	v_lshlrev_b32_e32 v5, 16, v115
	v_lshlrev_b32_e32 v0, 12, v156
	s_waitcnt lgkmcnt(0)
	v_mul_f32_e32 v4, v25, v8
	v_mul_f32_e32 v4, v4, v5
	v_mul_f32_e32 v14, v41, v8
	v_cvt_pk_bf16_f32 v16, v4, v1
	v_lshl_add_u64 v[4:5], s[80:81], 0, v[0:1]
	v_lshlrev_b32_e32 v0, 16, v116
	v_lshl_add_u64 v[4:5], v[4:5], 0, v[2:3]
	v_mul_f32_e32 v0, v14, v0
	global_store_short v[4:5], v16, off
	v_cvt_pk_bf16_f32 v0, v0, v1
	v_mul_f32_e32 v15, v57, v8
	global_store_short v[4:5], v0, off offset:64
	v_lshlrev_b32_e32 v0, 16, v117
	v_mul_f32_e32 v0, v15, v0
	v_cvt_pk_bf16_f32 v0, v0, v1
	v_mul_f32_e32 v8, v73, v8
	global_store_short v[4:5], v0, off offset:128
	v_lshlrev_b32_e32 v0, 16, v10
	v_mul_f32_e32 v0, v8, v0
	v_cvt_pk_bf16_f32 v0, v0, v1
	ds_read_b32 v8, v134 offset:72
	global_store_short v[4:5], v0, off offset:192
	v_lshlrev_b32_e32 v5, 16, v11
	v_lshlrev_b32_e32 v0, 12, v155
	s_waitcnt lgkmcnt(0)
	v_mul_f32_e32 v4, v26, v8
	v_mul_f32_e32 v4, v4, v5
	v_mul_f32_e32 v10, v42, v8
	v_cvt_pk_bf16_f32 v11, v4, v1
	v_lshl_add_u64 v[4:5], s[80:81], 0, v[0:1]
	v_lshlrev_b32_e32 v0, 16, v120
	v_lshl_add_u64 v[4:5], v[4:5], 0, v[2:3]
	v_mul_f32_e32 v0, v10, v0
	global_store_short v[4:5], v11, off
	v_cvt_pk_bf16_f32 v0, v0, v1
	v_mul_f32_e32 v14, v58, v8
	global_store_short v[4:5], v0, off offset:64
	v_lshlrev_b32_e32 v0, 16, v121
	v_mul_f32_e32 v0, v14, v0
	v_cvt_pk_bf16_f32 v0, v0, v1
	v_mul_f32_e32 v8, v74, v8
	global_store_short v[4:5], v0, off offset:128
	v_lshlrev_b32_e32 v0, 16, v12
	v_mul_f32_e32 v0, v8, v0
	v_cvt_pk_bf16_f32 v0, v0, v1
	ds_read_b32 v8, v134 offset:76
	global_store_short v[4:5], v0, off offset:192
	v_lshlrev_b32_e32 v5, 16, v122
	v_lshlrev_b32_e32 v0, 12, v154
	s_waitcnt lgkmcnt(0)
	v_mul_f32_e32 v4, v27, v8
	v_mul_f32_e32 v4, v4, v5
	v_mul_f32_e32 v10, v43, v8
	v_cvt_pk_bf16_f32 v12, v4, v1
	v_lshl_add_u64 v[4:5], s[80:81], 0, v[0:1]
	v_lshlrev_b32_e32 v0, 16, v123
	v_lshl_add_u64 v[4:5], v[4:5], 0, v[2:3]
	v_mul_f32_e32 v0, v10, v0
	global_store_short v[4:5], v12, off
	v_cvt_pk_bf16_f32 v0, v0, v1
	v_mul_f32_e32 v11, v59, v8
	global_store_short v[4:5], v0, off offset:64
	v_lshlrev_b32_e32 v0, 16, v124
	v_mul_f32_e32 v0, v11, v0
	v_cvt_pk_bf16_f32 v0, v0, v1
	v_mul_f32_e32 v8, v75, v8
	global_store_short v[4:5], v0, off offset:128
	v_lshlrev_b32_e32 v0, 16, v80
	v_mul_f32_e32 v0, v8, v0
	v_cvt_pk_bf16_f32 v0, v0, v1
	ds_read_b32 v8, v134 offset:96
	global_store_short v[4:5], v0, off offset:192
	v_lshlrev_b32_e32 v5, 16, v81
	v_lshlrev_b32_e32 v0, 12, v153
	s_waitcnt lgkmcnt(0)
; __device__ __forceinline__ unsigned cvtpk(float lo, float hi) { unsigned r; asm volatile("v_cvt_pk_bf16_f32 %0, %1, %2" : "=v"(r) : "v"(lo), "v"(hi)); return r; }
; __device__ __forceinline__ float bf2f(bf16_t v) { return __uint_as_float((unsigned)v << 16); }
; __device__ __forceinline__ int crow(int r, int hi) { return (r & 3) + 8 * (r >> 2) + 4 * hi; }
; template <int MODE, bool FAST>
; __device__ __forceinline__ int attn_item(const AttnP& a, int b, int h, int blk, char* lds) {
;     ...
;     for (int r = 0; r < 16; ++r) {
;         const int cr = crow(r, hi);
;         const float ra = wsf[cr];
;         float v[4];
;         if (MODE == 0) {
;             const float rb = wsf[32 + cr];
;             float ss = 0.f;
; #pragma unroll
;             for (int d = 0; d < 4; ++d) { v[d] = o[0][d][r] * ra - o[NMAP - 1][d][r] * rb; ss += v[d] * v[d]; }
;             ss += __shfl_xor(ss, 1); ss += __shfl_xor(ss, 2); ss += __shfl_xor(ss, 4); ss += __shfl_xor(ss, 8); ss += __shfl_xor(ss, 16);
;             const float rstd = rsqrtf(ss * (1.f / 128.f) + 1e-5f);
; #pragma unroll
;             for (int d = 0; d < 4; ++d) v[d] *= rstd * sg[d];
;         } else {
; #pragma unroll
;             for (int d = 0; d < 4; ++d) v[d] = o[0][d][r] * ra;
;         }
;         const size_t ro = obase + (size_t)cr * DM;
; #pragma unroll
;         for (int d = 0; d < 4; ++d) { const float gg = bf2f(gq[r][d]); a.MIX[ro + d * 32] = (bf16_t)(cvtpk(v[d] * gg, 0.f) & 0xffffu); }
;     }
	v_mul_f32_e32 v4, v28, v8
	v_mul_f32_e32 v4, v4, v5
	v_mul_f32_e32 v10, v44, v8
	v_cvt_pk_bf16_f32 v12, v4, v1
	v_lshl_add_u64 v[4:5], s[80:81], 0, v[0:1]
	v_lshlrev_b32_e32 v0, 16, v13
	v_lshl_add_u64 v[4:5], v[4:5], 0, v[2:3]
	v_mul_f32_e32 v0, v10, v0
	global_store_short v[4:5], v12, off
	v_cvt_pk_bf16_f32 v0, v0, v1
	v_mul_f32_e32 v11, v60, v8
	global_store_short v[4:5], v0, off offset:64
	s_waitcnt vmcnt(62)
	v_lshlrev_b32_e32 v0, 16, v9
	v_mul_f32_e32 v0, v11, v0
	v_cvt_pk_bf16_f32 v0, v0, v1
	v_mul_f32_e32 v8, v76, v8
	global_store_short v[4:5], v0, off offset:128
	s_waitcnt vmcnt(62)
	v_lshlrev_b32_e32 v0, 16, v82
	v_mul_f32_e32 v0, v8, v0
	v_cvt_pk_bf16_f32 v0, v0, v1
	ds_read_b32 v8, v134 offset:100
	global_store_short v[4:5], v0, off offset:192
	v_lshlrev_b32_e32 v5, 16, v125
	v_lshlrev_b32_e32 v0, 12, v152
	s_waitcnt lgkmcnt(0)
	v_mul_f32_e32 v4, v29, v8
	v_mul_f32_e32 v4, v4, v5
	v_mul_f32_e32 v9, v45, v8
	v_cvt_pk_bf16_f32 v11, v4, v1
	v_lshl_add_u64 v[4:5], s[80:81], 0, v[0:1]
	s_waitcnt vmcnt(59)
	v_lshlrev_b32_e32 v0, 16, v7
	v_lshl_add_u64 v[4:5], v[4:5], 0, v[2:3]
	v_mul_f32_e32 v0, v9, v0
	global_store_short v[4:5], v11, off
	v_cvt_pk_bf16_f32 v0, v0, v1
	v_mul_f32_e32 v10, v61, v8
	global_store_short v[4:5], v0, off offset:64
	s_waitcnt vmcnt(60)
	v_lshlrev_b32_e32 v0, 16, v129
	v_mul_f32_e32 v0, v10, v0
	v_cvt_pk_bf16_f32 v0, v0, v1
	v_mul_f32_e32 v8, v77, v8
	global_store_short v[4:5], v0, off offset:128
	s_waitcnt vmcnt(60)
	v_lshlrev_b32_e32 v0, 16, v84
	v_mul_f32_e32 v0, v8, v0
	v_cvt_pk_bf16_f32 v0, v0, v1
	ds_read_b32 v7, v134 offset:104
	global_store_short v[4:5], v0, off offset:192
	s_waitcnt vmcnt(60)
	v_lshlrev_b32_e32 v5, 16, v85
	v_lshlrev_b32_e32 v0, 12, v151
	s_waitcnt lgkmcnt(0)
	v_mul_f32_e32 v4, v30, v7
	v_mul_f32_e32 v4, v4, v5
	v_mul_f32_e32 v8, v46, v7
	v_cvt_pk_bf16_f32 v10, v4, v1
	v_lshl_add_u64 v[4:5], s[80:81], 0, v[0:1]
	v_lshlrev_b32_e32 v0, 16, v83
	v_lshl_add_u64 v[4:5], v[4:5], 0, v[2:3]
	v_mul_f32_e32 v0, v8, v0
	global_store_short v[4:5], v10, off
	v_cvt_pk_bf16_f32 v0, v0, v1
	v_mul_f32_e32 v9, v62, v7
	global_store_short v[4:5], v0, off offset:64
	v_lshlrev_b32_e32 v0, 16, v128
	v_mul_f32_e32 v0, v9, v0
	v_cvt_pk_bf16_f32 v0, v0, v1
	v_mul_f32_e32 v7, v78, v7
	global_store_short v[4:5], v0, off offset:128
	v_lshlrev_b32_e32 v0, 16, v6
	v_mul_f32_e32 v0, v7, v0
	v_cvt_pk_bf16_f32 v0, v0, v1
	ds_read_b32 v6, v134 offset:108
	global_store_short v[4:5], v0, off offset:192
	s_waitcnt vmcnt(62)
	v_lshlrev_b32_e32 v5, 16, v130
	v_lshlrev_b32_e32 v0, 12, v150
	s_waitcnt lgkmcnt(0)
	v_mul_f32_e32 v4, v31, v6
	v_mul_f32_e32 v4, v4, v5
	v_mul_f32_e32 v7, v47, v6
	v_cvt_pk_bf16_f32 v9, v4, v1
	v_lshl_add_u64 v[4:5], s[80:81], 0, v[0:1]
	v_lshlrev_b32_e32 v0, 16, v131
	v_lshl_add_u64 v[2:3], v[4:5], 0, v[2:3]
	v_mul_f32_e32 v0, v7, v0
	global_store_short v[2:3], v9, off
	v_cvt_pk_bf16_f32 v0, v0, v1
	v_mul_f32_e32 v8, v63, v6
	global_store_short v[2:3], v0, off offset:64
	s_waitcnt vmcnt(62)
	v_lshlrev_b32_e32 v0, 16, v132
	v_mul_f32_e32 v0, v8, v0
	v_cvt_pk_bf16_f32 v0, v0, v1
	v_mul_f32_e32 v6, v79, v6
	global_store_short v[2:3], v0, off offset:128
	v_lshlrev_b32_e32 v0, 16, v133
	v_mul_f32_e32 v0, v6, v0
	v_cvt_pk_bf16_f32 v0, v0, v1
	global_store_short v[2:3], v0, off offset:192
